# LDS-DMA groups: m0 write moved ahead of the address add so the s_nop pad goes (175 sites); 142 duplicate lgkmcnt(0) after the asm wait removed
# baseline (speedup 1.0000x reference)
;     __device__ __forceinline__ bool unit(int L, Unit& u) const { u.g = L; return order_mn(L, T / 256, NGU / 256, u.pm, u.pn); }
;     __device__ __forceinline__ bool unit(int L, Unit& u) const { u.g = L; return order_mn(L, T / 256, D / 256, u.pm, u.pn); }
;     __device__ __forceinline__ bool unit(int L, Unit& u) const { u.g = 0; return order_mn(L, T / 256, 8, u.pm, u.pn); }
;     __device__ __forceinline__ bool unit(int L, Unit& u) const { if (L >= NG * 4) return false; u.g = L >> 2; u.pm = (L >> 1) & 1; u.pn = L & 1; return true; }
;     __device__ __forceinline__ bool unit(int L, Unit& u) const { if (L >= NG * 8) return false; u.g = L >> 3; u.pm = (L >> 2) & 1; u.pn = L & 3; return true; }
;     ...
;         const bool has_next = p.unit((ui + 1) * G + c, nxt);
;         const char* nA = has_next ? p.a0(nxt) : cA; const char* nB = has_next ? p.b0(nxt) : cB;
;         const char* nA2 = P::SEG ? (has_next ? p.a1(nxt) : cA2) : nA; const char* nB2 = P::SEG ? (has_next ? p.b1(nxt) : cB2) : nB;
.LBB0_231:
	s_ashr_i32 s19, s18, 31
	ds_read_b128 v[0:3], v152
	ds_read_b128 v[4:7], v152 offset:1024
	ds_read_b128 v[8:11], v152 offset:2048
	ds_read_b128 v[12:15], v152 offset:3072
	s_lshl_b64 s[20:21], s[18:19], 19
	s_add_u32 s20, s10, s20
	s_addc_u32 s21, s11, s21
	s_ashr_i32 s17, s16, 31
	s_lshl_b64 s[22:23], s[16:17], 19
	s_add_u32 s22, s39, s22
	s_addc_u32 s23, s40, s23
	s_add_u32 s34, s26, 0x40080
	s_addc_u32 s35, s27, 0
	s_mov_b32 m0, s47
	v_lshl_add_u64 v[48:49], s[34:35], 0, v[136:137]
	ds_read_b128 v[16:19], v153
	ds_read_b128 v[20:23], v153 offset:1024
	ds_read_b128 v[24:27], v153 offset:2048
	ds_read_b128 v[28:31], v153 offset:3072
	ds_read_b128 v[32:35], v153 offset:4096
	ds_read_b128 v[36:39], v153 offset:5120
	ds_read_b128 v[40:43], v153 offset:6144
	ds_read_b128 v[44:47], v153 offset:7168
	global_load_lds_dwordx4 v[48:49], off
	s_mov_b32 m0, s48
	v_lshl_add_u64 v[48:49], s[34:35], 0, v[132:133]
	global_load_lds_dwordx4 v[48:49], off
	s_waitcnt lgkmcnt(8)
	s_barrier
	s_waitcnt lgkmcnt(0)
	s_setprio 1
	v_mfma_f32_16x16x32_bf16 v[48:51], v[0:3], v[16:19], 0
	v_mfma_f32_16x16x32_bf16 v[52:55], v[8:11], v[16:19], 0
	v_mfma_f32_16x16x32_bf16 v[56:59], v[0:3], v[24:27], 0
	v_mfma_f32_16x16x32_bf16 v[60:63], v[8:11], v[24:27], 0
	v_mfma_f32_16x16x32_bf16 v[64:67], v[0:3], v[32:35], 0
	v_mfma_f32_16x16x32_bf16 v[68:71], v[8:11], v[32:35], 0
	v_mfma_f32_16x16x32_bf16 v[72:75], v[0:3], v[40:43], 0
	v_mfma_f32_16x16x32_bf16 v[76:79], v[8:11], v[40:43], 0
	v_mfma_f32_16x16x32_bf16 v[48:51], v[4:7], v[20:23], v[48:51]
	v_mfma_f32_16x16x32_bf16 v[52:55], v[12:15], v[20:23], v[52:55]
	v_mfma_f32_16x16x32_bf16 v[56:59], v[4:7], v[28:31], v[56:59]
	v_mfma_f32_16x16x32_bf16 v[60:63], v[12:15], v[28:31], v[60:63]
	v_mfma_f32_16x16x32_bf16 v[64:67], v[4:7], v[36:39], v[64:67]
	v_mfma_f32_16x16x32_bf16 v[68:71], v[12:15], v[36:39], v[68:71]
	v_mfma_f32_16x16x32_bf16 v[72:75], v[4:7], v[44:47], v[72:75]
	v_mfma_f32_16x16x32_bf16 v[76:79], v[12:15], v[44:47], v[76:79]
	s_setprio 0
	s_barrier
	v_lshl_add_u64 v[218:219], s[28:29], 0, v[134:135]
	s_mov_b32 m0, s49
	v_lshl_add_u64 v[96:97], v[218:219], 0, s[8:9]
	v_lshl_add_u64 v[238:239], s[28:29], 0, v[130:131]
	ds_read_b128 v[80:83], v154
	ds_read_b128 v[84:87], v154 offset:1024
	ds_read_b128 v[88:91], v154 offset:2048
	ds_read_b128 v[92:95], v154 offset:3072
	global_load_lds_dwordx4 v[96:97], off
	s_mov_b32 m0, s50
	v_lshl_add_u64 v[96:97], v[238:239], 0, s[8:9]
	global_load_lds_dwordx4 v[96:97], off
	s_barrier
	s_waitcnt lgkmcnt(0)
	s_setprio 1
	v_mfma_f32_16x16x32_bf16 v[96:99], v[80:83], v[16:19], 0
	v_mfma_f32_16x16x32_bf16 v[16:19], v[88:91], v[16:19], 0
	v_mfma_f32_16x16x32_bf16 v[100:103], v[80:83], v[24:27], 0
	v_mfma_f32_16x16x32_bf16 v[24:27], v[88:91], v[24:27], 0
	v_mfma_f32_16x16x32_bf16 v[104:107], v[80:83], v[32:35], 0
	v_mfma_f32_16x16x32_bf16 v[32:35], v[88:91], v[32:35], 0
	v_mfma_f32_16x16x32_bf16 v[108:111], v[80:83], v[40:43], 0
	v_mfma_f32_16x16x32_bf16 v[40:43], v[88:91], v[40:43], 0
	v_mfma_f32_16x16x32_bf16 v[116:119], v[84:87], v[20:23], v[96:99]
	v_mfma_f32_16x16x32_bf16 v[16:19], v[92:95], v[20:23], v[16:19]
	v_mfma_f32_16x16x32_bf16 v[20:23], v[84:87], v[28:31], v[100:103]
	v_mfma_f32_16x16x32_bf16 v[24:27], v[92:95], v[28:31], v[24:27]
	v_mfma_f32_16x16x32_bf16 v[28:31], v[84:87], v[36:39], v[104:107]
	v_mfma_f32_16x16x32_bf16 v[32:35], v[92:95], v[36:39], v[32:35]
	v_mfma_f32_16x16x32_bf16 v[36:39], v[84:87], v[44:47], v[108:111]
	v_mfma_f32_16x16x32_bf16 v[40:43], v[92:95], v[44:47], v[40:43]
	s_setprio 0
	v_lshl_add_u64 v[246:247], s[26:27], 0, v[136:137]
	s_mov_b32 m0, s25
	v_lshl_add_u64 v[142:143], v[246:247], 0, s[8:9]
	v_lshl_add_u64 v[248:249], s[26:27], 0, v[132:133]
	s_barrier
	ds_read_b128 v[44:47], v153 offset:16384
	ds_read_b128 v[96:99], v153 offset:17408
	ds_read_b128 v[100:103], v153 offset:18432
	ds_read_b128 v[104:107], v153 offset:19456
	ds_read_b128 v[108:111], v153 offset:20480
	ds_read_b128 v[112:115], v153 offset:21504
	ds_read_b128 v[120:123], v153 offset:22528
	ds_read_b128 v[124:127], v153 offset:23552
	global_load_lds_dwordx4 v[142:143], off
	s_mov_b32 m0, s41
	v_lshl_add_u64 v[142:143], v[248:249], 0, s[8:9]
	global_load_lds_dwordx4 v[142:143], off
	s_barrier
	s_waitcnt lgkmcnt(0)
	s_setprio 1
	v_mfma_f32_16x16x32_bf16 v[142:145], v[0:3], v[44:47], 0
	v_mfma_f32_16x16x32_bf16 v[158:161], v[8:11], v[44:47], 0
	v_mfma_f32_16x16x32_bf16 v[162:165], v[0:3], v[100:103], 0
	v_mfma_f32_16x16x32_bf16 v[166:169], v[8:11], v[100:103], 0
	v_mfma_f32_16x16x32_bf16 v[170:173], v[0:3], v[108:111], 0
	v_mfma_f32_16x16x32_bf16 v[174:177], v[8:11], v[108:111], 0
	v_mfma_f32_16x16x32_bf16 v[0:3], v[0:3], v[120:123], 0
	v_mfma_f32_16x16x32_bf16 v[8:11], v[8:11], v[120:123], 0
	v_mfma_f32_16x16x32_bf16 v[142:145], v[4:7], v[96:99], v[142:145]
	v_mfma_f32_16x16x32_bf16 v[162:165], v[4:7], v[104:107], v[162:165]
	v_mfma_f32_16x16x32_bf16 v[170:173], v[4:7], v[112:115], v[170:173]
	v_mfma_f32_16x16x32_bf16 v[0:3], v[4:7], v[124:127], v[0:3]
	v_mfma_f32_16x16x32_bf16 v[4:7], v[12:15], v[124:127], v[8:11]
	v_mfma_f32_16x16x32_bf16 v[158:161], v[12:15], v[96:99], v[158:161]
	v_mfma_f32_16x16x32_bf16 v[166:169], v[12:15], v[104:107], v[166:169]
	v_mfma_f32_16x16x32_bf16 v[174:177], v[12:15], v[112:115], v[174:177]
	s_setprio 0
	s_barrier
	s_add_u32 s34, s28, 0x40100
	s_addc_u32 s35, s29, 0
	s_mov_b32 m0, s55
	v_lshl_add_u64 v[8:9], s[34:35], 0, v[134:135]
	global_load_lds_dwordx4 v[8:9], off
	s_mov_b32 m0, s56
	v_lshl_add_u64 v[8:9], s[34:35], 0, v[130:131]
	global_load_lds_dwordx4 v[8:9], off
	s_waitcnt vmcnt(6)
	s_barrier
	s_setprio 1
	v_mfma_f32_16x16x32_bf16 v[8:11], v[80:83], v[44:47], 0
	v_mfma_f32_16x16x32_bf16 v[12:15], v[88:91], v[44:47], 0
	v_mfma_f32_16x16x32_bf16 v[44:47], v[80:83], v[100:103], 0
	v_mfma_f32_16x16x32_bf16 v[100:103], v[88:91], v[100:103], 0
	v_mfma_f32_16x16x32_bf16 v[178:181], v[80:83], v[108:111], 0
	v_mfma_f32_16x16x32_bf16 v[108:111], v[88:91], v[108:111], 0
	v_mfma_f32_16x16x32_bf16 v[80:83], v[80:83], v[120:123], 0
	v_mfma_f32_16x16x32_bf16 v[88:91], v[88:91], v[120:123], 0
	v_mfma_f32_16x16x32_bf16 v[12:15], v[92:95], v[96:99], v[12:15]
	v_mfma_f32_16x16x32_bf16 v[44:47], v[84:87], v[104:107], v[44:47]
	v_mfma_f32_16x16x32_bf16 v[182:185], v[84:87], v[96:99], v[8:11]
	v_mfma_f32_16x16x32_bf16 v[186:189], v[92:95], v[104:107], v[100:103]
	v_mfma_f32_16x16x32_bf16 v[178:181], v[84:87], v[112:115], v[178:181]
	v_mfma_f32_16x16x32_bf16 v[190:193], v[92:95], v[112:115], v[108:111]
	v_mfma_f32_16x16x32_bf16 v[194:197], v[84:87], v[124:127], v[80:83]
	v_mfma_f32_16x16x32_bf16 v[198:201], v[92:95], v[124:127], v[88:91]
	s_setprio 0
	s_barrier
	ds_read_b128 v[8:11], v155
	ds_read_b128 v[202:205], v155 offset:1024
	ds_read_b128 v[206:209], v155 offset:2048
	ds_read_b128 v[210:213], v155 offset:3072
	s_add_u32 s34, s26, 0x40100
	s_addc_u32 s35, s27, 0
	s_mov_b32 m0, s42
	v_lshl_add_u64 v[80:81], s[34:35], 0, v[136:137]
	ds_read_b128 v[84:87], v153 offset:32768
	ds_read_b128 v[92:95], v153 offset:33792
	ds_read_b128 v[100:103], v153 offset:34816
	ds_read_b128 v[214:217], v153 offset:35840
	ds_read_b128 v[108:111], v153 offset:36864
	ds_read_b128 v[222:225], v153 offset:37888
	ds_read_b128 v[124:127], v153 offset:38912
	ds_read_b128 v[226:229], v153 offset:39936
	global_load_lds_dwordx4 v[80:81], off
	s_mov_b32 m0, s43
	v_lshl_add_u64 v[80:81], s[34:35], 0, v[132:133]
	global_load_lds_dwordx4 v[80:81], off
	s_waitcnt lgkmcnt(8)
	s_barrier
	s_waitcnt lgkmcnt(0)
	s_setprio 1
	v_mfma_f32_16x16x32_bf16 v[48:51], v[8:11], v[84:87], v[48:51]
	v_mfma_f32_16x16x32_bf16 v[52:55], v[206:209], v[84:87], v[52:55]
	v_mfma_f32_16x16x32_bf16 v[56:59], v[8:11], v[100:103], v[56:59]
	v_mfma_f32_16x16x32_bf16 v[60:63], v[206:209], v[100:103], v[60:63]
	v_mfma_f32_16x16x32_bf16 v[64:67], v[8:11], v[108:111], v[64:67]
	v_mfma_f32_16x16x32_bf16 v[68:71], v[206:209], v[108:111], v[68:71]
	v_mfma_f32_16x16x32_bf16 v[72:75], v[8:11], v[124:127], v[72:75]
	v_mfma_f32_16x16x32_bf16 v[76:79], v[206:209], v[124:127], v[76:79]
	v_mfma_f32_16x16x32_bf16 v[120:123], v[202:205], v[92:95], v[48:51]
	v_mfma_f32_16x16x32_bf16 v[112:115], v[210:213], v[92:95], v[52:55]
	v_mfma_f32_16x16x32_bf16 v[104:107], v[202:205], v[214:217], v[56:59]
	v_mfma_f32_16x16x32_bf16 v[96:99], v[210:213], v[214:217], v[60:63]
	v_mfma_f32_16x16x32_bf16 v[88:91], v[202:205], v[222:225], v[64:67]
	v_mfma_f32_16x16x32_bf16 v[80:83], v[210:213], v[222:225], v[68:71]
	v_mfma_f32_16x16x32_bf16 v[72:75], v[202:205], v[226:229], v[72:75]
	v_mfma_f32_16x16x32_bf16 v[60:63], v[210:213], v[226:229], v[76:79]
	s_setprio 0
	s_barrier
	s_mov_b32 m0, s57
	v_lshl_add_u64 v[48:49], v[218:219], 0, s[12:13]
	ds_read_b128 v[52:55], v156
	ds_read_b128 v[230:233], v156 offset:1024
	ds_read_b128 v[68:71], v156 offset:2048
	ds_read_b128 v[234:237], v156 offset:3072
	global_load_lds_dwordx4 v[48:49], off
	s_mov_b32 m0, s58
	v_lshl_add_u64 v[48:49], v[238:239], 0, s[12:13]
	global_load_lds_dwordx4 v[48:49], off
	s_barrier
	s_waitcnt lgkmcnt(0)
	s_setprio 1
	v_mfma_f32_16x16x32_bf16 v[48:51], v[52:55], v[84:87], v[116:119]
	v_mfma_f32_16x16x32_bf16 v[16:19], v[68:71], v[84:87], v[16:19]
	v_mfma_f32_16x16x32_bf16 v[20:23], v[52:55], v[100:103], v[20:23]
	v_mfma_f32_16x16x32_bf16 v[24:27], v[68:71], v[100:103], v[24:27]
	v_mfma_f32_16x16x32_bf16 v[28:31], v[52:55], v[108:111], v[28:31]
	v_mfma_f32_16x16x32_bf16 v[32:35], v[68:71], v[108:111], v[32:35]
	v_mfma_f32_16x16x32_bf16 v[36:39], v[52:55], v[124:127], v[36:39]
	v_mfma_f32_16x16x32_bf16 v[40:43], v[68:71], v[124:127], v[40:43]
	v_mfma_f32_16x16x32_bf16 v[124:127], v[230:233], v[92:95], v[48:51]
	v_mfma_f32_16x16x32_bf16 v[116:119], v[234:237], v[92:95], v[16:19]
	v_mfma_f32_16x16x32_bf16 v[108:111], v[230:233], v[214:217], v[20:23]
	v_mfma_f32_16x16x32_bf16 v[100:103], v[234:237], v[214:217], v[24:27]
	v_mfma_f32_16x16x32_bf16 v[92:95], v[230:233], v[222:225], v[28:31]
	v_mfma_f32_16x16x32_bf16 v[84:87], v[234:237], v[222:225], v[32:35]
	v_mfma_f32_16x16x32_bf16 v[76:79], v[230:233], v[226:229], v[36:39]
	v_mfma_f32_16x16x32_bf16 v[64:67], v[234:237], v[226:229], v[40:43]
	s_setprio 0
	s_mov_b32 m0, s44
	v_lshl_add_u64 v[16:17], v[246:247], 0, s[12:13]
	s_barrier
	ds_read_b128 v[20:23], v153 offset:49152
	ds_read_b128 v[28:31], v153 offset:50176
	ds_read_b128 v[36:39], v153 offset:51200
	ds_read_b128 v[214:217], v153 offset:52224
	ds_read_b128 v[222:225], v153 offset:53248
	ds_read_b128 v[226:229], v153 offset:54272
	ds_read_b128 v[238:241], v153 offset:55296
	ds_read_b128 v[242:245], v153 offset:56320
	global_load_lds_dwordx4 v[16:17], off
	s_mov_b32 m0, s45
	v_lshl_add_u64 v[16:17], v[248:249], 0, s[12:13]
	global_load_lds_dwordx4 v[16:17], off
	s_barrier
;     ...
;         G_PAIR(0, 1);
; #pragma unroll 1
;         for (int t = 2; t < nt; t += 2) G_PAIR(t, 0);
	s_waitcnt lgkmcnt(0)
	s_setprio 1
	v_mfma_f32_16x16x32_bf16 v[16:19], v[8:11], v[20:23], v[142:145]
	v_mfma_f32_16x16x32_bf16 v[24:27], v[206:209], v[20:23], v[158:161]
	v_mfma_f32_16x16x32_bf16 v[32:35], v[8:11], v[36:39], v[162:165]
	v_mfma_f32_16x16x32_bf16 v[142:145], v[206:209], v[36:39], v[166:169]
	v_mfma_f32_16x16x32_bf16 v[158:161], v[8:11], v[222:225], v[170:173]
	v_mfma_f32_16x16x32_bf16 v[162:165], v[206:209], v[222:225], v[174:177]
	v_mfma_f32_16x16x32_bf16 v[0:3], v[8:11], v[238:241], v[0:3]
	v_mfma_f32_16x16x32_bf16 v[4:7], v[206:209], v[238:241], v[4:7]
	v_mfma_f32_16x16x32_bf16 v[56:59], v[202:205], v[28:31], v[16:19]
	v_mfma_f32_16x16x32_bf16 v[48:51], v[210:213], v[28:31], v[24:27]
	v_mfma_f32_16x16x32_bf16 v[40:43], v[202:205], v[214:217], v[32:35]
	v_mfma_f32_16x16x32_bf16 v[32:35], v[210:213], v[214:217], v[142:145]
	v_mfma_f32_16x16x32_bf16 v[24:27], v[202:205], v[226:229], v[158:161]
	v_mfma_f32_16x16x32_bf16 v[16:19], v[210:213], v[226:229], v[162:165]
	v_mfma_f32_16x16x32_bf16 v[8:11], v[202:205], v[242:245], v[0:3]
	v_mfma_f32_16x16x32_bf16 v[0:3], v[210:213], v[242:245], v[4:7]
	s_setprio 0
	s_barrier
	s_add_u32 s34, s28, 0x40180
	s_addc_u32 s35, s29, 0
	s_mov_b32 m0, s59
	v_lshl_add_u64 v[4:5], s[34:35], 0, v[134:135]
	s_add_i32 s17, s59, 0x2000
	global_load_lds_dwordx4 v[4:5], off
	v_lshl_add_u64 v[4:5], s[34:35], 0, v[130:131]
	s_mov_b32 m0, s17
	s_mov_b64 s[34:35], 0x40180
	global_load_lds_dwordx4 v[4:5], off
	s_waitcnt vmcnt(6)
	s_barrier
	s_setprio 1
	v_mfma_f32_16x16x32_bf16 v[4:7], v[52:55], v[20:23], v[182:185]
	v_mfma_f32_16x16x32_bf16 v[12:15], v[68:71], v[20:23], v[12:15]
	v_mfma_f32_16x16x32_bf16 v[20:23], v[52:55], v[36:39], v[44:47]
	v_mfma_f32_16x16x32_bf16 v[36:39], v[68:71], v[36:39], v[186:189]
	v_mfma_f32_16x16x32_bf16 v[142:145], v[52:55], v[222:225], v[178:181]
	v_mfma_f32_16x16x32_bf16 v[158:161], v[68:71], v[222:225], v[190:193]
	v_mfma_f32_16x16x32_bf16 v[162:165], v[52:55], v[238:241], v[194:197]
	v_mfma_f32_16x16x32_bf16 v[166:169], v[68:71], v[238:241], v[198:201]
	v_mfma_f32_16x16x32_bf16 v[68:71], v[230:233], v[28:31], v[4:7]
	v_mfma_f32_16x16x32_bf16 v[52:55], v[234:237], v[28:31], v[12:15]
	v_mfma_f32_16x16x32_bf16 v[44:47], v[230:233], v[214:217], v[20:23]
	v_mfma_f32_16x16x32_bf16 v[36:39], v[234:237], v[214:217], v[36:39]
	v_mfma_f32_16x16x32_bf16 v[28:31], v[230:233], v[226:229], v[142:145]
	v_mfma_f32_16x16x32_bf16 v[20:23], v[234:237], v[226:229], v[158:161]
	v_mfma_f32_16x16x32_bf16 v[12:15], v[230:233], v[242:245], v[162:165]
	v_mfma_f32_16x16x32_bf16 v[4:7], v[234:237], v[242:245], v[166:169]
	s_setprio 0
	v_lshl_add_u64 v[142:143], s[26:27], 0, v[138:139]
	v_lshl_add_u64 v[144:145], s[26:27], 0, v[140:141]
	s_mov_b32 s19, 0
	s_barrier
.LBB0_232:
	ds_read_b128 v[158:161], v152
	ds_read_b128 v[162:165], v152 offset:1024
	ds_read_b128 v[166:169], v152 offset:2048
	ds_read_b128 v[170:173], v152 offset:3072
	s_mov_b32 m0, s47
	v_lshl_add_u64 v[206:207], v[142:143], 0, s[34:35]
	ds_read_b128 v[174:177], v153
	ds_read_b128 v[178:181], v153 offset:1024
	ds_read_b128 v[182:185], v153 offset:2048
	ds_read_b128 v[186:189], v153 offset:3072
	ds_read_b128 v[190:193], v153 offset:4096
	ds_read_b128 v[194:197], v153 offset:5120
	ds_read_b128 v[198:201], v153 offset:6144
	ds_read_b128 v[202:205], v153 offset:7168
	global_load_lds_dwordx4 v[206:207], off
	s_mov_b32 m0, s48
	v_lshl_add_u64 v[206:207], v[144:145], 0, s[34:35]
	global_load_lds_dwordx4 v[206:207], off
	s_waitcnt lgkmcnt(8)
	s_barrier
	s_waitcnt lgkmcnt(0)
	s_setprio 1
	v_mfma_f32_16x16x32_bf16 v[120:123], v[158:161], v[174:177], v[120:123]
	s_add_i32 s61, s34, 0xfffc0080
	v_mfma_f32_16x16x32_bf16 v[112:115], v[166:169], v[174:177], v[112:115]
	s_cmp_eq_u32 s19, 12
	v_mfma_f32_16x16x32_bf16 v[104:107], v[158:161], v[182:185], v[104:107]
	s_cselect_b64 s[36:37], -1, 0
	v_mfma_f32_16x16x32_bf16 v[96:99], v[166:169], v[182:185], v[96:99]
	s_and_b64 s[62:63], s[36:37], exec
	v_mfma_f32_16x16x32_bf16 v[88:91], v[158:161], v[190:193], v[88:91]
	s_cselect_b32 s61, 0, s61
	v_mfma_f32_16x16x32_bf16 v[80:83], v[166:169], v[190:193], v[80:83]
	s_and_b64 s[36:37], s[30:31], s[36:37]
	v_mfma_f32_16x16x32_bf16 v[72:75], v[158:161], v[198:201], v[72:75]
	s_and_b64 s[36:37], s[36:37], exec
	v_mfma_f32_16x16x32_bf16 v[60:63], v[166:169], v[198:201], v[60:63]
	s_cselect_b32 s63, s21, s27
	v_mfma_f32_16x16x32_bf16 v[120:123], v[162:165], v[178:181], v[120:123]
	s_cselect_b32 s62, s20, s26
	v_mfma_f32_16x16x32_bf16 v[112:115], v[170:173], v[178:181], v[112:115]
	s_cselect_b32 s37, s23, s29
	v_mfma_f32_16x16x32_bf16 v[104:107], v[162:165], v[186:189], v[104:107]
	s_cselect_b32 s36, s22, s28
	v_mfma_f32_16x16x32_bf16 v[96:99], v[170:173], v[186:189], v[96:99]
	v_mfma_f32_16x16x32_bf16 v[88:91], v[162:165], v[194:197], v[88:91]
	v_mfma_f32_16x16x32_bf16 v[80:83], v[170:173], v[194:197], v[80:83]
	v_mfma_f32_16x16x32_bf16 v[72:75], v[162:165], v[202:205], v[72:75]
	v_mfma_f32_16x16x32_bf16 v[60:63], v[170:173], v[202:205], v[60:63]
	s_setprio 0
	s_barrier
	s_add_u32 s36, s36, s61
	s_addc_u32 s37, s37, 0
	s_mov_b32 m0, s49
	v_lshl_add_u64 v[218:219], s[36:37], 0, v[134:135]
	ds_read_b128 v[206:209], v154
	ds_read_b128 v[210:213], v154 offset:1024
	ds_read_b128 v[214:217], v154 offset:2048
	ds_read_b128 v[222:225], v154 offset:3072
	global_load_lds_dwordx4 v[218:219], off
	s_mov_b32 m0, s50
	v_lshl_add_u64 v[226:227], s[36:37], 0, v[130:131]
	global_load_lds_dwordx4 v[226:227], off
	s_barrier
	s_waitcnt lgkmcnt(0)
	s_setprio 1
	v_mfma_f32_16x16x32_bf16 v[124:127], v[206:209], v[174:177], v[124:127]
	v_mfma_f32_16x16x32_bf16 v[116:119], v[214:217], v[174:177], v[116:119]
	v_mfma_f32_16x16x32_bf16 v[108:111], v[206:209], v[182:185], v[108:111]
	v_mfma_f32_16x16x32_bf16 v[100:103], v[214:217], v[182:185], v[100:103]
	v_mfma_f32_16x16x32_bf16 v[92:95], v[206:209], v[190:193], v[92:95]
	v_mfma_f32_16x16x32_bf16 v[84:87], v[214:217], v[190:193], v[84:87]
	v_mfma_f32_16x16x32_bf16 v[76:79], v[206:209], v[198:201], v[76:79]
	v_mfma_f32_16x16x32_bf16 v[64:67], v[214:217], v[198:201], v[64:67]
	v_mfma_f32_16x16x32_bf16 v[124:127], v[210:213], v[178:181], v[124:127]
	v_mfma_f32_16x16x32_bf16 v[116:119], v[222:225], v[178:181], v[116:119]
	v_mfma_f32_16x16x32_bf16 v[108:111], v[210:213], v[186:189], v[108:111]
	v_mfma_f32_16x16x32_bf16 v[100:103], v[222:225], v[186:189], v[100:103]
	v_mfma_f32_16x16x32_bf16 v[92:95], v[210:213], v[194:197], v[92:95]
	v_mfma_f32_16x16x32_bf16 v[84:87], v[222:225], v[194:197], v[84:87]
	v_mfma_f32_16x16x32_bf16 v[76:79], v[210:213], v[202:205], v[76:79]
	v_mfma_f32_16x16x32_bf16 v[64:67], v[222:225], v[202:205], v[64:67]
	s_setprio 0
	s_add_u32 s62, s62, s61
	s_addc_u32 s63, s63, 0
	s_mov_b32 m0, s25
	v_lshl_add_u64 v[228:229], s[62:63], 0, v[136:137]
	s_barrier
	ds_read_b128 v[174:177], v153 offset:16384
	ds_read_b128 v[178:181], v153 offset:17408
	ds_read_b128 v[182:185], v153 offset:18432
	ds_read_b128 v[186:189], v153 offset:19456
	ds_read_b128 v[190:193], v153 offset:20480
	ds_read_b128 v[194:197], v153 offset:21504
	ds_read_b128 v[198:201], v153 offset:22528
	ds_read_b128 v[202:205], v153 offset:23552
	global_load_lds_dwordx4 v[228:229], off
	s_mov_b32 m0, s41
	v_lshl_add_u64 v[230:231], s[62:63], 0, v[132:133]
	global_load_lds_dwordx4 v[230:231], off
	s_barrier
	s_waitcnt lgkmcnt(0)
	s_setprio 1
	v_mfma_f32_16x16x32_bf16 v[56:59], v[158:161], v[174:177], v[56:59]
	v_mfma_f32_16x16x32_bf16 v[48:51], v[166:169], v[174:177], v[48:51]
	v_mfma_f32_16x16x32_bf16 v[40:43], v[158:161], v[182:185], v[40:43]
	v_mfma_f32_16x16x32_bf16 v[32:35], v[166:169], v[182:185], v[32:35]
	v_mfma_f32_16x16x32_bf16 v[24:27], v[158:161], v[190:193], v[24:27]
	v_mfma_f32_16x16x32_bf16 v[16:19], v[166:169], v[190:193], v[16:19]
	v_mfma_f32_16x16x32_bf16 v[8:11], v[158:161], v[198:201], v[8:11]
	v_mfma_f32_16x16x32_bf16 v[0:3], v[166:169], v[198:201], v[0:3]
	v_mfma_f32_16x16x32_bf16 v[56:59], v[162:165], v[178:181], v[56:59]
	v_mfma_f32_16x16x32_bf16 v[48:51], v[170:173], v[178:181], v[48:51]
	v_mfma_f32_16x16x32_bf16 v[40:43], v[162:165], v[186:189], v[40:43]
	v_mfma_f32_16x16x32_bf16 v[32:35], v[170:173], v[186:189], v[32:35]
	v_mfma_f32_16x16x32_bf16 v[24:27], v[162:165], v[194:197], v[24:27]
	v_mfma_f32_16x16x32_bf16 v[16:19], v[170:173], v[194:197], v[16:19]
	v_mfma_f32_16x16x32_bf16 v[8:11], v[162:165], v[202:205], v[8:11]
	v_mfma_f32_16x16x32_bf16 v[0:3], v[170:173], v[202:205], v[0:3]
	s_setprio 0
	s_barrier
	s_add_u32 s64, s36, 0x40000
	s_addc_u32 s65, s37, 0
	s_mov_b32 m0, s55
	v_lshl_add_u64 v[158:159], s[64:65], 0, v[134:135]
	global_load_lds_dwordx4 v[158:159], off
	s_mov_b32 m0, s56
	v_lshl_add_u64 v[158:159], s[64:65], 0, v[130:131]
	global_load_lds_dwordx4 v[158:159], off
	s_waitcnt vmcnt(6)
	s_barrier
	s_setprio 1
	v_mfma_f32_16x16x32_bf16 v[68:71], v[206:209], v[174:177], v[68:71]
	v_mfma_f32_16x16x32_bf16 v[52:55], v[214:217], v[174:177], v[52:55]
	v_mfma_f32_16x16x32_bf16 v[44:47], v[206:209], v[182:185], v[44:47]
	v_mfma_f32_16x16x32_bf16 v[36:39], v[214:217], v[182:185], v[36:39]
	v_mfma_f32_16x16x32_bf16 v[28:31], v[206:209], v[190:193], v[28:31]
	v_mfma_f32_16x16x32_bf16 v[20:23], v[214:217], v[190:193], v[20:23]
	v_mfma_f32_16x16x32_bf16 v[12:15], v[206:209], v[198:201], v[12:15]
	v_mfma_f32_16x16x32_bf16 v[4:7], v[214:217], v[198:201], v[4:7]
	v_mfma_f32_16x16x32_bf16 v[68:71], v[210:213], v[178:181], v[68:71]
	v_mfma_f32_16x16x32_bf16 v[52:55], v[222:225], v[178:181], v[52:55]
	v_mfma_f32_16x16x32_bf16 v[44:47], v[210:213], v[186:189], v[44:47]
	v_mfma_f32_16x16x32_bf16 v[36:39], v[222:225], v[186:189], v[36:39]
	v_mfma_f32_16x16x32_bf16 v[28:31], v[210:213], v[194:197], v[28:31]
	v_mfma_f32_16x16x32_bf16 v[20:23], v[222:225], v[194:197], v[20:23]
	v_mfma_f32_16x16x32_bf16 v[12:15], v[210:213], v[202:205], v[12:15]
	v_mfma_f32_16x16x32_bf16 v[4:7], v[222:225], v[202:205], v[4:7]
	s_setprio 0
	s_barrier
	ds_read_b128 v[158:161], v155
	ds_read_b128 v[162:165], v155 offset:1024
	ds_read_b128 v[166:169], v155 offset:2048
	ds_read_b128 v[170:173], v155 offset:3072
	s_add_u32 s62, s62, 0x40000
	s_addc_u32 s63, s63, 0
	s_mov_b32 m0, s42
	v_lshl_add_u64 v[206:207], s[62:63], 0, v[136:137]
	ds_read_b128 v[174:177], v153 offset:32768
	ds_read_b128 v[178:181], v153 offset:33792
	ds_read_b128 v[182:185], v153 offset:34816
	ds_read_b128 v[186:189], v153 offset:35840
	ds_read_b128 v[190:193], v153 offset:36864
	ds_read_b128 v[194:197], v153 offset:37888
	ds_read_b128 v[198:201], v153 offset:38912
	ds_read_b128 v[202:205], v153 offset:39936
	global_load_lds_dwordx4 v[206:207], off
	s_mov_b32 m0, s43
	v_lshl_add_u64 v[206:207], s[62:63], 0, v[132:133]
	global_load_lds_dwordx4 v[206:207], off
	s_waitcnt lgkmcnt(8)
	s_barrier
	s_waitcnt lgkmcnt(0)
	s_setprio 1
	v_mfma_f32_16x16x32_bf16 v[120:123], v[158:161], v[174:177], v[120:123]
	v_mfma_f32_16x16x32_bf16 v[112:115], v[166:169], v[174:177], v[112:115]
	v_mfma_f32_16x16x32_bf16 v[104:107], v[158:161], v[182:185], v[104:107]
	v_mfma_f32_16x16x32_bf16 v[96:99], v[166:169], v[182:185], v[96:99]
	v_mfma_f32_16x16x32_bf16 v[88:91], v[158:161], v[190:193], v[88:91]
	v_mfma_f32_16x16x32_bf16 v[80:83], v[166:169], v[190:193], v[80:83]
	v_mfma_f32_16x16x32_bf16 v[72:75], v[158:161], v[198:201], v[72:75]
	v_mfma_f32_16x16x32_bf16 v[60:63], v[166:169], v[198:201], v[60:63]
	v_mfma_f32_16x16x32_bf16 v[120:123], v[162:165], v[178:181], v[120:123]
	v_mfma_f32_16x16x32_bf16 v[112:115], v[170:173], v[178:181], v[112:115]
	v_mfma_f32_16x16x32_bf16 v[104:107], v[162:165], v[186:189], v[104:107]
	v_mfma_f32_16x16x32_bf16 v[96:99], v[170:173], v[186:189], v[96:99]
	v_mfma_f32_16x16x32_bf16 v[88:91], v[162:165], v[194:197], v[88:91]
	v_mfma_f32_16x16x32_bf16 v[80:83], v[170:173], v[194:197], v[80:83]
	v_mfma_f32_16x16x32_bf16 v[72:75], v[162:165], v[202:205], v[72:75]
	v_mfma_f32_16x16x32_bf16 v[60:63], v[170:173], v[202:205], v[60:63]
	s_setprio 0
	s_barrier
	s_mov_b32 m0, s57
	v_lshl_add_u64 v[218:219], v[218:219], 0, s[6:7]
	ds_read_b128 v[206:209], v156
	ds_read_b128 v[210:213], v156 offset:1024
	ds_read_b128 v[214:217], v156 offset:2048
	ds_read_b128 v[222:225], v156 offset:3072
	global_load_lds_dwordx4 v[218:219], off
	s_mov_b32 m0, s58
	v_lshl_add_u64 v[218:219], v[226:227], 0, s[6:7]
	global_load_lds_dwordx4 v[218:219], off
	s_barrier
	s_waitcnt lgkmcnt(0)
	s_setprio 1
	v_mfma_f32_16x16x32_bf16 v[124:127], v[206:209], v[174:177], v[124:127]
	v_mfma_f32_16x16x32_bf16 v[116:119], v[214:217], v[174:177], v[116:119]
	v_mfma_f32_16x16x32_bf16 v[108:111], v[206:209], v[182:185], v[108:111]
	v_mfma_f32_16x16x32_bf16 v[100:103], v[214:217], v[182:185], v[100:103]
	v_mfma_f32_16x16x32_bf16 v[92:95], v[206:209], v[190:193], v[92:95]
	v_mfma_f32_16x16x32_bf16 v[84:87], v[214:217], v[190:193], v[84:87]
	v_mfma_f32_16x16x32_bf16 v[76:79], v[206:209], v[198:201], v[76:79]
	v_mfma_f32_16x16x32_bf16 v[64:67], v[214:217], v[198:201], v[64:67]
	v_mfma_f32_16x16x32_bf16 v[124:127], v[210:213], v[178:181], v[124:127]
	v_mfma_f32_16x16x32_bf16 v[116:119], v[222:225], v[178:181], v[116:119]
	v_mfma_f32_16x16x32_bf16 v[108:111], v[210:213], v[186:189], v[108:111]
	v_mfma_f32_16x16x32_bf16 v[100:103], v[222:225], v[186:189], v[100:103]
	v_mfma_f32_16x16x32_bf16 v[92:95], v[210:213], v[194:197], v[92:95]
	v_mfma_f32_16x16x32_bf16 v[84:87], v[222:225], v[194:197], v[84:87]
	v_mfma_f32_16x16x32_bf16 v[76:79], v[210:213], v[202:205], v[76:79]
	v_mfma_f32_16x16x32_bf16 v[64:67], v[222:225], v[202:205], v[64:67]
	s_setprio 0
	s_mov_b32 m0, s44
	v_lshl_add_u64 v[218:219], v[228:229], 0, s[6:7]
	s_barrier
	ds_read_b128 v[174:177], v153 offset:49152
	ds_read_b128 v[178:181], v153 offset:50176
	ds_read_b128 v[182:185], v153 offset:51200
	ds_read_b128 v[186:189], v153 offset:52224
	ds_read_b128 v[190:193], v153 offset:53248
	ds_read_b128 v[194:197], v153 offset:54272
	ds_read_b128 v[198:201], v153 offset:55296
	ds_read_b128 v[202:205], v153 offset:56320
	global_load_lds_dwordx4 v[218:219], off
	s_mov_b32 m0, s45
	v_lshl_add_u64 v[218:219], v[230:231], 0, s[6:7]
	global_load_lds_dwordx4 v[218:219], off
	s_barrier
	s_waitcnt lgkmcnt(0)
	s_setprio 1
	v_mfma_f32_16x16x32_bf16 v[56:59], v[158:161], v[174:177], v[56:59]
	v_mfma_f32_16x16x32_bf16 v[48:51], v[166:169], v[174:177], v[48:51]
	v_mfma_f32_16x16x32_bf16 v[40:43], v[158:161], v[182:185], v[40:43]
	v_mfma_f32_16x16x32_bf16 v[32:35], v[166:169], v[182:185], v[32:35]
	v_mfma_f32_16x16x32_bf16 v[24:27], v[158:161], v[190:193], v[24:27]
	v_mfma_f32_16x16x32_bf16 v[16:19], v[166:169], v[190:193], v[16:19]
	v_mfma_f32_16x16x32_bf16 v[8:11], v[158:161], v[198:201], v[8:11]
	v_mfma_f32_16x16x32_bf16 v[0:3], v[166:169], v[198:201], v[0:3]
	v_mfma_f32_16x16x32_bf16 v[56:59], v[162:165], v[178:181], v[56:59]
	v_mfma_f32_16x16x32_bf16 v[48:51], v[170:173], v[178:181], v[48:51]
	v_mfma_f32_16x16x32_bf16 v[40:43], v[162:165], v[186:189], v[40:43]
	v_mfma_f32_16x16x32_bf16 v[32:35], v[170:173], v[186:189], v[32:35]
	v_mfma_f32_16x16x32_bf16 v[24:27], v[162:165], v[194:197], v[24:27]
	v_mfma_f32_16x16x32_bf16 v[16:19], v[170:173], v[194:197], v[16:19]
	v_mfma_f32_16x16x32_bf16 v[8:11], v[162:165], v[202:205], v[8:11]
	v_mfma_f32_16x16x32_bf16 v[0:3], v[170:173], v[202:205], v[0:3]
	s_setprio 0
	s_barrier
	s_add_u32 s36, s36, 0x40080
	s_addc_u32 s37, s37, 0
	s_mov_b32 m0, s59
	v_lshl_add_u64 v[158:159], s[36:37], 0, v[134:135]
	global_load_lds_dwordx4 v[158:159], off
	s_mov_b32 m0, s17
	v_lshl_add_u64 v[158:159], s[36:37], 0, v[130:131]
	global_load_lds_dwordx4 v[158:159], off
	s_waitcnt vmcnt(6)
	s_barrier
	s_setprio 1
	v_mfma_f32_16x16x32_bf16 v[68:71], v[206:209], v[174:177], v[68:71]
	v_mfma_f32_16x16x32_bf16 v[52:55], v[214:217], v[174:177], v[52:55]
	v_mfma_f32_16x16x32_bf16 v[44:47], v[206:209], v[182:185], v[44:47]
	v_mfma_f32_16x16x32_bf16 v[36:39], v[214:217], v[182:185], v[36:39]
	v_mfma_f32_16x16x32_bf16 v[28:31], v[206:209], v[190:193], v[28:31]
	v_mfma_f32_16x16x32_bf16 v[20:23], v[214:217], v[190:193], v[20:23]
	v_mfma_f32_16x16x32_bf16 v[12:15], v[206:209], v[198:201], v[12:15]
	v_mfma_f32_16x16x32_bf16 v[4:7], v[214:217], v[198:201], v[4:7]
	v_mfma_f32_16x16x32_bf16 v[68:71], v[210:213], v[178:181], v[68:71]
	v_mfma_f32_16x16x32_bf16 v[52:55], v[222:225], v[178:181], v[52:55]
	v_mfma_f32_16x16x32_bf16 v[44:47], v[210:213], v[186:189], v[44:47]
	v_mfma_f32_16x16x32_bf16 v[36:39], v[222:225], v[186:189], v[36:39]
	v_mfma_f32_16x16x32_bf16 v[28:31], v[210:213], v[194:197], v[28:31]
	v_mfma_f32_16x16x32_bf16 v[20:23], v[222:225], v[194:197], v[20:23]
	v_mfma_f32_16x16x32_bf16 v[12:15], v[210:213], v[202:205], v[12:15]
	v_mfma_f32_16x16x32_bf16 v[4:7], v[222:225], v[202:205], v[4:7]
	s_setprio 0
	s_add_i32 s19, s19, 2
	s_add_u32 s34, s34, 0x100
	s_addc_u32 s35, s35, 0
	s_cmp_gt_u32 s19, 13
	s_barrier
; __device__ __forceinline__ unsigned pk2(float lo, float hi) { unsigned r; asm volatile("v_cvt_pk_bf16_f32 %0, %1, %2" : "=v"(r) : "v"(lo), "v"(hi)); return r; }
; __device__ __forceinline__ unsigned pk2(float lo, float hi) { return f2bf(lo) | (f2bf(hi) << 16); }
;     __device__ __forceinline__ void epi(const f32x4 (&acc)[2][2][4][2], const Unit& u, int wr, int wc, int fr, int fq) const {
;         if ((PROBE & 32) && dry) { dry_epi(acc, nq, (float*)H); return; }
;         ConvHost<1> ch; ch.begin(cj, u.g, 2, wr * 4 + wc, fq * 16 + fr);
;         const int row0 = u.pm * 256 + wr * 64 + fr, col0 = u.pn * 128 + wc * 32 + 8 * fq;
; #pragma unroll
;         for (int ai = 0; ai < 2; ++ai)
; #pragma unroll
;             for (int m = 0; m < 4; ++m) {
;                 const int row = row0 + ai * 128 + m * 16; const float rs = rs_lds[((u.pm >> 3) & 1) * 256 + (row & 255)];
;                 const float rs2 = rs * -1.4426950408889634f, rsq = rs * rs;
;                 f32x2 v[4];
; #pragma unroll
;                 for (int n = 0; n < 2; ++n)
; #pragma unroll
;                     for (int jp = 0; jp < 2; ++jp) {
;                         const f32x2 gg = (f32x2){acc[ai][0][m][n][2 * jp], acc[ai][0][m][n][2 * jp + 1]}, uu = (f32x2){acc[ai][1][m][n][2 * jp], acc[ai][1][m][n][2 * jp + 1]};
;                         const f32x2 t = gg * rs2; f32x2 e; e.x = __builtin_amdgcn_exp2f(t.x); e.y = __builtin_amdgcn_exp2f(t.y);
;                         const f32x2 d = e + 1.0f; f32x2 r; r.x = __builtin_amdgcn_rcpf(d.x); r.y = __builtin_amdgcn_rcpf(d.y);
;                         v[n * 2 + jp] = (gg * uu) * (r * rsq);
;                     }
;                 u32x4 w; w.x = pk2(v[0].x, v[0].y); w.y = pk2(v[1].x, v[1].y); w.z = pk2(v[2].x, v[2].y); w.w = pk2(v[3].x, v[3].y);
;                 *(u32x4*)(H + (size_t)row * FF + col0) = w;
	s_cbranch_scc0 .LBB0_232
	s_lshl_b32 s17, s24, 7
	s_and_b32 s17, s17, 0x400
	s_add_i32 s17, s17, 0
	s_add_i32 s17, s17, 0x20000
	v_lshl_add_u32 v142, v151, 2, s17
	ds_read_b32 v143, v142
	v_lshl_add_u32 v142, s24, 8, v129
	v_lshl_or_b32 v144, s60, 7, v150
	v_ashrrev_i32_e32 v145, 31, v144
	s_and_b64 vcc, exec, s[14:15]
	s_waitcnt lgkmcnt(0)
	v_mul_f32_e32 v158, 0xbfb8aa3b, v143
	v_pk_mul_f32 v[160:161], v[120:121], v[158:159] op_sel_hi:[1,0]
	v_pk_mul_f32 v[164:165], v[122:123], v[158:159] op_sel_hi:[1,0]
	v_exp_f32_e32 v160, v160
	v_exp_f32_e32 v161, v161
	v_exp_f32_e32 v164, v164
	v_exp_f32_e32 v165, v165
	v_pk_mul_f32 v[122:123], v[122:123], v[126:127]
	v_pk_add_f32 v[160:161], v[160:161], 1.0 op_sel_hi:[1,0]
	v_mul_f32_e32 v162, v143, v143
	v_rcp_f32_e32 v160, v160
	v_rcp_f32_e32 v161, v161
	v_pk_add_f32 v[126:127], v[164:165], 1.0 op_sel_hi:[1,0]
	v_pk_mul_f32 v[120:121], v[120:121], v[124:125]
	v_rcp_f32_e32 v126, v126
	v_rcp_f32_e32 v127, v127
	v_pk_mul_f32 v[124:125], v[162:163], v[160:161] op_sel_hi:[0,1]
	v_pk_mul_f32 v[160:161], v[112:113], v[158:159] op_sel_hi:[1,0]
	v_pk_mul_f32 v[120:121], v[120:121], v[124:125]
	v_exp_f32_e32 v160, v160
	v_exp_f32_e32 v161, v161
	v_pk_mul_f32 v[124:125], v[162:163], v[126:127] op_sel_hi:[0,1]
	v_pk_mul_f32 v[126:127], v[114:115], v[158:159] op_sel_hi:[1,0]
	v_pk_mul_f32 v[122:123], v[122:123], v[124:125]
	v_exp_f32_e32 v126, v126
	v_exp_f32_e32 v127, v127
	v_pk_add_f32 v[124:125], v[160:161], 1.0 op_sel_hi:[1,0]
	v_pk_mul_f32 v[114:115], v[114:115], v[118:119]
	v_rcp_f32_e32 v124, v124
	v_rcp_f32_e32 v125, v125
	v_pk_add_f32 v[118:119], v[126:127], 1.0 op_sel_hi:[1,0]
	v_pk_mul_f32 v[112:113], v[112:113], v[116:117]
	v_rcp_f32_e32 v118, v118
	v_rcp_f32_e32 v119, v119
	v_pk_mul_f32 v[116:117], v[162:163], v[124:125] op_sel_hi:[0,1]
	v_pk_mul_f32 v[112:113], v[112:113], v[116:117]
	s_mov_b32 s60, s16
	v_pk_mul_f32 v[116:117], v[162:163], v[118:119] op_sel_hi:[0,1]
	v_pk_mul_f32 v[114:115], v[114:115], v[116:117]
	v_cvt_pk_bf16_f32 v116, v120, v121
	v_cvt_pk_bf16_f32 v117, v122, v123
	v_cvt_pk_bf16_f32 v118, v112, v113
	v_bitop3_b32 v112, v142, s52, 16 bitop3:0xc8
	v_lshl_add_u32 v112, v112, 2, s17
	v_cvt_pk_bf16_f32 v119, v114, v115
	ds_read_b32 v123, v112
	v_mov_b64_e32 v[112:113], s[2:3]
	v_mad_i64_i32 v[120:121], s[26:27], v142, s51, v[112:113]
	v_lshlrev_b64 v[114:115], 1, v[144:145]
	s_waitcnt lgkmcnt(0)
	v_mul_f32_e32 v122, 0xbfb8aa3b, v123
	v_pk_mul_f32 v[124:125], v[104:105], v[122:123] op_sel_hi:[1,0]
	v_lshl_add_u64 v[120:121], v[120:121], 0, v[114:115]
	v_exp_f32_e32 v124, v124
	v_exp_f32_e32 v125, v125
	global_store_dwordx4 v[120:121], v[116:119], off
	v_pk_mul_f32 v[120:121], v[106:107], v[122:123] op_sel_hi:[1,0]
	v_pk_mul_f32 v[106:107], v[106:107], v[110:111]
	v_exp_f32_e32 v120, v120
	v_exp_f32_e32 v121, v121
	v_pk_add_f32 v[118:119], v[124:125], 1.0 op_sel_hi:[1,0]
	v_mul_f32_e32 v116, v123, v123
	v_rcp_f32_e32 v118, v118
	v_rcp_f32_e32 v119, v119
	v_pk_add_f32 v[110:111], v[120:121], 1.0 op_sel_hi:[1,0]
	v_pk_mul_f32 v[104:105], v[104:105], v[108:109]
	v_rcp_f32_e32 v110, v110
	v_rcp_f32_e32 v111, v111
	v_pk_mul_f32 v[108:109], v[116:117], v[118:119] op_sel_hi:[0,1]
	v_pk_mul_f32 v[118:119], v[96:97], v[122:123] op_sel_hi:[1,0]
	v_pk_mul_f32 v[104:105], v[104:105], v[108:109]
	v_exp_f32_e32 v118, v118
	v_exp_f32_e32 v119, v119
	v_pk_mul_f32 v[108:109], v[116:117], v[110:111] op_sel_hi:[0,1]
	v_pk_mul_f32 v[110:111], v[98:99], v[122:123] op_sel_hi:[1,0]
	v_pk_mul_f32 v[106:107], v[106:107], v[108:109]
	v_exp_f32_e32 v110, v110
	v_exp_f32_e32 v111, v111
	v_pk_add_f32 v[108:109], v[118:119], 1.0 op_sel_hi:[1,0]
	v_pk_mul_f32 v[98:99], v[98:99], v[102:103]
	v_rcp_f32_e32 v108, v108
	v_rcp_f32_e32 v109, v109
	v_pk_add_f32 v[102:103], v[110:111], 1.0 op_sel_hi:[1,0]
	v_pk_mul_f32 v[96:97], v[96:97], v[100:101]
	v_rcp_f32_e32 v102, v102
	v_rcp_f32_e32 v103, v103
	v_pk_mul_f32 v[100:101], v[116:117], v[108:109] op_sel_hi:[0,1]
	v_pk_mul_f32 v[100:101], v[96:97], v[100:101]
	s_mov_b32 s24, s18
	v_pk_mul_f32 v[96:97], v[116:117], v[102:103] op_sel_hi:[0,1]
	v_pk_mul_f32 v[102:103], v[98:99], v[96:97]
	v_cvt_pk_bf16_f32 v96, v104, v105
	v_cvt_pk_bf16_f32 v97, v106, v107
	v_cvt_pk_bf16_f32 v98, v100, v101
	v_bitop3_b32 v100, v142, s53, 32 bitop3:0xc8
	v_lshl_add_u32 v100, v100, 2, s17
	v_cvt_pk_bf16_f32 v99, v102, v103
	ds_read_b32 v103, v100
	v_or_b32_e32 v100, 16, v142
	v_mad_i64_i32 v[100:101], s[26:27], v100, s51, v[112:113]
	v_lshl_add_u64 v[100:101], v[100:101], 0, v[114:115]
	s_waitcnt lgkmcnt(0)
	v_mul_f32_e32 v102, 0xbfb8aa3b, v103
	v_pk_mul_f32 v[104:105], v[88:89], v[102:103] op_sel_hi:[1,0]
	global_store_dwordx4 v[100:101], v[96:99], off
	v_exp_f32_e32 v104, v104
	v_exp_f32_e32 v105, v105
	v_pk_mul_f32 v[100:101], v[90:91], v[102:103] op_sel_hi:[1,0]
	v_pk_mul_f32 v[90:91], v[90:91], v[94:95]
	v_exp_f32_e32 v100, v100
	v_exp_f32_e32 v101, v101
	v_pk_add_f32 v[98:99], v[104:105], 1.0 op_sel_hi:[1,0]
	v_mul_f32_e32 v96, v103, v103
	v_rcp_f32_e32 v98, v98
	v_rcp_f32_e32 v99, v99
	v_pk_add_f32 v[94:95], v[100:101], 1.0 op_sel_hi:[1,0]
	v_pk_mul_f32 v[88:89], v[88:89], v[92:93]
	v_rcp_f32_e32 v94, v94
	v_rcp_f32_e32 v95, v95
	v_pk_mul_f32 v[92:93], v[96:97], v[98:99] op_sel_hi:[0,1]
	v_pk_mul_f32 v[98:99], v[80:81], v[102:103] op_sel_hi:[1,0]
	v_pk_mul_f32 v[88:89], v[88:89], v[92:93]
	v_exp_f32_e32 v98, v98
	v_exp_f32_e32 v99, v99
	v_pk_mul_f32 v[92:93], v[96:97], v[94:95] op_sel_hi:[0,1]
	v_pk_mul_f32 v[94:95], v[82:83], v[102:103] op_sel_hi:[1,0]
	v_pk_mul_f32 v[90:91], v[90:91], v[92:93]
	v_exp_f32_e32 v94, v94
	v_exp_f32_e32 v95, v95
	v_pk_add_f32 v[92:93], v[98:99], 1.0 op_sel_hi:[1,0]
	v_pk_mul_f32 v[82:83], v[82:83], v[86:87]
	v_rcp_f32_e32 v92, v92
	v_rcp_f32_e32 v93, v93
	v_pk_add_f32 v[86:87], v[94:95], 1.0 op_sel_hi:[1,0]
	v_pk_mul_f32 v[80:81], v[80:81], v[84:85]
	v_rcp_f32_e32 v86, v86
	v_rcp_f32_e32 v87, v87
	v_pk_mul_f32 v[84:85], v[96:97], v[92:93] op_sel_hi:[0,1]
	v_pk_mul_f32 v[84:85], v[80:81], v[84:85]
	s_mov_b64 s[28:29], s[22:23]
	v_pk_mul_f32 v[80:81], v[96:97], v[86:87] op_sel_hi:[0,1]
	v_pk_mul_f32 v[86:87], v[82:83], v[80:81]
	v_cvt_pk_bf16_f32 v80, v88, v89
	v_cvt_pk_bf16_f32 v81, v90, v91
	v_cvt_pk_bf16_f32 v82, v84, v85
	v_bitop3_b32 v84, v142, s54, 48 bitop3:0xc8
	v_lshl_add_u32 v84, v84, 2, s17
	v_cvt_pk_bf16_f32 v83, v86, v87
	ds_read_b32 v87, v84
	v_or_b32_e32 v84, 32, v142
	v_mad_i64_i32 v[84:85], s[26:27], v84, s51, v[112:113]
	v_lshl_add_u64 v[84:85], v[84:85], 0, v[114:115]
	s_waitcnt lgkmcnt(0)
; __device__ __forceinline__ unsigned pk2(float lo, float hi) { unsigned r; asm volatile("v_cvt_pk_bf16_f32 %0, %1, %2" : "=v"(r) : "v"(lo), "v"(hi)); return r; }
; __device__ __forceinline__ unsigned pk2(float lo, float hi) { return f2bf(lo) | (f2bf(hi) << 16); }
;     __device__ __forceinline__ void epi(const f32x4 (&acc)[2][2][4][2], const Unit& u, int wr, int wc, int fr, int fq) const {
;     ...
;             for (int m = 0; m < 4; ++m) {
;                 const int row = row0 + ai * 128 + m * 16; const float rs = rs_lds[((u.pm >> 3) & 1) * 256 + (row & 255)];
;                 const float rs2 = rs * -1.4426950408889634f, rsq = rs * rs;
;                 f32x2 v[4];
; #pragma unroll
;                 for (int n = 0; n < 2; ++n)
; #pragma unroll
;                     for (int jp = 0; jp < 2; ++jp) {
;                         const f32x2 gg = (f32x2){acc[ai][0][m][n][2 * jp], acc[ai][0][m][n][2 * jp + 1]}, uu = (f32x2){acc[ai][1][m][n][2 * jp], acc[ai][1][m][n][2 * jp + 1]};
;                         const f32x2 t = gg * rs2; f32x2 e; e.x = __builtin_amdgcn_exp2f(t.x); e.y = __builtin_amdgcn_exp2f(t.y);
;                         const f32x2 d = e + 1.0f; f32x2 r; r.x = __builtin_amdgcn_rcpf(d.x); r.y = __builtin_amdgcn_rcpf(d.y);
;                         v[n * 2 + jp] = (gg * uu) * (r * rsq);
;                     }
;                 u32x4 w; w.x = pk2(v[0].x, v[0].y); w.y = pk2(v[1].x, v[1].y); w.z = pk2(v[2].x, v[2].y); w.w = pk2(v[3].x, v[3].y);
;                 *(u32x4*)(H + (size_t)row * FF + col0) = w;
	v_mul_f32_e32 v86, 0xbfb8aa3b, v87
	v_pk_mul_f32 v[88:89], v[72:73], v[86:87] op_sel_hi:[1,0]
	global_store_dwordx4 v[84:85], v[80:83], off
	v_exp_f32_e32 v88, v88
	v_exp_f32_e32 v89, v89
	v_pk_mul_f32 v[84:85], v[74:75], v[86:87] op_sel_hi:[1,0]
	v_pk_mul_f32 v[74:75], v[74:75], v[78:79]
	v_exp_f32_e32 v84, v84
	v_exp_f32_e32 v85, v85
	v_pk_add_f32 v[82:83], v[88:89], 1.0 op_sel_hi:[1,0]
	v_mul_f32_e32 v80, v87, v87
	v_rcp_f32_e32 v82, v82
	v_rcp_f32_e32 v83, v83
	v_pk_add_f32 v[78:79], v[84:85], 1.0 op_sel_hi:[1,0]
	v_pk_mul_f32 v[72:73], v[72:73], v[76:77]
	v_rcp_f32_e32 v78, v78
	v_rcp_f32_e32 v79, v79
	v_pk_mul_f32 v[76:77], v[80:81], v[82:83] op_sel_hi:[0,1]
	v_pk_mul_f32 v[82:83], v[60:61], v[86:87] op_sel_hi:[1,0]
	v_pk_mul_f32 v[72:73], v[72:73], v[76:77]
	v_exp_f32_e32 v82, v82
	v_exp_f32_e32 v83, v83
	v_pk_mul_f32 v[76:77], v[80:81], v[78:79] op_sel_hi:[0,1]
	v_pk_mul_f32 v[78:79], v[62:63], v[86:87] op_sel_hi:[1,0]
	v_pk_mul_f32 v[74:75], v[74:75], v[76:77]
	v_exp_f32_e32 v78, v78
	v_exp_f32_e32 v79, v79
	v_pk_add_f32 v[76:77], v[82:83], 1.0 op_sel_hi:[1,0]
	v_pk_mul_f32 v[62:63], v[62:63], v[66:67]
	v_rcp_f32_e32 v76, v76
	v_rcp_f32_e32 v77, v77
	v_pk_add_f32 v[66:67], v[78:79], 1.0 op_sel_hi:[1,0]
	v_pk_mul_f32 v[60:61], v[60:61], v[64:65]
	v_rcp_f32_e32 v66, v66
	v_rcp_f32_e32 v67, v67
	v_pk_mul_f32 v[64:65], v[80:81], v[76:77] op_sel_hi:[0,1]
	v_pk_mul_f32 v[64:65], v[60:61], v[64:65]
	v_pk_mul_f32 v[60:61], v[80:81], v[66:67] op_sel_hi:[0,1]
	v_pk_mul_f32 v[66:67], v[62:63], v[60:61]
	v_cvt_pk_bf16_f32 v60, v72, v73
	v_cvt_pk_bf16_f32 v61, v74, v75
	v_cvt_pk_bf16_f32 v62, v64, v65
	s_nop 0
	v_cvt_pk_bf16_f32 v63, v66, v67
	v_add_u32_e32 v67, 0x80, v142
	v_and_b32_e32 v64, 0xcf, v67
	v_lshl_add_u32 v64, v64, 2, s17
	ds_read_b32 v74, v64
	v_or_b32_e32 v64, 48, v142
	v_mad_i64_i32 v[64:65], s[26:27], v64, s51, v[112:113]
	v_lshl_add_u64 v[64:65], v[64:65], 0, v[114:115]
	s_waitcnt lgkmcnt(0)
	v_mul_f32_e32 v66, 0xbfb8aa3b, v74
	v_pk_mul_f32 v[72:73], v[56:57], v[66:67] op_sel_hi:[1,0]
	global_store_dwordx4 v[64:65], v[60:63], off
	v_exp_f32_e32 v72, v72
	v_exp_f32_e32 v73, v73
	v_pk_mul_f32 v[64:65], v[58:59], v[66:67] op_sel_hi:[1,0]
	v_mul_f32_e32 v60, v74, v74
	v_exp_f32_e32 v64, v64
	v_exp_f32_e32 v65, v65
	v_pk_add_f32 v[62:63], v[72:73], 1.0 op_sel_hi:[1,0]
	v_pk_mul_f32 v[56:57], v[56:57], v[68:69]
	v_rcp_f32_e32 v62, v62
	v_rcp_f32_e32 v63, v63
	v_pk_add_f32 v[64:65], v[64:65], 1.0 op_sel_hi:[1,0]
	v_pk_mul_f32 v[68:69], v[48:49], v[66:67] op_sel_hi:[1,0]
	v_rcp_f32_e32 v64, v64
	v_rcp_f32_e32 v65, v65
	v_pk_mul_f32 v[62:63], v[60:61], v[62:63] op_sel_hi:[0,1]
	v_exp_f32_e32 v68, v68
	v_exp_f32_e32 v69, v69
	v_pk_mul_f32 v[56:57], v[56:57], v[62:63]
	v_pk_mul_f32 v[62:63], v[60:61], v[64:65] op_sel_hi:[0,1]
	v_pk_mul_f32 v[64:65], v[50:51], v[66:67] op_sel_hi:[1,0]
	v_pk_mul_f32 v[58:59], v[58:59], v[70:71]
	v_exp_f32_e32 v64, v64
	v_exp_f32_e32 v65, v65
	v_pk_mul_f32 v[58:59], v[58:59], v[62:63]
	v_pk_add_f32 v[62:63], v[68:69], 1.0 op_sel_hi:[1,0]
	v_pk_mul_f32 v[50:51], v[50:51], v[54:55]
	v_rcp_f32_e32 v62, v62
	v_rcp_f32_e32 v63, v63
	v_pk_add_f32 v[54:55], v[64:65], 1.0 op_sel_hi:[1,0]
	v_pk_mul_f32 v[48:49], v[48:49], v[52:53]
	v_rcp_f32_e32 v54, v54
	v_rcp_f32_e32 v55, v55
	v_pk_mul_f32 v[52:53], v[60:61], v[62:63] op_sel_hi:[0,1]
	v_pk_mul_f32 v[52:53], v[48:49], v[52:53]
	v_pk_mul_f32 v[48:49], v[60:61], v[54:55] op_sel_hi:[0,1]
	v_pk_mul_f32 v[54:55], v[50:51], v[48:49]
	v_cvt_pk_bf16_f32 v48, v56, v57
	v_cvt_pk_bf16_f32 v49, v58, v59
	v_cvt_pk_bf16_f32 v50, v52, v53
	s_nop 0
	v_cvt_pk_bf16_f32 v51, v54, v55
	v_add_u32_e32 v55, 0x90, v142
	v_and_b32_e32 v52, 0xdf, v55
	v_lshl_add_u32 v52, v52, 2, s17
	ds_read_b32 v58, v52
	v_mad_i64_i32 v[52:53], s[26:27], v67, s51, v[112:113]
	v_lshl_add_u64 v[52:53], v[52:53], 0, v[114:115]
	global_store_dwordx4 v[52:53], v[48:51], off
	s_waitcnt lgkmcnt(0)
; __device__ __forceinline__ unsigned pk2(float lo, float hi) { unsigned r; asm volatile("v_cvt_pk_bf16_f32 %0, %1, %2" : "=v"(r) : "v"(lo), "v"(hi)); return r; }
; __device__ __forceinline__ unsigned pk2(float lo, float hi) { return f2bf(lo) | (f2bf(hi) << 16); }
; #define G_WAIT_V(n) asm volatile("s_waitcnt vmcnt(" #n ")" ::: "memory")
; #define G_BAR __builtin_amdgcn_s_barrier()
;     ...
;         if (!has_next) break;
;         cur = nxt; cA = nA; cB = nB; cA2 = nA2; cB2 = nB2; ++ui;
;     }
;     G_WAIT_V(0);
;     if (wr == 0) G_BAR;
;     G_BAR;
;     __device__ __forceinline__ void epi(const f32x4 (&acc)[2][2][4][2], const Unit& u, int wr, int wc, int fr, int fq) const {
;     ...
;             for (int m = 0; m < 4; ++m) {
;                 const int row = row0 + ai * 128 + m * 16; const float rs = rs_lds[((u.pm >> 3) & 1) * 256 + (row & 255)];
;                 const float rs2 = rs * -1.4426950408889634f, rsq = rs * rs;
;                 f32x2 v[4];
; #pragma unroll
;                 for (int n = 0; n < 2; ++n)
; #pragma unroll
;                     for (int jp = 0; jp < 2; ++jp) {
;                         const f32x2 gg = (f32x2){acc[ai][0][m][n][2 * jp], acc[ai][0][m][n][2 * jp + 1]}, uu = (f32x2){acc[ai][1][m][n][2 * jp], acc[ai][1][m][n][2 * jp + 1]};
;                         const f32x2 t = gg * rs2; f32x2 e; e.x = __builtin_amdgcn_exp2f(t.x); e.y = __builtin_amdgcn_exp2f(t.y);
;                         const f32x2 d = e + 1.0f; f32x2 r; r.x = __builtin_amdgcn_rcpf(d.x); r.y = __builtin_amdgcn_rcpf(d.y);
;                         v[n * 2 + jp] = (gg * uu) * (r * rsq);
;                     }
;                 u32x4 w; w.x = pk2(v[0].x, v[0].y); w.y = pk2(v[1].x, v[1].y); w.z = pk2(v[2].x, v[2].y); w.w = pk2(v[3].x, v[3].y);
;                 *(u32x4*)(H + (size_t)row * FF + col0) = w;
;             }
;         ch.finish();
	v_mul_f32_e32 v54, 0xbfb8aa3b, v58
	v_pk_mul_f32 v[56:57], v[40:41], v[54:55] op_sel_hi:[1,0]
	v_pk_mul_f32 v[52:53], v[42:43], v[54:55] op_sel_hi:[1,0]
	v_exp_f32_e32 v56, v56
	v_exp_f32_e32 v57, v57
	v_exp_f32_e32 v52, v52
	v_exp_f32_e32 v53, v53
	v_pk_mul_f32 v[42:43], v[42:43], v[46:47]
	v_pk_add_f32 v[50:51], v[56:57], 1.0 op_sel_hi:[1,0]
	v_mul_f32_e32 v48, v58, v58
	v_rcp_f32_e32 v50, v50
	v_rcp_f32_e32 v51, v51
	v_pk_add_f32 v[46:47], v[52:53], 1.0 op_sel_hi:[1,0]
	v_pk_mul_f32 v[40:41], v[40:41], v[44:45]
	v_rcp_f32_e32 v46, v46
	v_rcp_f32_e32 v47, v47
	v_pk_mul_f32 v[44:45], v[48:49], v[50:51] op_sel_hi:[0,1]
	v_pk_mul_f32 v[50:51], v[32:33], v[54:55] op_sel_hi:[1,0]
	v_pk_mul_f32 v[40:41], v[40:41], v[44:45]
	v_exp_f32_e32 v50, v50
	v_exp_f32_e32 v51, v51
	v_pk_mul_f32 v[44:45], v[48:49], v[46:47] op_sel_hi:[0,1]
	v_pk_mul_f32 v[46:47], v[34:35], v[54:55] op_sel_hi:[1,0]
	v_pk_mul_f32 v[42:43], v[42:43], v[44:45]
	v_exp_f32_e32 v46, v46
	v_exp_f32_e32 v47, v47
	v_pk_add_f32 v[44:45], v[50:51], 1.0 op_sel_hi:[1,0]
	v_pk_mul_f32 v[34:35], v[34:35], v[38:39]
	v_rcp_f32_e32 v44, v44
	v_rcp_f32_e32 v45, v45
	v_pk_add_f32 v[38:39], v[46:47], 1.0 op_sel_hi:[1,0]
	v_pk_mul_f32 v[32:33], v[32:33], v[36:37]
	v_rcp_f32_e32 v38, v38
	v_rcp_f32_e32 v39, v39
	v_pk_mul_f32 v[36:37], v[48:49], v[44:45] op_sel_hi:[0,1]
	v_pk_mul_f32 v[36:37], v[32:33], v[36:37]
	v_pk_mul_f32 v[32:33], v[48:49], v[38:39] op_sel_hi:[0,1]
	v_pk_mul_f32 v[38:39], v[34:35], v[32:33]
	v_cvt_pk_bf16_f32 v32, v40, v41
	v_cvt_pk_bf16_f32 v33, v42, v43
	v_cvt_pk_bf16_f32 v34, v36, v37
	s_nop 0
	v_cvt_pk_bf16_f32 v35, v38, v39
	v_add_u32_e32 v39, 0xa0, v142
	v_and_b32_e32 v36, 0xef, v39
	v_lshl_add_u32 v36, v36, 2, s17
	ds_read_b32 v42, v36
	v_mad_i64_i32 v[36:37], s[26:27], v55, s51, v[112:113]
	v_lshl_add_u64 v[36:37], v[36:37], 0, v[114:115]
	global_store_dwordx4 v[36:37], v[32:35], off
	s_waitcnt lgkmcnt(0)
	v_mul_f32_e32 v38, 0xbfb8aa3b, v42
	v_pk_mul_f32 v[40:41], v[24:25], v[38:39] op_sel_hi:[1,0]
	v_pk_mul_f32 v[36:37], v[26:27], v[38:39] op_sel_hi:[1,0]
	v_exp_f32_e32 v40, v40
	v_exp_f32_e32 v41, v41
	v_exp_f32_e32 v36, v36
	v_exp_f32_e32 v37, v37
	v_pk_mul_f32 v[26:27], v[26:27], v[30:31]
	v_pk_add_f32 v[34:35], v[40:41], 1.0 op_sel_hi:[1,0]
	v_mul_f32_e32 v32, v42, v42
	v_rcp_f32_e32 v34, v34
	v_rcp_f32_e32 v35, v35
	v_pk_add_f32 v[30:31], v[36:37], 1.0 op_sel_hi:[1,0]
	v_pk_mul_f32 v[24:25], v[24:25], v[28:29]
	v_rcp_f32_e32 v30, v30
	v_rcp_f32_e32 v31, v31
	v_pk_mul_f32 v[28:29], v[32:33], v[34:35] op_sel_hi:[0,1]
	v_pk_mul_f32 v[34:35], v[16:17], v[38:39] op_sel_hi:[1,0]
	v_pk_mul_f32 v[24:25], v[24:25], v[28:29]
	v_exp_f32_e32 v34, v34
	v_exp_f32_e32 v35, v35
	v_pk_mul_f32 v[28:29], v[32:33], v[30:31] op_sel_hi:[0,1]
	v_pk_mul_f32 v[30:31], v[18:19], v[38:39] op_sel_hi:[1,0]
	v_pk_mul_f32 v[26:27], v[26:27], v[28:29]
	v_exp_f32_e32 v30, v30
	v_exp_f32_e32 v31, v31
	v_pk_add_f32 v[28:29], v[34:35], 1.0 op_sel_hi:[1,0]
	v_pk_mul_f32 v[18:19], v[18:19], v[22:23]
	v_rcp_f32_e32 v28, v28
	v_rcp_f32_e32 v29, v29
	v_pk_add_f32 v[22:23], v[30:31], 1.0 op_sel_hi:[1,0]
	v_pk_mul_f32 v[16:17], v[16:17], v[20:21]
	v_rcp_f32_e32 v22, v22
	v_rcp_f32_e32 v23, v23
	v_pk_mul_f32 v[20:21], v[32:33], v[28:29] op_sel_hi:[0,1]
	v_pk_mul_f32 v[20:21], v[16:17], v[20:21]
	v_pk_mul_f32 v[16:17], v[32:33], v[22:23] op_sel_hi:[0,1]
	v_pk_mul_f32 v[22:23], v[18:19], v[16:17]
	v_cvt_pk_bf16_f32 v16, v24, v25
	v_cvt_pk_bf16_f32 v17, v26, v27
	v_cvt_pk_bf16_f32 v18, v20, v21
	s_nop 0
	v_cvt_pk_bf16_f32 v19, v22, v23
	v_add_u32_e32 v23, 0xb0, v142
	v_and_b32_e32 v20, 0xff, v23
	v_lshl_add_u32 v20, v20, 2, s17
	ds_read_b32 v26, v20
	v_mad_i64_i32 v[20:21], s[26:27], v39, s51, v[112:113]
	v_lshl_add_u64 v[20:21], v[20:21], 0, v[114:115]
	global_store_dwordx4 v[20:21], v[16:19], off
	s_waitcnt lgkmcnt(0)
	v_mul_f32_e32 v22, 0xbfb8aa3b, v26
	v_pk_mul_f32 v[24:25], v[8:9], v[22:23] op_sel_hi:[1,0]
	v_pk_mul_f32 v[20:21], v[10:11], v[22:23] op_sel_hi:[1,0]
	v_exp_f32_e32 v24, v24
	v_exp_f32_e32 v25, v25
	v_exp_f32_e32 v20, v20
	v_exp_f32_e32 v21, v21
	v_pk_mul_f32 v[10:11], v[10:11], v[14:15]
	v_pk_add_f32 v[18:19], v[24:25], 1.0 op_sel_hi:[1,0]
	v_mul_f32_e32 v16, v26, v26
	v_rcp_f32_e32 v18, v18
	v_rcp_f32_e32 v19, v19
	v_pk_add_f32 v[14:15], v[20:21], 1.0 op_sel_hi:[1,0]
	v_pk_mul_f32 v[8:9], v[8:9], v[12:13]
	v_rcp_f32_e32 v14, v14
	v_rcp_f32_e32 v15, v15
	v_pk_mul_f32 v[12:13], v[16:17], v[18:19] op_sel_hi:[0,1]
	v_pk_mul_f32 v[18:19], v[0:1], v[22:23] op_sel_hi:[1,0]
	v_pk_mul_f32 v[8:9], v[8:9], v[12:13]
	v_exp_f32_e32 v18, v18
	v_exp_f32_e32 v19, v19
	v_pk_mul_f32 v[12:13], v[16:17], v[14:15] op_sel_hi:[0,1]
	v_pk_mul_f32 v[14:15], v[2:3], v[22:23] op_sel_hi:[1,0]
	v_pk_mul_f32 v[10:11], v[10:11], v[12:13]
	v_exp_f32_e32 v14, v14
	v_exp_f32_e32 v15, v15
	v_pk_add_f32 v[12:13], v[18:19], 1.0 op_sel_hi:[1,0]
	v_pk_mul_f32 v[2:3], v[2:3], v[6:7]
	v_rcp_f32_e32 v12, v12
	v_rcp_f32_e32 v13, v13
	v_pk_add_f32 v[6:7], v[14:15], 1.0 op_sel_hi:[1,0]
	v_pk_mul_f32 v[0:1], v[0:1], v[4:5]
	v_rcp_f32_e32 v6, v6
	v_rcp_f32_e32 v7, v7
	v_pk_mul_f32 v[4:5], v[16:17], v[12:13] op_sel_hi:[0,1]
	v_pk_mul_f32 v[4:5], v[0:1], v[4:5]
	v_pk_mul_f32 v[0:1], v[16:17], v[6:7] op_sel_hi:[0,1]
	v_pk_mul_f32 v[6:7], v[2:3], v[0:1]
	v_cvt_pk_bf16_f32 v0, v8, v9
	v_cvt_pk_bf16_f32 v1, v10, v11
	v_cvt_pk_bf16_f32 v2, v4, v5
	v_mad_i64_i32 v[4:5], s[26:27], v23, s51, v[112:113]
	v_lshl_add_u64 v[4:5], v[4:5], 0, v[114:115]
	s_mov_b64 s[26:27], s[20:21]
	v_cvt_pk_bf16_f32 v3, v6, v7
	global_store_dwordx4 v[4:5], v[0:3], off
	s_cbranch_vccz .LBB0_229
	s_waitcnt vmcnt(0)
	s_cmpk_gt_u32 s38, 0xff
	s_cbranch_scc1 .LBB0_236
	s_barrier

.LBB0_356:
	s_waitcnt lgkmcnt(0)
	ds_read_b128 v[0:3], v190
	ds_read_b128 v[4:7], v190 offset:1024
	ds_read_b128 v[8:11], v190 offset:2048
	ds_read_b128 v[12:15], v190 offset:3072
	s_add_u32 s34, s28, 0xb0080
	s_addc_u32 s35, s29, 0
	s_mov_b32 m0, s54
	v_lshl_add_u64 v[48:49], s[34:35], 0, v[154:155]
	ds_read_b128 v[16:19], v191
	ds_read_b128 v[20:23], v191 offset:1024
	ds_read_b128 v[24:27], v191 offset:2048
	ds_read_b128 v[28:31], v191 offset:3072
	ds_read_b128 v[32:35], v191 offset:4096
	ds_read_b128 v[36:39], v191 offset:5120
	ds_read_b128 v[40:43], v191 offset:6144
	ds_read_b128 v[44:47], v191 offset:7168
	global_load_lds_dwordx4 v[48:49], off
	s_mov_b32 m0, s55
	v_lshl_add_u64 v[48:49], s[34:35], 0, v[158:159]
	global_load_lds_dwordx4 v[48:49], off
	s_waitcnt lgkmcnt(8)
	s_barrier
	s_waitcnt lgkmcnt(0)
	s_setprio 1
	v_mfma_f32_16x16x32_bf16 v[48:51], v[0:3], v[16:19], 0
	v_mfma_f32_16x16x32_bf16 v[52:55], v[8:11], v[16:19], 0
	v_mfma_f32_16x16x32_bf16 v[56:59], v[0:3], v[24:27], 0
	v_mfma_f32_16x16x32_bf16 v[60:63], v[8:11], v[24:27], 0
	v_mfma_f32_16x16x32_bf16 v[64:67], v[0:3], v[32:35], 0
	v_mfma_f32_16x16x32_bf16 v[68:71], v[8:11], v[32:35], 0
	v_mfma_f32_16x16x32_bf16 v[72:75], v[0:3], v[40:43], 0
	v_mfma_f32_16x16x32_bf16 v[76:79], v[8:11], v[40:43], 0
	v_mfma_f32_16x16x32_bf16 v[48:51], v[4:7], v[20:23], v[48:51]
	v_mfma_f32_16x16x32_bf16 v[52:55], v[12:15], v[20:23], v[52:55]
	v_mfma_f32_16x16x32_bf16 v[56:59], v[4:7], v[28:31], v[56:59]
	v_mfma_f32_16x16x32_bf16 v[60:63], v[12:15], v[28:31], v[60:63]
	v_mfma_f32_16x16x32_bf16 v[64:67], v[4:7], v[36:39], v[64:67]
	v_mfma_f32_16x16x32_bf16 v[68:71], v[12:15], v[36:39], v[68:71]
	v_mfma_f32_16x16x32_bf16 v[72:75], v[4:7], v[44:47], v[72:75]
	v_mfma_f32_16x16x32_bf16 v[76:79], v[12:15], v[44:47], v[76:79]
	s_setprio 0
	s_barrier
	v_lshl_add_u64 v[182:183], s[30:31], 0, v[156:157]
	s_mov_b32 m0, s56
	v_lshl_add_u64 v[96:97], v[182:183], 0, s[12:13]
	v_lshl_add_u64 v[218:219], s[30:31], 0, v[160:161]
	ds_read_b128 v[80:83], v192
	ds_read_b128 v[84:87], v192 offset:1024
	ds_read_b128 v[88:91], v192 offset:2048
	ds_read_b128 v[92:95], v192 offset:3072
	global_load_lds_dwordx4 v[96:97], off
	s_mov_b32 m0, s57
	v_lshl_add_u64 v[96:97], v[218:219], 0, s[12:13]
	global_load_lds_dwordx4 v[96:97], off
	s_barrier
	s_waitcnt lgkmcnt(0)
	s_setprio 1
	v_mfma_f32_16x16x32_bf16 v[96:99], v[80:83], v[16:19], 0
	v_mfma_f32_16x16x32_bf16 v[16:19], v[88:91], v[16:19], 0
	v_mfma_f32_16x16x32_bf16 v[100:103], v[80:83], v[24:27], 0
	v_mfma_f32_16x16x32_bf16 v[24:27], v[88:91], v[24:27], 0
	v_mfma_f32_16x16x32_bf16 v[104:107], v[80:83], v[32:35], 0
	v_mfma_f32_16x16x32_bf16 v[32:35], v[88:91], v[32:35], 0
	v_mfma_f32_16x16x32_bf16 v[108:111], v[80:83], v[40:43], 0
	v_mfma_f32_16x16x32_bf16 v[40:43], v[88:91], v[40:43], 0
	v_mfma_f32_16x16x32_bf16 v[96:99], v[84:87], v[20:23], v[96:99]
	v_mfma_f32_16x16x32_bf16 v[16:19], v[92:95], v[20:23], v[16:19]
	v_mfma_f32_16x16x32_bf16 v[20:23], v[84:87], v[28:31], v[100:103]
	v_mfma_f32_16x16x32_bf16 v[24:27], v[92:95], v[28:31], v[24:27]
	v_mfma_f32_16x16x32_bf16 v[28:31], v[84:87], v[36:39], v[104:107]
	v_mfma_f32_16x16x32_bf16 v[32:35], v[92:95], v[36:39], v[32:35]
	v_mfma_f32_16x16x32_bf16 v[36:39], v[84:87], v[44:47], v[108:111]
	v_mfma_f32_16x16x32_bf16 v[40:43], v[92:95], v[44:47], v[40:43]
	s_setprio 0
	v_lshl_add_u64 v[246:247], s[28:29], 0, v[154:155]
	s_mov_b32 m0, s46
	v_lshl_add_u64 v[128:129], v[246:247], 0, s[12:13]
	v_lshl_add_u64 v[248:249], s[28:29], 0, v[158:159]
	s_barrier
	ds_read_b128 v[44:47], v191 offset:16384
	ds_read_b128 v[100:103], v191 offset:17408
	ds_read_b128 v[104:107], v191 offset:18432
	ds_read_b128 v[108:111], v191 offset:19456
	ds_read_b128 v[112:115], v191 offset:20480
	ds_read_b128 v[116:119], v191 offset:21504
	ds_read_b128 v[120:123], v191 offset:22528
	ds_read_b128 v[124:127], v191 offset:23552
	global_load_lds_dwordx4 v[128:129], off
	s_mov_b32 m0, s47
	v_lshl_add_u64 v[128:129], v[248:249], 0, s[12:13]
	global_load_lds_dwordx4 v[128:129], off
	s_barrier
	s_waitcnt lgkmcnt(0)
	s_setprio 1
	v_mfma_f32_16x16x32_bf16 v[128:131], v[0:3], v[44:47], 0
	v_mfma_f32_16x16x32_bf16 v[132:135], v[8:11], v[44:47], 0
	v_mfma_f32_16x16x32_bf16 v[136:139], v[0:3], v[104:107], 0
	v_mfma_f32_16x16x32_bf16 v[140:143], v[8:11], v[104:107], 0
	v_mfma_f32_16x16x32_bf16 v[144:147], v[0:3], v[112:115], 0
	v_mfma_f32_16x16x32_bf16 v[148:151], v[8:11], v[112:115], 0
	v_mfma_f32_16x16x32_bf16 v[0:3], v[0:3], v[120:123], 0
	v_mfma_f32_16x16x32_bf16 v[8:11], v[8:11], v[120:123], 0
	v_mfma_f32_16x16x32_bf16 v[128:131], v[4:7], v[100:103], v[128:131]
	v_mfma_f32_16x16x32_bf16 v[166:169], v[12:15], v[100:103], v[132:135]
	v_mfma_f32_16x16x32_bf16 v[134:137], v[4:7], v[108:111], v[136:139]
	v_mfma_f32_16x16x32_bf16 v[138:141], v[12:15], v[108:111], v[140:143]
	v_mfma_f32_16x16x32_bf16 v[142:145], v[4:7], v[116:119], v[144:147]
	v_mfma_f32_16x16x32_bf16 v[0:3], v[4:7], v[124:127], v[0:3]
	v_mfma_f32_16x16x32_bf16 v[4:7], v[12:15], v[124:127], v[8:11]
	v_mfma_f32_16x16x32_bf16 v[146:149], v[12:15], v[116:119], v[148:151]
	s_setprio 0
	s_barrier
	s_add_u32 s34, s30, 0xb0100
	s_addc_u32 s35, s31, 0
	s_add_i32 s0, s53, s43
	v_lshl_add_u64 v[8:9], s[34:35], 0, v[156:157]
	s_mov_b32 m0, s0
	s_add_i32 s62, s0, 0x2000
	global_load_lds_dwordx4 v[8:9], off
	s_mov_b32 m0, s62
	v_lshl_add_u64 v[8:9], s[34:35], 0, v[160:161]
	global_load_lds_dwordx4 v[8:9], off
	s_waitcnt vmcnt(6)
	s_barrier
	s_setprio 1
	v_mfma_f32_16x16x32_bf16 v[8:11], v[80:83], v[44:47], 0
	v_mfma_f32_16x16x32_bf16 v[12:15], v[88:91], v[44:47], 0
	v_mfma_f32_16x16x32_bf16 v[44:47], v[80:83], v[104:107], 0
	v_mfma_f32_16x16x32_bf16 v[104:107], v[88:91], v[104:107], 0
	v_mfma_f32_16x16x32_bf16 v[170:173], v[80:83], v[112:115], 0
	v_mfma_f32_16x16x32_bf16 v[112:115], v[88:91], v[112:115], 0
	v_mfma_f32_16x16x32_bf16 v[80:83], v[80:83], v[120:123], 0
	v_mfma_f32_16x16x32_bf16 v[88:91], v[88:91], v[120:123], 0
	v_mfma_f32_16x16x32_bf16 v[8:11], v[84:87], v[100:103], v[8:11]
	v_mfma_f32_16x16x32_bf16 v[174:177], v[92:95], v[100:103], v[12:15]
	v_mfma_f32_16x16x32_bf16 v[178:181], v[84:87], v[108:111], v[44:47]
	v_mfma_f32_16x16x32_bf16 v[194:197], v[92:95], v[108:111], v[104:107]
	v_mfma_f32_16x16x32_bf16 v[170:173], v[84:87], v[116:119], v[170:173]
	v_mfma_f32_16x16x32_bf16 v[198:201], v[92:95], v[116:119], v[112:115]
	v_mfma_f32_16x16x32_bf16 v[202:205], v[84:87], v[124:127], v[80:83]
	v_mfma_f32_16x16x32_bf16 v[206:209], v[92:95], v[124:127], v[88:91]
	s_setprio 0
	s_add_i32 s63, 0, 0x18000
	v_add_u32_e32 v132, s63, v188
	s_barrier
	ds_read_b128 v[12:15], v132
	ds_read_b128 v[210:213], v132 offset:1024
	ds_read_b128 v[44:47], v132 offset:2048
	ds_read_b128 v[214:217], v132 offset:3072
	s_add_u32 s34, s28, 0xb0100
	s_addc_u32 s35, s29, 0
	s_mov_b32 m0, s48
	v_lshl_add_u64 v[88:89], s[34:35], 0, v[154:155]
	ds_read_b128 v[80:83], v191 offset:32768
	ds_read_b128 v[84:87], v191 offset:33792
	ds_read_b128 v[100:103], v191 offset:34816
	ds_read_b128 v[222:225], v191 offset:35840
	ds_read_b128 v[120:123], v191 offset:36864
	ds_read_b128 v[226:229], v191 offset:37888
	ds_read_b128 v[124:127], v191 offset:38912
	ds_read_b128 v[230:233], v191 offset:39936
	global_load_lds_dwordx4 v[88:89], off
	s_mov_b32 m0, s49
	v_lshl_add_u64 v[88:89], s[34:35], 0, v[158:159]
	global_load_lds_dwordx4 v[88:89], off
	s_waitcnt lgkmcnt(8)
	s_barrier
	s_waitcnt lgkmcnt(0)
	s_setprio 1
	v_mfma_f32_16x16x32_bf16 v[48:51], v[12:15], v[80:83], v[48:51]
	v_mfma_f32_16x16x32_bf16 v[52:55], v[44:47], v[80:83], v[52:55]
	v_mfma_f32_16x16x32_bf16 v[56:59], v[12:15], v[100:103], v[56:59]
	v_mfma_f32_16x16x32_bf16 v[60:63], v[44:47], v[100:103], v[60:63]
	v_mfma_f32_16x16x32_bf16 v[64:67], v[12:15], v[120:123], v[64:67]
	v_mfma_f32_16x16x32_bf16 v[68:71], v[44:47], v[120:123], v[68:71]
	v_mfma_f32_16x16x32_bf16 v[72:75], v[12:15], v[124:127], v[72:75]
	v_mfma_f32_16x16x32_bf16 v[234:237], v[44:47], v[124:127], v[76:79]
	v_mfma_f32_16x16x32_bf16 v[116:119], v[210:213], v[84:87], v[48:51]
	v_mfma_f32_16x16x32_bf16 v[112:115], v[214:217], v[84:87], v[52:55]
	v_mfma_f32_16x16x32_bf16 v[108:111], v[210:213], v[222:225], v[56:59]
	v_mfma_f32_16x16x32_bf16 v[104:107], v[214:217], v[222:225], v[60:63]
	v_mfma_f32_16x16x32_bf16 v[92:95], v[210:213], v[226:229], v[64:67]
	v_mfma_f32_16x16x32_bf16 v[88:91], v[214:217], v[226:229], v[68:71]
	v_mfma_f32_16x16x32_bf16 v[76:79], v[210:213], v[230:233], v[72:75]
	v_mfma_f32_16x16x32_bf16 v[72:75], v[214:217], v[230:233], v[234:237]
	s_setprio 0
	s_barrier
	s_add_i32 s65, 0, 0x1c000
	s_add_i32 s63, s63, s43
	v_add_u32_e32 v133, s65, v188
	v_lshl_add_u64 v[48:49], v[182:183], 0, s[14:15]
	s_mov_b32 m0, s63
	s_add_i32 s64, s63, 0x2000
	ds_read_b128 v[56:59], v133
	ds_read_b128 v[234:237], v133 offset:1024
	ds_read_b128 v[60:63], v133 offset:2048
	ds_read_b128 v[238:241], v133 offset:3072
	global_load_lds_dwordx4 v[48:49], off
	s_mov_b32 m0, s64
	v_lshl_add_u64 v[48:49], v[218:219], 0, s[14:15]
	global_load_lds_dwordx4 v[48:49], off
	s_barrier
	s_waitcnt lgkmcnt(0)
	s_setprio 1
	v_mfma_f32_16x16x32_bf16 v[48:51], v[56:59], v[80:83], v[96:99]
	v_mfma_f32_16x16x32_bf16 v[16:19], v[60:63], v[80:83], v[16:19]
	v_mfma_f32_16x16x32_bf16 v[20:23], v[56:59], v[100:103], v[20:23]
	v_mfma_f32_16x16x32_bf16 v[24:27], v[60:63], v[100:103], v[24:27]
	v_mfma_f32_16x16x32_bf16 v[28:31], v[56:59], v[120:123], v[28:31]
	v_mfma_f32_16x16x32_bf16 v[32:35], v[60:63], v[120:123], v[32:35]
	v_mfma_f32_16x16x32_bf16 v[36:39], v[56:59], v[124:127], v[36:39]
	v_mfma_f32_16x16x32_bf16 v[40:43], v[60:63], v[124:127], v[40:43]
	v_mfma_f32_16x16x32_bf16 v[124:127], v[234:237], v[84:87], v[48:51]
	v_mfma_f32_16x16x32_bf16 v[120:123], v[238:241], v[84:87], v[16:19]
	v_mfma_f32_16x16x32_bf16 v[100:103], v[234:237], v[222:225], v[20:23]
	v_mfma_f32_16x16x32_bf16 v[96:99], v[238:241], v[222:225], v[24:27]
	v_mfma_f32_16x16x32_bf16 v[84:87], v[234:237], v[226:229], v[28:31]
	v_mfma_f32_16x16x32_bf16 v[80:83], v[238:241], v[226:229], v[32:35]
	v_mfma_f32_16x16x32_bf16 v[68:71], v[234:237], v[230:233], v[36:39]
	v_mfma_f32_16x16x32_bf16 v[64:67], v[238:241], v[230:233], v[40:43]
	s_setprio 0
	s_mov_b32 m0, s51
	v_lshl_add_u64 v[20:21], v[246:247], 0, s[14:15]
	s_barrier
	ds_read_b128 v[16:19], v191 offset:49152
	ds_read_b128 v[24:27], v191 offset:50176
	ds_read_b128 v[32:35], v191 offset:51200
	ds_read_b128 v[222:225], v191 offset:52224
	ds_read_b128 v[40:43], v191 offset:53248
	ds_read_b128 v[226:229], v191 offset:54272
	ds_read_b128 v[230:233], v191 offset:55296
	ds_read_b128 v[242:245], v191 offset:56320
	global_load_lds_dwordx4 v[20:21], off
	s_mov_b32 m0, s52
	v_lshl_add_u64 v[20:21], v[248:249], 0, s[14:15]
	global_load_lds_dwordx4 v[20:21], off
	s_barrier
;     ...
;         G_PAIR(0, 1);
; #pragma unroll 1
;         for (int t = 2; t < nt; t += 2) G_PAIR(t, 0);
	s_waitcnt lgkmcnt(0)
	s_setprio 1
	v_mfma_f32_16x16x32_bf16 v[20:23], v[12:15], v[16:19], v[128:131]
	v_mfma_f32_16x16x32_bf16 v[28:31], v[44:47], v[16:19], v[166:169]
	v_mfma_f32_16x16x32_bf16 v[36:39], v[12:15], v[32:35], v[134:137]
	v_mfma_f32_16x16x32_bf16 v[128:131], v[44:47], v[32:35], v[138:141]
	v_mfma_f32_16x16x32_bf16 v[134:137], v[12:15], v[40:43], v[142:145]
	v_mfma_f32_16x16x32_bf16 v[138:141], v[44:47], v[40:43], v[146:149]
	v_mfma_f32_16x16x32_bf16 v[0:3], v[12:15], v[230:233], v[0:3]
	v_mfma_f32_16x16x32_bf16 v[4:7], v[44:47], v[230:233], v[4:7]
	v_mfma_f32_16x16x32_bf16 v[52:55], v[210:213], v[24:27], v[20:23]
	v_mfma_f32_16x16x32_bf16 v[48:51], v[214:217], v[24:27], v[28:31]
	v_mfma_f32_16x16x32_bf16 v[44:47], v[210:213], v[222:225], v[36:39]
	v_mfma_f32_16x16x32_bf16 v[36:39], v[214:217], v[222:225], v[128:131]
	v_mfma_f32_16x16x32_bf16 v[28:31], v[210:213], v[226:229], v[134:137]
	v_mfma_f32_16x16x32_bf16 v[20:23], v[214:217], v[226:229], v[138:141]
	v_mfma_f32_16x16x32_bf16 v[12:15], v[210:213], v[242:245], v[0:3]
	v_mfma_f32_16x16x32_bf16 v[4:7], v[214:217], v[242:245], v[4:7]
	s_setprio 0
	s_barrier
	s_add_u32 s34, s30, 0xb0180
	s_addc_u32 s35, s31, 0
	s_add_i32 s65, s65, s43
	v_lshl_add_u64 v[0:1], s[34:35], 0, v[156:157]
	s_mov_b32 m0, s65
	s_add_i32 s66, s65, 0x2000
	global_load_lds_dwordx4 v[0:1], off
	v_lshl_add_u64 v[0:1], s[34:35], 0, v[160:161]
	s_mov_b32 m0, s66
	s_mov_b64 s[34:35], 0xb0180
	global_load_lds_dwordx4 v[0:1], off
	s_waitcnt vmcnt(6)
	s_barrier
	s_setprio 1
	v_mfma_f32_16x16x32_bf16 v[0:3], v[56:59], v[16:19], v[8:11]
	v_mfma_f32_16x16x32_bf16 v[8:11], v[60:63], v[16:19], v[174:177]
	v_mfma_f32_16x16x32_bf16 v[16:19], v[56:59], v[32:35], v[178:181]
	v_mfma_f32_16x16x32_bf16 v[32:35], v[60:63], v[32:35], v[194:197]
	v_mfma_f32_16x16x32_bf16 v[128:131], v[56:59], v[40:43], v[170:173]
	v_mfma_f32_16x16x32_bf16 v[134:137], v[60:63], v[40:43], v[198:201]
	v_mfma_f32_16x16x32_bf16 v[138:141], v[56:59], v[230:233], v[202:205]
	v_mfma_f32_16x16x32_bf16 v[142:145], v[60:63], v[230:233], v[206:209]
	v_mfma_f32_16x16x32_bf16 v[60:63], v[234:237], v[24:27], v[0:3]
	v_mfma_f32_16x16x32_bf16 v[56:59], v[238:241], v[24:27], v[8:11]
	v_mfma_f32_16x16x32_bf16 v[40:43], v[234:237], v[222:225], v[16:19]
	v_mfma_f32_16x16x32_bf16 v[32:35], v[238:241], v[222:225], v[32:35]
	v_mfma_f32_16x16x32_bf16 v[24:27], v[234:237], v[226:229], v[128:131]
	v_mfma_f32_16x16x32_bf16 v[16:19], v[238:241], v[226:229], v[134:137]
	v_mfma_f32_16x16x32_bf16 v[8:11], v[234:237], v[242:245], v[138:141]
	v_mfma_f32_16x16x32_bf16 v[0:3], v[238:241], v[242:245], v[142:145]
	s_setprio 0
	v_lshl_add_u64 v[128:129], s[28:29], 0, v[162:163]
	v_lshl_add_u64 v[130:131], s[28:29], 0, v[164:165]
	s_mov_b32 s67, 0
	s_barrier
.LBB0_357:
	ds_read_b128 v[134:137], v190
	ds_read_b128 v[138:141], v190 offset:1024
	ds_read_b128 v[142:145], v190 offset:2048
	ds_read_b128 v[146:149], v190 offset:3072
	s_mov_b32 m0, s54
	v_lshl_add_u64 v[150:151], v[128:129], 0, s[34:35]
	ds_read_b128 v[166:169], v191
	ds_read_b128 v[170:173], v191 offset:1024
	ds_read_b128 v[174:177], v191 offset:2048
	ds_read_b128 v[178:181], v191 offset:3072
	ds_read_b128 v[194:197], v191 offset:4096
	ds_read_b128 v[198:201], v191 offset:5120
	ds_read_b128 v[202:205], v191 offset:6144
	ds_read_b128 v[206:209], v191 offset:7168
	global_load_lds_dwordx4 v[150:151], off
	s_mov_b32 m0, s55
	v_lshl_add_u64 v[150:151], v[130:131], 0, s[34:35]
	global_load_lds_dwordx4 v[150:151], off
	s_waitcnt lgkmcnt(8)
	s_barrier
	s_waitcnt lgkmcnt(0)
	s_setprio 1
	v_mfma_f32_16x16x32_bf16 v[116:119], v[134:137], v[166:169], v[116:119]
	s_add_i32 s36, s34, 0xfff50080
	v_mfma_f32_16x16x32_bf16 v[112:115], v[142:145], v[166:169], v[112:115]
	s_cmp_eq_u32 s67, 40
	v_mfma_f32_16x16x32_bf16 v[108:111], v[134:137], v[174:177], v[108:111]
	s_cselect_b32 s69, s27, s29
	v_mfma_f32_16x16x32_bf16 v[104:107], v[142:145], v[174:177], v[104:107]
	s_cselect_b32 s68, s26, s28
	v_mfma_f32_16x16x32_bf16 v[92:95], v[134:137], v[194:197], v[92:95]
	s_cselect_b32 s37, s9, s31
	v_mfma_f32_16x16x32_bf16 v[88:91], v[142:145], v[194:197], v[88:91]
	s_cselect_b32 s70, s8, s30
	v_mfma_f32_16x16x32_bf16 v[76:79], v[134:137], v[202:205], v[76:79]
	v_mfma_f32_16x16x32_bf16 v[72:75], v[142:145], v[202:205], v[72:75]
	v_mfma_f32_16x16x32_bf16 v[116:119], v[138:141], v[170:173], v[116:119]
	v_mfma_f32_16x16x32_bf16 v[112:115], v[146:149], v[170:173], v[112:115]
	v_mfma_f32_16x16x32_bf16 v[108:111], v[138:141], v[178:181], v[108:111]
	v_mfma_f32_16x16x32_bf16 v[104:107], v[146:149], v[178:181], v[104:107]
	v_mfma_f32_16x16x32_bf16 v[92:95], v[138:141], v[198:201], v[92:95]
	v_mfma_f32_16x16x32_bf16 v[88:91], v[146:149], v[198:201], v[88:91]
	v_mfma_f32_16x16x32_bf16 v[76:79], v[138:141], v[206:209], v[76:79]
	v_mfma_f32_16x16x32_bf16 v[72:75], v[146:149], v[206:209], v[72:75]
	s_setprio 0
	s_barrier
	s_cselect_b32 s71, 0, s36
	s_add_u32 s36, s70, s71
	s_addc_u32 s37, s37, 0
	s_mov_b32 m0, s56
	v_lshl_add_u64 v[150:151], s[36:37], 0, v[156:157]
	ds_read_b128 v[210:213], v192
	ds_read_b128 v[214:217], v192 offset:1024
	ds_read_b128 v[222:225], v192 offset:2048
	ds_read_b128 v[226:229], v192 offset:3072
	global_load_lds_dwordx4 v[150:151], off
	s_mov_b32 m0, s57
	v_lshl_add_u64 v[182:183], s[36:37], 0, v[160:161]
	global_load_lds_dwordx4 v[182:183], off
	s_barrier
	s_waitcnt lgkmcnt(0)
	s_setprio 1
	v_mfma_f32_16x16x32_bf16 v[124:127], v[210:213], v[166:169], v[124:127]
	v_mfma_f32_16x16x32_bf16 v[120:123], v[222:225], v[166:169], v[120:123]
	v_mfma_f32_16x16x32_bf16 v[100:103], v[210:213], v[174:177], v[100:103]
	v_mfma_f32_16x16x32_bf16 v[96:99], v[222:225], v[174:177], v[96:99]
	v_mfma_f32_16x16x32_bf16 v[84:87], v[210:213], v[194:197], v[84:87]
	v_mfma_f32_16x16x32_bf16 v[80:83], v[222:225], v[194:197], v[80:83]
	v_mfma_f32_16x16x32_bf16 v[68:71], v[210:213], v[202:205], v[68:71]
	v_mfma_f32_16x16x32_bf16 v[64:67], v[222:225], v[202:205], v[64:67]
	v_mfma_f32_16x16x32_bf16 v[124:127], v[214:217], v[170:173], v[124:127]
	v_mfma_f32_16x16x32_bf16 v[120:123], v[226:229], v[170:173], v[120:123]
	v_mfma_f32_16x16x32_bf16 v[100:103], v[214:217], v[178:181], v[100:103]
	v_mfma_f32_16x16x32_bf16 v[96:99], v[226:229], v[178:181], v[96:99]
	v_mfma_f32_16x16x32_bf16 v[84:87], v[214:217], v[198:201], v[84:87]
	v_mfma_f32_16x16x32_bf16 v[80:83], v[226:229], v[198:201], v[80:83]
	v_mfma_f32_16x16x32_bf16 v[68:71], v[214:217], v[206:209], v[68:71]
	v_mfma_f32_16x16x32_bf16 v[64:67], v[226:229], v[206:209], v[64:67]
	s_setprio 0
	s_add_u32 s68, s68, s71
	s_addc_u32 s69, s69, 0
	s_mov_b32 m0, s46
	v_lshl_add_u64 v[218:219], s[68:69], 0, v[154:155]
	s_barrier
	ds_read_b128 v[166:169], v191 offset:16384
	ds_read_b128 v[170:173], v191 offset:17408
	ds_read_b128 v[174:177], v191 offset:18432
	ds_read_b128 v[178:181], v191 offset:19456
	ds_read_b128 v[194:197], v191 offset:20480
	ds_read_b128 v[198:201], v191 offset:21504
	ds_read_b128 v[202:205], v191 offset:22528
	ds_read_b128 v[206:209], v191 offset:23552
	global_load_lds_dwordx4 v[218:219], off
	s_mov_b32 m0, s47
	v_lshl_add_u64 v[230:231], s[68:69], 0, v[158:159]
	global_load_lds_dwordx4 v[230:231], off
	s_barrier
	s_waitcnt lgkmcnt(0)
	s_setprio 1
	v_mfma_f32_16x16x32_bf16 v[52:55], v[134:137], v[166:169], v[52:55]
	v_mfma_f32_16x16x32_bf16 v[48:51], v[142:145], v[166:169], v[48:51]
	v_mfma_f32_16x16x32_bf16 v[44:47], v[134:137], v[174:177], v[44:47]
	v_mfma_f32_16x16x32_bf16 v[36:39], v[142:145], v[174:177], v[36:39]
	v_mfma_f32_16x16x32_bf16 v[28:31], v[134:137], v[194:197], v[28:31]
	v_mfma_f32_16x16x32_bf16 v[20:23], v[142:145], v[194:197], v[20:23]
	v_mfma_f32_16x16x32_bf16 v[12:15], v[134:137], v[202:205], v[12:15]
	v_mfma_f32_16x16x32_bf16 v[4:7], v[142:145], v[202:205], v[4:7]
	v_mfma_f32_16x16x32_bf16 v[52:55], v[138:141], v[170:173], v[52:55]
	v_mfma_f32_16x16x32_bf16 v[48:51], v[146:149], v[170:173], v[48:51]
	v_mfma_f32_16x16x32_bf16 v[44:47], v[138:141], v[178:181], v[44:47]
	v_mfma_f32_16x16x32_bf16 v[36:39], v[146:149], v[178:181], v[36:39]
	v_mfma_f32_16x16x32_bf16 v[28:31], v[138:141], v[198:201], v[28:31]
	v_mfma_f32_16x16x32_bf16 v[20:23], v[146:149], v[198:201], v[20:23]
	v_mfma_f32_16x16x32_bf16 v[12:15], v[138:141], v[206:209], v[12:15]
	v_mfma_f32_16x16x32_bf16 v[4:7], v[146:149], v[206:209], v[4:7]
	s_setprio 0
	s_barrier
	s_add_u32 s70, s36, 0xb0000
	s_addc_u32 s71, s37, 0
	s_mov_b32 m0, s0
	v_lshl_add_u64 v[134:135], s[70:71], 0, v[156:157]
	global_load_lds_dwordx4 v[134:135], off
	s_mov_b32 m0, s62
	v_lshl_add_u64 v[134:135], s[70:71], 0, v[160:161]
	global_load_lds_dwordx4 v[134:135], off
	s_waitcnt vmcnt(6)
	s_barrier
	s_setprio 1
	v_mfma_f32_16x16x32_bf16 v[60:63], v[210:213], v[166:169], v[60:63]
	v_mfma_f32_16x16x32_bf16 v[56:59], v[222:225], v[166:169], v[56:59]
	v_mfma_f32_16x16x32_bf16 v[40:43], v[210:213], v[174:177], v[40:43]
	v_mfma_f32_16x16x32_bf16 v[32:35], v[222:225], v[174:177], v[32:35]
	v_mfma_f32_16x16x32_bf16 v[24:27], v[210:213], v[194:197], v[24:27]
	v_mfma_f32_16x16x32_bf16 v[16:19], v[222:225], v[194:197], v[16:19]
	v_mfma_f32_16x16x32_bf16 v[8:11], v[210:213], v[202:205], v[8:11]
	v_mfma_f32_16x16x32_bf16 v[0:3], v[222:225], v[202:205], v[0:3]
	v_mfma_f32_16x16x32_bf16 v[60:63], v[214:217], v[170:173], v[60:63]
	v_mfma_f32_16x16x32_bf16 v[56:59], v[226:229], v[170:173], v[56:59]
	v_mfma_f32_16x16x32_bf16 v[40:43], v[214:217], v[178:181], v[40:43]
	v_mfma_f32_16x16x32_bf16 v[32:35], v[226:229], v[178:181], v[32:35]
	v_mfma_f32_16x16x32_bf16 v[24:27], v[214:217], v[198:201], v[24:27]
	v_mfma_f32_16x16x32_bf16 v[16:19], v[226:229], v[198:201], v[16:19]
	v_mfma_f32_16x16x32_bf16 v[8:11], v[214:217], v[206:209], v[8:11]
	v_mfma_f32_16x16x32_bf16 v[0:3], v[226:229], v[206:209], v[0:3]
	s_setprio 0
	s_barrier
	ds_read_b128 v[134:137], v132
	ds_read_b128 v[138:141], v132 offset:1024
	ds_read_b128 v[142:145], v132 offset:2048
	ds_read_b128 v[146:149], v132 offset:3072
	s_add_u32 s68, s68, 0xb0000
	s_addc_u32 s69, s69, 0
	s_mov_b32 m0, s48
	v_lshl_add_u64 v[210:211], s[68:69], 0, v[154:155]
	ds_read_b128 v[166:169], v191 offset:32768
	ds_read_b128 v[170:173], v191 offset:33792
	ds_read_b128 v[174:177], v191 offset:34816
	ds_read_b128 v[178:181], v191 offset:35840
	ds_read_b128 v[194:197], v191 offset:36864
	ds_read_b128 v[198:201], v191 offset:37888
	ds_read_b128 v[202:205], v191 offset:38912
	ds_read_b128 v[206:209], v191 offset:39936
	global_load_lds_dwordx4 v[210:211], off
	s_mov_b32 m0, s49
	v_lshl_add_u64 v[210:211], s[68:69], 0, v[158:159]
	global_load_lds_dwordx4 v[210:211], off
	s_waitcnt lgkmcnt(8)
	s_barrier
	s_waitcnt lgkmcnt(0)
	s_setprio 1
	v_mfma_f32_16x16x32_bf16 v[116:119], v[134:137], v[166:169], v[116:119]
	v_mfma_f32_16x16x32_bf16 v[112:115], v[142:145], v[166:169], v[112:115]
	v_mfma_f32_16x16x32_bf16 v[108:111], v[134:137], v[174:177], v[108:111]
	v_mfma_f32_16x16x32_bf16 v[104:107], v[142:145], v[174:177], v[104:107]
	v_mfma_f32_16x16x32_bf16 v[92:95], v[134:137], v[194:197], v[92:95]
	v_mfma_f32_16x16x32_bf16 v[88:91], v[142:145], v[194:197], v[88:91]
	v_mfma_f32_16x16x32_bf16 v[76:79], v[134:137], v[202:205], v[76:79]
	v_mfma_f32_16x16x32_bf16 v[72:75], v[142:145], v[202:205], v[72:75]
	v_mfma_f32_16x16x32_bf16 v[116:119], v[138:141], v[170:173], v[116:119]
	v_mfma_f32_16x16x32_bf16 v[112:115], v[146:149], v[170:173], v[112:115]
	v_mfma_f32_16x16x32_bf16 v[108:111], v[138:141], v[178:181], v[108:111]
	v_mfma_f32_16x16x32_bf16 v[104:107], v[146:149], v[178:181], v[104:107]
	v_mfma_f32_16x16x32_bf16 v[92:95], v[138:141], v[198:201], v[92:95]
	v_mfma_f32_16x16x32_bf16 v[88:91], v[146:149], v[198:201], v[88:91]
	v_mfma_f32_16x16x32_bf16 v[76:79], v[138:141], v[206:209], v[76:79]
	v_mfma_f32_16x16x32_bf16 v[72:75], v[146:149], v[206:209], v[72:75]
	s_setprio 0
	s_barrier
	s_mov_b32 m0, s63
	v_lshl_add_u64 v[150:151], v[150:151], 0, s[10:11]
	ds_read_b128 v[210:213], v133
	ds_read_b128 v[214:217], v133 offset:1024
	ds_read_b128 v[222:225], v133 offset:2048
	ds_read_b128 v[226:229], v133 offset:3072
	global_load_lds_dwordx4 v[150:151], off
	s_mov_b32 m0, s64
	v_lshl_add_u64 v[150:151], v[182:183], 0, s[10:11]
	global_load_lds_dwordx4 v[150:151], off
	s_barrier
	s_waitcnt lgkmcnt(0)
	s_setprio 1
	v_mfma_f32_16x16x32_bf16 v[124:127], v[210:213], v[166:169], v[124:127]
	v_mfma_f32_16x16x32_bf16 v[120:123], v[222:225], v[166:169], v[120:123]
	v_mfma_f32_16x16x32_bf16 v[100:103], v[210:213], v[174:177], v[100:103]
	v_mfma_f32_16x16x32_bf16 v[96:99], v[222:225], v[174:177], v[96:99]
	v_mfma_f32_16x16x32_bf16 v[84:87], v[210:213], v[194:197], v[84:87]
	v_mfma_f32_16x16x32_bf16 v[80:83], v[222:225], v[194:197], v[80:83]
	v_mfma_f32_16x16x32_bf16 v[68:71], v[210:213], v[202:205], v[68:71]
	v_mfma_f32_16x16x32_bf16 v[64:67], v[222:225], v[202:205], v[64:67]
	v_mfma_f32_16x16x32_bf16 v[124:127], v[214:217], v[170:173], v[124:127]
	v_mfma_f32_16x16x32_bf16 v[120:123], v[226:229], v[170:173], v[120:123]
	v_mfma_f32_16x16x32_bf16 v[100:103], v[214:217], v[178:181], v[100:103]
	v_mfma_f32_16x16x32_bf16 v[96:99], v[226:229], v[178:181], v[96:99]
	v_mfma_f32_16x16x32_bf16 v[84:87], v[214:217], v[198:201], v[84:87]
	v_mfma_f32_16x16x32_bf16 v[80:83], v[226:229], v[198:201], v[80:83]
	v_mfma_f32_16x16x32_bf16 v[68:71], v[214:217], v[206:209], v[68:71]
	v_mfma_f32_16x16x32_bf16 v[64:67], v[226:229], v[206:209], v[64:67]
	s_setprio 0
	s_mov_b32 m0, s51
	v_lshl_add_u64 v[150:151], v[218:219], 0, s[10:11]
	s_barrier
	ds_read_b128 v[166:169], v191 offset:49152
	ds_read_b128 v[170:173], v191 offset:50176
	ds_read_b128 v[174:177], v191 offset:51200
	ds_read_b128 v[178:181], v191 offset:52224
	ds_read_b128 v[194:197], v191 offset:53248
	ds_read_b128 v[198:201], v191 offset:54272
	ds_read_b128 v[202:205], v191 offset:55296
	ds_read_b128 v[206:209], v191 offset:56320
	global_load_lds_dwordx4 v[150:151], off
	s_mov_b32 m0, s52
	v_lshl_add_u64 v[150:151], v[230:231], 0, s[10:11]
	global_load_lds_dwordx4 v[150:151], off
	s_barrier
	s_waitcnt lgkmcnt(0)
	s_setprio 1
	v_mfma_f32_16x16x32_bf16 v[52:55], v[134:137], v[166:169], v[52:55]
	v_mfma_f32_16x16x32_bf16 v[48:51], v[142:145], v[166:169], v[48:51]
	v_mfma_f32_16x16x32_bf16 v[44:47], v[134:137], v[174:177], v[44:47]
	v_mfma_f32_16x16x32_bf16 v[36:39], v[142:145], v[174:177], v[36:39]
	v_mfma_f32_16x16x32_bf16 v[28:31], v[134:137], v[194:197], v[28:31]
	v_mfma_f32_16x16x32_bf16 v[20:23], v[142:145], v[194:197], v[20:23]
	v_mfma_f32_16x16x32_bf16 v[12:15], v[134:137], v[202:205], v[12:15]
	v_mfma_f32_16x16x32_bf16 v[4:7], v[142:145], v[202:205], v[4:7]
	v_mfma_f32_16x16x32_bf16 v[52:55], v[138:141], v[170:173], v[52:55]
	v_mfma_f32_16x16x32_bf16 v[48:51], v[146:149], v[170:173], v[48:51]
	v_mfma_f32_16x16x32_bf16 v[44:47], v[138:141], v[178:181], v[44:47]
	v_mfma_f32_16x16x32_bf16 v[36:39], v[146:149], v[178:181], v[36:39]
	v_mfma_f32_16x16x32_bf16 v[28:31], v[138:141], v[198:201], v[28:31]
	v_mfma_f32_16x16x32_bf16 v[20:23], v[146:149], v[198:201], v[20:23]
	v_mfma_f32_16x16x32_bf16 v[12:15], v[138:141], v[206:209], v[12:15]
	v_mfma_f32_16x16x32_bf16 v[4:7], v[146:149], v[206:209], v[4:7]
	s_setprio 0
	s_barrier
	s_add_u32 s36, s36, 0xb0080
	s_addc_u32 s37, s37, 0
	s_mov_b32 m0, s65
	v_lshl_add_u64 v[134:135], s[36:37], 0, v[156:157]
	global_load_lds_dwordx4 v[134:135], off
	s_mov_b32 m0, s66
	v_lshl_add_u64 v[134:135], s[36:37], 0, v[160:161]
	global_load_lds_dwordx4 v[134:135], off
	s_waitcnt vmcnt(6)
	s_barrier
; __device__ __forceinline__ unsigned pk2(float lo, float hi) { unsigned r; asm volatile("v_cvt_pk_bf16_f32 %0, %1, %2" : "=v"(r) : "v"(lo), "v"(hi)); return r; }
; __device__ __forceinline__ unsigned pk2(float lo, float hi) { return f2bf(lo) | (f2bf(hi) << 16); }
;     __device__ __forceinline__ void epi(const f32x4 (&acc)[2][2][4][2], const Unit& u, int wr, int wc, int fr, int fq) const {
;         if ((PROBE & 64) && coef == 0.f) { dry_epi(acc, pool, rowss); return; }
;         ConvHost<3> ch; ch.begin(cj, u.g, 22, wr * 4 + wc, fq * 16 + fr);
;         const int row0 = u.pm * 256 + wr * 64 + fr, col0 = u.pn * 256 + wc * 32 + 8 * fq;
; #pragma unroll
;         for (int ai = 0; ai < 2; ++ai) {
;             u32x4 xo[4][2];
; #pragma unroll
;             for (int m = 0; m < 4; ++m)
; #pragma unroll
;                 for (int bj = 0; bj < 2; ++bj) xo[m][bj] = *(const u32x4*)(xb + (size_t)(row0 + ai * 128 + m * 16) * D + col0 + bj * 128);
; #pragma unroll
;             for (int m = 0; m < 4; ++m) {
;                 const int row = row0 + ai * 128 + m * 16; const size_t off = (size_t)row * D + col0; float ss = 0.f;
; #pragma unroll
;                 for (int bj = 0; bj < 2; ++bj) {
;                     const u32x4 o = xo[m][bj]; const f32x4 a0v = acc[ai][bj][m][0], a1v = acc[ai][bj][m][1];
;                     const float v0 = bf_lo(o.x) + coef * a0v[0], v1 = bf_hi(o.x) + coef * a0v[1], v2 = bf_lo(o.y) + coef * a0v[2], v3 = bf_hi(o.y) + coef * a0v[3];
;                     const float v4 = bf_lo(o.z) + coef * a1v[0], v5 = bf_hi(o.z) + coef * a1v[1], v6 = bf_lo(o.w) + coef * a1v[2], v7 = bf_hi(o.w) + coef * a1v[3];
;                     u32x4 w; w.x = pk2(v0, v1); w.y = pk2(v2, v3); w.z = pk2(v4, v5); w.w = pk2(v6, v7);
;                     *(u32x4*)(xb + off + bj * 128) = w;
;                     ss += ((v0 * v0 + v1 * v1) + (v2 * v2 + v3 * v3)) + ((v4 * v4 + v5 * v5) + (v6 * v6 + v7 * v7));
;                 }
;                 ss += __shfl_xor(ss, 16); ss += __shfl_xor(ss, 32);
;                 if (fq == 0) rowss[(size_t)row * 32 + u.pn * 4 + wc] = ss;
;             }
	s_setprio 1
	v_mfma_f32_16x16x32_bf16 v[60:63], v[210:213], v[166:169], v[60:63]
	v_mfma_f32_16x16x32_bf16 v[56:59], v[222:225], v[166:169], v[56:59]
	v_mfma_f32_16x16x32_bf16 v[40:43], v[210:213], v[174:177], v[40:43]
	v_mfma_f32_16x16x32_bf16 v[32:35], v[222:225], v[174:177], v[32:35]
	v_mfma_f32_16x16x32_bf16 v[24:27], v[210:213], v[194:197], v[24:27]
	v_mfma_f32_16x16x32_bf16 v[16:19], v[222:225], v[194:197], v[16:19]
	v_mfma_f32_16x16x32_bf16 v[8:11], v[210:213], v[202:205], v[8:11]
	v_mfma_f32_16x16x32_bf16 v[0:3], v[222:225], v[202:205], v[0:3]
	v_mfma_f32_16x16x32_bf16 v[60:63], v[214:217], v[170:173], v[60:63]
	v_mfma_f32_16x16x32_bf16 v[56:59], v[226:229], v[170:173], v[56:59]
	v_mfma_f32_16x16x32_bf16 v[40:43], v[214:217], v[178:181], v[40:43]
	v_mfma_f32_16x16x32_bf16 v[32:35], v[226:229], v[178:181], v[32:35]
	v_mfma_f32_16x16x32_bf16 v[24:27], v[214:217], v[198:201], v[24:27]
	v_mfma_f32_16x16x32_bf16 v[16:19], v[226:229], v[198:201], v[16:19]
	v_mfma_f32_16x16x32_bf16 v[8:11], v[214:217], v[206:209], v[8:11]
	v_mfma_f32_16x16x32_bf16 v[0:3], v[226:229], v[206:209], v[0:3]
	s_setprio 0
	s_add_i32 s67, s67, 2
	s_add_u32 s34, s34, 0x100
	s_addc_u32 s35, s35, 0
	s_cmp_gt_u32 s67, 41
	s_barrier
	s_cbranch_scc0 .LBB0_357
	v_lshl_or_b32 v166, s40, 8, v189
	v_lshl_add_u32 v170, s61, 8, v153
	v_ashrrev_i32_e32 v167, 31, v166
	v_lshlrev_b64 v[202:203], 1, v[166:167]
	v_ashrrev_i32_e32 v171, 31, v170
	v_lshl_add_u64 v[168:169], s[20:21], 0, v[202:203]
	v_lshlrev_b64 v[204:205], 11, v[170:171]
	v_lshl_add_u64 v[128:129], v[168:169], 0, v[204:205]
	global_load_dwordx4 v[194:197], v[128:129], off
	global_load_dwordx4 v[198:201], v[128:129], off offset:256
	v_or_b32_e32 v180, 16, v170
	v_or_b32_e32 v176, 32, v170
	v_or_b32_e32 v172, 48, v170
	v_ashrrev_i32_e32 v181, 31, v180
	v_ashrrev_i32_e32 v177, 31, v176
	v_ashrrev_i32_e32 v173, 31, v172
	v_lshlrev_b64 v[182:183], 11, v[180:181]
	v_lshlrev_b64 v[178:179], 11, v[176:177]
	v_lshlrev_b64 v[174:175], 11, v[172:173]
	v_lshl_add_u64 v[128:129], v[168:169], 0, v[182:183]
	v_lshl_add_u64 v[130:131], v[168:169], 0, v[178:179]
	v_lshl_add_u64 v[206:207], v[168:169], 0, v[174:175]
	global_load_dwordx4 v[148:151], v[128:129], off
	global_load_dwordx4 v[144:147], v[128:129], off offset:256
	global_load_dwordx4 v[140:143], v[130:131], off
	global_load_dwordx4 v[136:139], v[130:131], off offset:256
	global_load_dwordx4 v[132:135], v[206:207], off
	s_nop 0
	global_load_dwordx4 v[128:131], v[206:207], off offset:256
	v_and_b32_e32 v206, 64, v193
	v_xor_b32_e32 v208, 16, v193
	v_add_u32_e32 v206, 64, v206
	v_cmp_lt_i32_e32 vcc, v208, v206
	s_waitcnt vmcnt(0)
	v_lshlrev_b32_e32 v209, 16, v195
	v_cndmask_b32_e32 v207, v193, v208, vcc
	v_lshlrev_b32_e32 v208, 16, v194
	v_and_b32_e32 v194, 0xffff0000, v194
	v_and_b32_e32 v195, 0xffff0000, v195
	v_lshlrev_b32_e32 v210, 16, v196
	v_and_b32_e32 v196, 0xffff0000, v196
	v_lshlrev_b32_e32 v211, 16, v197
	v_and_b32_e32 v197, 0xffff0000, v197
	v_lshlrev_b32_e32 v212, 16, v198
	v_and_b32_e32 v198, 0xffff0000, v198
	v_lshlrev_b32_e32 v213, 16, v199
	v_and_b32_e32 v199, 0xffff0000, v199
	v_lshlrev_b32_e32 v214, 16, v200
	v_and_b32_e32 v200, 0xffff0000, v200
	v_lshlrev_b32_e32 v215, 16, v201
	v_and_b32_e32 v201, 0xffff0000, v201
	v_fmac_f32_e32 v194, 0.5, v117
	v_fmac_f32_e32 v195, 0.5, v119
	v_fmac_f32_e32 v196, 0.5, v113
	v_fmac_f32_e32 v197, 0.5, v115
	v_fmac_f32_e32 v198, 0.5, v125
	v_fmac_f32_e32 v199, 0.5, v127
	v_fmac_f32_e32 v200, 0.5, v121
	v_fmac_f32_e32 v201, 0.5, v123
	v_fmac_f32_e32 v208, 0.5, v116
	v_fmac_f32_e32 v209, 0.5, v118
	v_fmac_f32_e32 v210, 0.5, v112
	v_fmac_f32_e32 v211, 0.5, v114
	v_fmac_f32_e32 v212, 0.5, v124
	v_fmac_f32_e32 v213, 0.5, v126
	v_fmac_f32_e32 v214, 0.5, v120
	v_fmac_f32_e32 v215, 0.5, v122
	v_mul_f32_e32 v112, v194, v194
	v_mul_f32_e32 v113, v195, v195
	v_mul_f32_e32 v118, v196, v196
	v_mul_f32_e32 v119, v197, v197
	v_mul_f32_e32 v120, v198, v198
	v_mul_f32_e32 v121, v199, v199
	v_mul_f32_e32 v122, v200, v200
	v_mul_f32_e32 v123, v201, v201
	v_fmac_f32_e32 v112, v208, v208
	v_fmac_f32_e32 v113, v209, v209
	v_fmac_f32_e32 v118, v210, v210
	v_fmac_f32_e32 v119, v211, v211
	v_fmac_f32_e32 v120, v212, v212
	v_fmac_f32_e32 v121, v213, v213
	v_fmac_f32_e32 v122, v214, v214
	v_fmac_f32_e32 v123, v215, v215
	v_add_f32_e32 v112, v112, v113
	v_add_f32_e32 v113, v118, v119
	v_add_f32_e32 v118, v120, v121
	v_add_f32_e32 v119, v122, v123
	v_add_f32_e32 v112, v112, v113
	v_add_f32_e32 v113, v118, v119
	v_add_f32_e32 v113, v112, v113
	v_lshlrev_b32_e32 v112, 2, v207
	ds_bpermute_b32 v122, v112, v113
	v_lshl_add_u64 v[118:119], s[20:21], 0, v[204:205]
	v_cvt_pk_bf16_f32 v114, v208, v194
	v_lshl_add_u64 v[120:121], v[118:119], 0, v[202:203]
	v_cvt_pk_bf16_f32 v115, v209, v195
	v_cvt_pk_bf16_f32 v116, v210, v196
	v_cvt_pk_bf16_f32 v117, v211, v197
	global_store_dwordx4 v[120:121], v[114:117], off
	s_waitcnt lgkmcnt(0)
	s_nop 0
	v_add_f32_e32 v114, v113, v122
	v_xor_b32_e32 v113, 32, v193
	v_cmp_lt_i32_e32 vcc, v113, v206
	v_cvt_pk_bf16_f32 v116, v212, v198
	v_cvt_pk_bf16_f32 v117, v213, v199
	v_cvt_pk_bf16_f32 v118, v214, v200
	v_cvt_pk_bf16_f32 v119, v215, v201
	global_store_dwordx4 v[120:121], v[116:119], off offset:256
	s_nop 0
	v_cndmask_b32_e32 v113, v193, v113, vcc
	v_lshlrev_b32_e32 v113, 2, v113
	ds_bpermute_b32 v115, v113, v114
	s_and_saveexec_b64 s[28:29], s[6:7]
	s_cbranch_execz .LBB0_360
	s_waitcnt lgkmcnt(0)
	v_add_f32_e32 v116, v114, v115
	s_lshl_b32 s30, s40, 2
	v_lshlrev_b64 v[114:115], 7, v[170:171]
	s_ashr_i32 s31, s30, 31
	v_lshl_add_u64 v[114:115], s[2:3], 0, v[114:115]
	v_lshl_add_u64 v[114:115], s[30:31], 2, v[114:115]
	s_lshl_b32 s0, s50, 2
	v_lshl_add_u64 v[114:115], v[114:115], 0, s[0:1]
	global_store_dword v[114:115], v116, off

.LBB0_579:
	ds_read_b128 v[0:3], v144
	ds_read_b128 v[4:7], v144 offset:1024
	ds_read_b128 v[8:11], v144 offset:2048
	ds_read_b128 v[12:15], v144 offset:3072
	s_lshl_b64 s[44:45], s[44:45], 19
	s_add_u32 s1, s49, s44
	s_addc_u32 s12, s50, s45
	s_add_u32 s40, s1, s40
	s_addc_u32 s41, s12, s41
	s_add_u32 s44, s4, 0x40080
	s_addc_u32 s45, s5, 0
	s_add_i32 s1, s52, 0xc000
	v_lshl_add_u64 v[48:49], s[44:45], 0, v[130:131]
	s_mov_b32 m0, s1
	s_add_i32 s12, s52, 0xe000
	ds_read_b128 v[16:19], v145
	ds_read_b128 v[20:23], v145 offset:1024
	ds_read_b128 v[24:27], v145 offset:2048
	ds_read_b128 v[28:31], v145 offset:3072
	ds_read_b128 v[32:35], v145 offset:4096
	ds_read_b128 v[36:39], v145 offset:5120
	ds_read_b128 v[40:43], v145 offset:6144
	ds_read_b128 v[44:47], v145 offset:7168
	global_load_lds_dwordx4 v[48:49], off
	s_mov_b32 m0, s12
	v_lshl_add_u64 v[48:49], s[44:45], 0, v[128:129]
	global_load_lds_dwordx4 v[48:49], off
	s_waitcnt lgkmcnt(8)
	s_barrier
	s_waitcnt lgkmcnt(0)
	s_setprio 1
	v_mfma_f32_16x16x32_bf16 v[48:51], v[0:3], v[16:19], 0
	v_mfma_f32_16x16x32_bf16 v[52:55], v[8:11], v[16:19], 0
	v_mfma_f32_16x16x32_bf16 v[56:59], v[0:3], v[24:27], 0
	v_mfma_f32_16x16x32_bf16 v[60:63], v[8:11], v[24:27], 0
	v_mfma_f32_16x16x32_bf16 v[64:67], v[0:3], v[32:35], 0
	v_mfma_f32_16x16x32_bf16 v[68:71], v[8:11], v[32:35], 0
	v_mfma_f32_16x16x32_bf16 v[72:75], v[0:3], v[40:43], 0
	v_mfma_f32_16x16x32_bf16 v[76:79], v[8:11], v[40:43], 0
	v_mfma_f32_16x16x32_bf16 v[48:51], v[4:7], v[20:23], v[48:51]
	v_mfma_f32_16x16x32_bf16 v[52:55], v[12:15], v[20:23], v[52:55]
	v_mfma_f32_16x16x32_bf16 v[56:59], v[4:7], v[28:31], v[56:59]
	v_mfma_f32_16x16x32_bf16 v[60:63], v[12:15], v[28:31], v[60:63]
	v_mfma_f32_16x16x32_bf16 v[64:67], v[4:7], v[36:39], v[64:67]
	v_mfma_f32_16x16x32_bf16 v[68:71], v[12:15], v[36:39], v[68:71]
	v_mfma_f32_16x16x32_bf16 v[72:75], v[4:7], v[44:47], v[72:75]
	v_mfma_f32_16x16x32_bf16 v[76:79], v[12:15], v[44:47], v[76:79]
	s_setprio 0
	s_barrier
	v_lshl_add_u64 v[246:247], s[6:7], 0, v[130:131]
	s_add_i32 s35, s64, s51
	v_lshl_add_u64 v[96:97], v[246:247], 0, s[14:15]
	s_mov_b32 m0, s35
	v_lshl_add_u64 v[248:249], s[6:7], 0, v[128:129]
	s_add_i32 s73, s35, 0x2000
	ds_read_b128 v[80:83], v146
	ds_read_b128 v[84:87], v146 offset:1024
	ds_read_b128 v[88:91], v146 offset:2048
	ds_read_b128 v[92:95], v146 offset:3072
	global_load_lds_dwordx4 v[96:97], off
	s_mov_b32 m0, s73
	v_lshl_add_u64 v[96:97], v[248:249], 0, s[14:15]
	global_load_lds_dwordx4 v[96:97], off
	s_barrier
	s_waitcnt lgkmcnt(0)
	s_setprio 1
	v_mfma_f32_16x16x32_bf16 v[96:99], v[80:83], v[16:19], 0
	v_mfma_f32_16x16x32_bf16 v[16:19], v[88:91], v[16:19], 0
	v_mfma_f32_16x16x32_bf16 v[100:103], v[80:83], v[24:27], 0
	v_mfma_f32_16x16x32_bf16 v[24:27], v[88:91], v[24:27], 0
	v_mfma_f32_16x16x32_bf16 v[104:107], v[80:83], v[32:35], 0
	v_mfma_f32_16x16x32_bf16 v[32:35], v[88:91], v[32:35], 0
	v_mfma_f32_16x16x32_bf16 v[108:111], v[80:83], v[40:43], 0
	v_mfma_f32_16x16x32_bf16 v[40:43], v[88:91], v[40:43], 0
	v_mfma_f32_16x16x32_bf16 v[96:99], v[84:87], v[20:23], v[96:99]
	v_mfma_f32_16x16x32_bf16 v[112:115], v[92:95], v[20:23], v[16:19]
	v_mfma_f32_16x16x32_bf16 v[100:103], v[84:87], v[28:31], v[100:103]
	v_mfma_f32_16x16x32_bf16 v[116:119], v[92:95], v[28:31], v[24:27]
	v_mfma_f32_16x16x32_bf16 v[104:107], v[84:87], v[36:39], v[104:107]
	v_mfma_f32_16x16x32_bf16 v[32:35], v[92:95], v[36:39], v[32:35]
	v_mfma_f32_16x16x32_bf16 v[36:39], v[84:87], v[44:47], v[108:111]
	v_mfma_f32_16x16x32_bf16 v[40:43], v[92:95], v[44:47], v[40:43]
	s_setprio 0
	v_lshl_add_u64 v[250:251], s[4:5], 0, v[130:131]
	s_mov_b32 m0, s52
	v_lshl_add_u64 v[138:139], v[250:251], 0, s[14:15]
	v_lshl_add_u64 v[252:253], s[4:5], 0, v[128:129]
	s_barrier
	ds_read_b128 v[16:19], v145 offset:16384
	ds_read_b128 v[20:23], v145 offset:17408
	ds_read_b128 v[24:27], v145 offset:18432
	ds_read_b128 v[28:31], v145 offset:19456
	ds_read_b128 v[44:47], v145 offset:20480
	ds_read_b128 v[108:111], v145 offset:21504
	ds_read_b128 v[120:123], v145 offset:22528
	ds_read_b128 v[124:127], v145 offset:23552
	global_load_lds_dwordx4 v[138:139], off
	s_mov_b32 m0, s55
	v_lshl_add_u64 v[138:139], v[252:253], 0, s[14:15]
	global_load_lds_dwordx4 v[138:139], off
	s_barrier
	s_waitcnt lgkmcnt(0)
	s_setprio 1
	v_mfma_f32_16x16x32_bf16 v[138:141], v[0:3], v[16:19], 0
	v_mfma_f32_16x16x32_bf16 v[148:151], v[8:11], v[16:19], 0
	v_mfma_f32_16x16x32_bf16 v[152:155], v[0:3], v[24:27], 0
	v_mfma_f32_16x16x32_bf16 v[156:159], v[8:11], v[24:27], 0
	v_mfma_f32_16x16x32_bf16 v[160:163], v[0:3], v[44:47], 0
	v_mfma_f32_16x16x32_bf16 v[164:167], v[8:11], v[44:47], 0
	v_mfma_f32_16x16x32_bf16 v[0:3], v[0:3], v[120:123], 0
	v_mfma_f32_16x16x32_bf16 v[8:11], v[8:11], v[120:123], 0
	v_mfma_f32_16x16x32_bf16 v[138:141], v[4:7], v[20:23], v[138:141]
	v_mfma_f32_16x16x32_bf16 v[168:171], v[12:15], v[20:23], v[148:151]
	v_mfma_f32_16x16x32_bf16 v[150:153], v[4:7], v[28:31], v[152:155]
	v_mfma_f32_16x16x32_bf16 v[154:157], v[12:15], v[28:31], v[156:159]
	v_mfma_f32_16x16x32_bf16 v[158:161], v[4:7], v[108:111], v[160:163]
	v_mfma_f32_16x16x32_bf16 v[162:165], v[12:15], v[108:111], v[164:167]
	v_mfma_f32_16x16x32_bf16 v[172:175], v[4:7], v[124:127], v[0:3]
	v_mfma_f32_16x16x32_bf16 v[176:179], v[12:15], v[124:127], v[8:11]
	s_setprio 0
	s_barrier
	s_add_u32 s44, s6, 0x40100
	s_addc_u32 s45, s7, 0
	s_add_i32 s74, s66, s51
	v_lshl_add_u64 v[0:1], s[44:45], 0, v[130:131]
	s_mov_b32 m0, s74
	s_add_i32 s75, s74, 0x2000
	global_load_lds_dwordx4 v[0:1], off
	s_mov_b32 m0, s75
	v_lshl_add_u64 v[0:1], s[44:45], 0, v[128:129]
	global_load_lds_dwordx4 v[0:1], off
	s_waitcnt vmcnt(6)
	s_barrier
	s_setprio 1
	v_mfma_f32_16x16x32_bf16 v[0:3], v[80:83], v[16:19], 0
	v_mfma_f32_16x16x32_bf16 v[4:7], v[88:91], v[16:19], 0
	v_mfma_f32_16x16x32_bf16 v[8:11], v[80:83], v[24:27], 0
	v_mfma_f32_16x16x32_bf16 v[12:15], v[88:91], v[24:27], 0
	v_mfma_f32_16x16x32_bf16 v[16:19], v[80:83], v[44:47], 0
	v_mfma_f32_16x16x32_bf16 v[24:27], v[88:91], v[44:47], 0
	v_mfma_f32_16x16x32_bf16 v[44:47], v[80:83], v[120:123], 0
	v_mfma_f32_16x16x32_bf16 v[80:83], v[88:91], v[120:123], 0
	v_mfma_f32_16x16x32_bf16 v[120:123], v[84:87], v[20:23], v[0:3]
	v_mfma_f32_16x16x32_bf16 v[192:195], v[84:87], v[108:111], v[16:19]
	v_mfma_f32_16x16x32_bf16 v[108:111], v[92:95], v[108:111], v[24:27]
	v_mfma_f32_16x16x32_bf16 v[196:199], v[84:87], v[124:127], v[44:47]
	v_mfma_f32_16x16x32_bf16 v[124:127], v[92:95], v[124:127], v[80:83]
	v_mfma_f32_16x16x32_bf16 v[180:183], v[92:95], v[20:23], v[4:7]
	v_mfma_f32_16x16x32_bf16 v[184:187], v[84:87], v[28:31], v[8:11]
	v_mfma_f32_16x16x32_bf16 v[188:191], v[92:95], v[28:31], v[12:15]
	s_setprio 0
	s_add_i32 s76, 0, 0x18000
	v_add_u32_e32 v147, s76, v143
	s_barrier
	ds_read_b128 v[80:83], v147
	ds_read_b128 v[200:203], v147 offset:1024
	ds_read_b128 v[84:87], v147 offset:2048
	ds_read_b128 v[204:207], v147 offset:3072
	s_add_u32 s44, s4, 0x40100
	s_addc_u32 s45, s5, 0
	s_mov_b32 m0, s56
	v_lshl_add_u64 v[0:1], s[44:45], 0, v[130:131]
	ds_read_b128 v[44:47], v145 offset:32768
	ds_read_b128 v[88:91], v145 offset:33792
	ds_read_b128 v[92:95], v145 offset:34816
	ds_read_b128 v[208:211], v145 offset:35840
	ds_read_b128 v[212:215], v145 offset:36864
	ds_read_b128 v[216:219], v145 offset:37888
	ds_read_b128 v[222:225], v145 offset:38912
	ds_read_b128 v[226:229], v145 offset:39936
	global_load_lds_dwordx4 v[0:1], off
	s_mov_b32 m0, s57
	v_lshl_add_u64 v[0:1], s[44:45], 0, v[128:129]
	global_load_lds_dwordx4 v[0:1], off
	s_waitcnt lgkmcnt(8)
	s_barrier
	s_waitcnt lgkmcnt(0)
	s_setprio 1
	v_mfma_f32_16x16x32_bf16 v[0:3], v[80:83], v[44:47], v[48:51]
	v_mfma_f32_16x16x32_bf16 v[4:7], v[84:87], v[44:47], v[52:55]
	v_mfma_f32_16x16x32_bf16 v[8:11], v[80:83], v[92:95], v[56:59]
	v_mfma_f32_16x16x32_bf16 v[12:15], v[84:87], v[92:95], v[60:63]
	v_mfma_f32_16x16x32_bf16 v[48:51], v[80:83], v[212:215], v[64:67]
	v_mfma_f32_16x16x32_bf16 v[52:55], v[84:87], v[212:215], v[68:71]
	v_mfma_f32_16x16x32_bf16 v[56:59], v[80:83], v[222:225], v[72:75]
	v_mfma_f32_16x16x32_bf16 v[60:63], v[84:87], v[222:225], v[76:79]
	v_mfma_f32_16x16x32_bf16 v[28:31], v[200:203], v[88:91], v[0:3]
	v_mfma_f32_16x16x32_bf16 v[24:27], v[204:207], v[88:91], v[4:7]
	v_mfma_f32_16x16x32_bf16 v[20:23], v[200:203], v[208:211], v[8:11]
	v_mfma_f32_16x16x32_bf16 v[16:19], v[204:207], v[208:211], v[12:15]
	v_mfma_f32_16x16x32_bf16 v[12:15], v[200:203], v[216:219], v[48:51]
	v_mfma_f32_16x16x32_bf16 v[8:11], v[204:207], v[216:219], v[52:55]
	v_mfma_f32_16x16x32_bf16 v[4:7], v[200:203], v[226:229], v[56:59]
	v_mfma_f32_16x16x32_bf16 v[0:3], v[204:207], v[226:229], v[60:63]
	s_setprio 0
	s_barrier
	s_add_i32 s78, 0, 0x1c000
	s_add_i32 s76, s76, s51
	v_add_u32_e32 v148, s78, v143
	v_lshl_add_u64 v[48:49], v[246:247], 0, s[16:17]
	s_mov_b32 m0, s76
	s_add_i32 s77, s76, 0x2000
	ds_read_b128 v[230:233], v148
	ds_read_b128 v[234:237], v148 offset:1024
	ds_read_b128 v[238:241], v148 offset:2048
	ds_read_b128 v[242:245], v148 offset:3072
	global_load_lds_dwordx4 v[48:49], off
	s_mov_b32 m0, s77
	v_lshl_add_u64 v[48:49], v[248:249], 0, s[16:17]
	global_load_lds_dwordx4 v[48:49], off
	s_barrier
	s_waitcnt lgkmcnt(0)
	s_setprio 1
	v_mfma_f32_16x16x32_bf16 v[48:51], v[230:233], v[44:47], v[96:99]
	v_mfma_f32_16x16x32_bf16 v[44:47], v[238:241], v[44:47], v[112:115]
	v_mfma_f32_16x16x32_bf16 v[52:55], v[230:233], v[92:95], v[100:103]
	v_mfma_f32_16x16x32_bf16 v[56:59], v[238:241], v[92:95], v[116:119]
	v_mfma_f32_16x16x32_bf16 v[60:63], v[230:233], v[212:215], v[104:107]
	v_mfma_f32_16x16x32_bf16 v[32:35], v[238:241], v[212:215], v[32:35]
	v_mfma_f32_16x16x32_bf16 v[36:39], v[230:233], v[222:225], v[36:39]
	v_mfma_f32_16x16x32_bf16 v[40:43], v[238:241], v[222:225], v[40:43]
	v_mfma_f32_16x16x32_bf16 v[92:95], v[234:237], v[88:91], v[48:51]
	v_mfma_f32_16x16x32_bf16 v[88:91], v[242:245], v[88:91], v[44:47]
	v_mfma_f32_16x16x32_bf16 v[76:79], v[234:237], v[208:211], v[52:55]
	v_mfma_f32_16x16x32_bf16 v[72:75], v[242:245], v[208:211], v[56:59]
	v_mfma_f32_16x16x32_bf16 v[60:63], v[234:237], v[216:219], v[60:63]
	v_mfma_f32_16x16x32_bf16 v[56:59], v[242:245], v[216:219], v[32:35]
	v_mfma_f32_16x16x32_bf16 v[44:47], v[234:237], v[226:229], v[36:39]
	v_mfma_f32_16x16x32_bf16 v[40:43], v[242:245], v[226:229], v[40:43]
	s_setprio 0
	s_mov_b32 m0, s61
	v_lshl_add_u64 v[32:33], v[250:251], 0, s[16:17]
	s_barrier
	ds_read_b128 v[96:99], v145 offset:49152
	ds_read_b128 v[100:103], v145 offset:50176
	ds_read_b128 v[104:107], v145 offset:51200
	ds_read_b128 v[112:115], v145 offset:52224
	ds_read_b128 v[116:119], v145 offset:53248
	ds_read_b128 v[208:211], v145 offset:54272
	ds_read_b128 v[212:215], v145 offset:55296
	ds_read_b128 v[216:219], v145 offset:56320
	global_load_lds_dwordx4 v[32:33], off
	s_mov_b32 m0, s62
	v_lshl_add_u64 v[32:33], v[252:253], 0, s[16:17]
	global_load_lds_dwordx4 v[32:33], off
	s_barrier
;     ...
;         G_PAIR(0, 1);
; #pragma unroll 1
;         for (int t = 2; t < nt; t += 2) G_PAIR(t, 0);
	s_waitcnt lgkmcnt(0)
	s_setprio 1
	v_mfma_f32_16x16x32_bf16 v[32:35], v[80:83], v[96:99], v[138:141]
	v_mfma_f32_16x16x32_bf16 v[36:39], v[84:87], v[96:99], v[168:171]
	v_mfma_f32_16x16x32_bf16 v[48:51], v[80:83], v[104:107], v[150:153]
	v_mfma_f32_16x16x32_bf16 v[52:55], v[84:87], v[104:107], v[154:157]
	v_mfma_f32_16x16x32_bf16 v[138:141], v[80:83], v[116:119], v[158:161]
	v_mfma_f32_16x16x32_bf16 v[150:153], v[84:87], v[116:119], v[162:165]
	v_mfma_f32_16x16x32_bf16 v[154:157], v[80:83], v[212:215], v[172:175]
	v_mfma_f32_16x16x32_bf16 v[158:161], v[84:87], v[212:215], v[176:179]
	v_mfma_f32_16x16x32_bf16 v[84:87], v[200:203], v[100:103], v[32:35]
	v_mfma_f32_16x16x32_bf16 v[80:83], v[204:207], v[100:103], v[36:39]
	v_mfma_f32_16x16x32_bf16 v[68:71], v[200:203], v[112:115], v[48:51]
	v_mfma_f32_16x16x32_bf16 v[64:67], v[204:207], v[112:115], v[52:55]
	v_mfma_f32_16x16x32_bf16 v[52:55], v[200:203], v[208:211], v[138:141]
	v_mfma_f32_16x16x32_bf16 v[48:51], v[204:207], v[208:211], v[150:153]
	v_mfma_f32_16x16x32_bf16 v[36:39], v[200:203], v[216:219], v[154:157]
	v_mfma_f32_16x16x32_bf16 v[32:35], v[204:207], v[216:219], v[158:161]
	s_setprio 0
	s_barrier
	s_add_u32 s44, s6, 0x40180
	s_addc_u32 s45, s7, 0
	s_add_i32 s78, s78, s51
	v_lshl_add_u64 v[138:139], s[44:45], 0, v[130:131]
	s_mov_b32 m0, s78
	s_add_i32 s79, s78, 0x2000
	global_load_lds_dwordx4 v[138:139], off
	v_lshl_add_u64 v[138:139], s[44:45], 0, v[128:129]
	s_mov_b32 m0, s79
	s_mov_b64 s[44:45], 0x40180
	global_load_lds_dwordx4 v[138:139], off
	s_waitcnt vmcnt(6)
	s_barrier
	s_setprio 1
	v_mfma_f32_16x16x32_bf16 v[120:123], v[230:233], v[96:99], v[120:123]
	v_mfma_f32_16x16x32_bf16 v[96:99], v[238:241], v[96:99], v[180:183]
	v_mfma_f32_16x16x32_bf16 v[138:141], v[230:233], v[104:107], v[184:187]
	v_mfma_f32_16x16x32_bf16 v[104:107], v[238:241], v[104:107], v[188:191]
	v_mfma_f32_16x16x32_bf16 v[150:153], v[230:233], v[116:119], v[192:195]
	v_mfma_f32_16x16x32_bf16 v[154:157], v[238:241], v[116:119], v[108:111]
	v_mfma_f32_16x16x32_bf16 v[158:161], v[230:233], v[212:215], v[196:199]
	v_mfma_f32_16x16x32_bf16 v[162:165], v[238:241], v[212:215], v[124:127]
	v_mfma_f32_16x16x32_bf16 v[124:127], v[234:237], v[100:103], v[120:123]
	v_mfma_f32_16x16x32_bf16 v[120:123], v[242:245], v[100:103], v[96:99]
	v_mfma_f32_16x16x32_bf16 v[116:119], v[234:237], v[112:115], v[138:141]
	v_mfma_f32_16x16x32_bf16 v[112:115], v[242:245], v[112:115], v[104:107]
	v_mfma_f32_16x16x32_bf16 v[108:111], v[234:237], v[208:211], v[150:153]
	v_mfma_f32_16x16x32_bf16 v[104:107], v[242:245], v[208:211], v[154:157]
	v_mfma_f32_16x16x32_bf16 v[100:103], v[234:237], v[216:219], v[158:161]
	v_mfma_f32_16x16x32_bf16 v[96:99], v[242:245], v[216:219], v[162:165]
	s_setprio 0
	v_lshl_add_u64 v[138:139], s[4:5], 0, v[134:135]
	v_lshl_add_u64 v[140:141], s[4:5], 0, v[136:137]
	s_mov_b32 s80, 0
	s_barrier
.LBB0_580:
	ds_read_b128 v[150:153], v144
	ds_read_b128 v[154:157], v144 offset:1024
	ds_read_b128 v[158:161], v144 offset:2048
	ds_read_b128 v[162:165], v144 offset:3072
	s_mov_b32 m0, s1
	v_lshl_add_u64 v[198:199], v[138:139], 0, s[44:45]
	ds_read_b128 v[166:169], v145
	ds_read_b128 v[170:173], v145 offset:1024
	ds_read_b128 v[174:177], v145 offset:2048
	ds_read_b128 v[178:181], v145 offset:3072
	ds_read_b128 v[182:185], v145 offset:4096
	ds_read_b128 v[186:189], v145 offset:5120
	ds_read_b128 v[190:193], v145 offset:6144
	ds_read_b128 v[194:197], v145 offset:7168
	global_load_lds_dwordx4 v[198:199], off
	s_mov_b32 m0, s12
	v_lshl_add_u64 v[198:199], v[140:141], 0, s[44:45]
	global_load_lds_dwordx4 v[198:199], off
	s_waitcnt lgkmcnt(8)
	s_barrier
	s_waitcnt lgkmcnt(0)
	s_setprio 1
	v_mfma_f32_16x16x32_bf16 v[28:31], v[150:153], v[166:169], v[28:31]
	s_add_i32 s81, s44, 0xfffc0080
	v_mfma_f32_16x16x32_bf16 v[24:27], v[158:161], v[166:169], v[24:27]
	s_cmp_eq_u32 s80, 4
	v_mfma_f32_16x16x32_bf16 v[20:23], v[150:153], v[174:177], v[20:23]
	s_cselect_b64 s[46:47], -1, 0
	v_mfma_f32_16x16x32_bf16 v[16:19], v[158:161], v[174:177], v[16:19]
	s_and_b64 s[82:83], s[46:47], exec
	v_mfma_f32_16x16x32_bf16 v[12:15], v[150:153], v[182:185], v[12:15]
	s_cselect_b32 s83, s39, s5
	v_mfma_f32_16x16x32_bf16 v[8:11], v[158:161], v[182:185], v[8:11]
	s_cselect_b32 s82, s38, s4
	v_mfma_f32_16x16x32_bf16 v[4:7], v[150:153], v[190:193], v[4:7]
	s_cselect_b32 s81, 0, s81
	v_mfma_f32_16x16x32_bf16 v[0:3], v[158:161], v[190:193], v[0:3]
	s_and_b64 s[46:47], s[42:43], s[46:47]
	v_mfma_f32_16x16x32_bf16 v[28:31], v[154:157], v[170:173], v[28:31]
	s_and_b64 s[46:47], s[46:47], exec
	v_mfma_f32_16x16x32_bf16 v[24:27], v[162:165], v[170:173], v[24:27]
	s_cselect_b32 s47, s41, s7
	v_mfma_f32_16x16x32_bf16 v[20:23], v[154:157], v[178:181], v[20:23]
	s_cselect_b32 s46, s40, s6
	v_mfma_f32_16x16x32_bf16 v[16:19], v[162:165], v[178:181], v[16:19]
	v_mfma_f32_16x16x32_bf16 v[12:15], v[154:157], v[186:189], v[12:15]
	v_mfma_f32_16x16x32_bf16 v[8:11], v[162:165], v[186:189], v[8:11]
	v_mfma_f32_16x16x32_bf16 v[4:7], v[154:157], v[194:197], v[4:7]
	v_mfma_f32_16x16x32_bf16 v[0:3], v[162:165], v[194:197], v[0:3]
	s_setprio 0
	s_barrier
	s_add_u32 s46, s46, s81
	s_addc_u32 s47, s47, 0
	s_mov_b32 m0, s35
	v_lshl_add_u64 v[214:215], s[46:47], 0, v[130:131]
	ds_read_b128 v[198:201], v146
	ds_read_b128 v[202:205], v146 offset:1024
	ds_read_b128 v[206:209], v146 offset:2048
	ds_read_b128 v[210:213], v146 offset:3072
	global_load_lds_dwordx4 v[214:215], off
	s_mov_b32 m0, s73
	v_lshl_add_u64 v[216:217], s[46:47], 0, v[128:129]
	global_load_lds_dwordx4 v[216:217], off
	s_barrier
	s_waitcnt lgkmcnt(0)
	s_setprio 1
	v_mfma_f32_16x16x32_bf16 v[92:95], v[198:201], v[166:169], v[92:95]
	v_mfma_f32_16x16x32_bf16 v[88:91], v[206:209], v[166:169], v[88:91]
	v_mfma_f32_16x16x32_bf16 v[76:79], v[198:201], v[174:177], v[76:79]
	v_mfma_f32_16x16x32_bf16 v[72:75], v[206:209], v[174:177], v[72:75]
	v_mfma_f32_16x16x32_bf16 v[60:63], v[198:201], v[182:185], v[60:63]
	v_mfma_f32_16x16x32_bf16 v[56:59], v[206:209], v[182:185], v[56:59]
	v_mfma_f32_16x16x32_bf16 v[44:47], v[198:201], v[190:193], v[44:47]
	v_mfma_f32_16x16x32_bf16 v[40:43], v[206:209], v[190:193], v[40:43]
	v_mfma_f32_16x16x32_bf16 v[92:95], v[202:205], v[170:173], v[92:95]
	v_mfma_f32_16x16x32_bf16 v[88:91], v[210:213], v[170:173], v[88:91]
	v_mfma_f32_16x16x32_bf16 v[76:79], v[202:205], v[178:181], v[76:79]
	v_mfma_f32_16x16x32_bf16 v[72:75], v[210:213], v[178:181], v[72:75]
	v_mfma_f32_16x16x32_bf16 v[60:63], v[202:205], v[186:189], v[60:63]
	v_mfma_f32_16x16x32_bf16 v[56:59], v[210:213], v[186:189], v[56:59]
	v_mfma_f32_16x16x32_bf16 v[44:47], v[202:205], v[194:197], v[44:47]
	v_mfma_f32_16x16x32_bf16 v[40:43], v[210:213], v[194:197], v[40:43]
	s_setprio 0
	s_add_u32 s82, s82, s81
	s_addc_u32 s83, s83, 0
	s_mov_b32 m0, s52
	v_lshl_add_u64 v[218:219], s[82:83], 0, v[130:131]
	s_barrier
	ds_read_b128 v[166:169], v145 offset:16384
	ds_read_b128 v[170:173], v145 offset:17408
	ds_read_b128 v[174:177], v145 offset:18432
	ds_read_b128 v[178:181], v145 offset:19456
	ds_read_b128 v[182:185], v145 offset:20480
	ds_read_b128 v[186:189], v145 offset:21504
	ds_read_b128 v[190:193], v145 offset:22528
	ds_read_b128 v[194:197], v145 offset:23552
	global_load_lds_dwordx4 v[218:219], off
	s_mov_b32 m0, s55
	v_lshl_add_u64 v[222:223], s[82:83], 0, v[128:129]
	global_load_lds_dwordx4 v[222:223], off
	s_barrier
	s_waitcnt lgkmcnt(0)
	s_setprio 1
	v_mfma_f32_16x16x32_bf16 v[84:87], v[150:153], v[166:169], v[84:87]
	v_mfma_f32_16x16x32_bf16 v[80:83], v[158:161], v[166:169], v[80:83]
	v_mfma_f32_16x16x32_bf16 v[68:71], v[150:153], v[174:177], v[68:71]
	v_mfma_f32_16x16x32_bf16 v[64:67], v[158:161], v[174:177], v[64:67]
	v_mfma_f32_16x16x32_bf16 v[52:55], v[150:153], v[182:185], v[52:55]
	v_mfma_f32_16x16x32_bf16 v[48:51], v[158:161], v[182:185], v[48:51]
	v_mfma_f32_16x16x32_bf16 v[36:39], v[150:153], v[190:193], v[36:39]
	v_mfma_f32_16x16x32_bf16 v[32:35], v[158:161], v[190:193], v[32:35]
	v_mfma_f32_16x16x32_bf16 v[84:87], v[154:157], v[170:173], v[84:87]
	v_mfma_f32_16x16x32_bf16 v[80:83], v[162:165], v[170:173], v[80:83]
	v_mfma_f32_16x16x32_bf16 v[68:71], v[154:157], v[178:181], v[68:71]
	v_mfma_f32_16x16x32_bf16 v[64:67], v[162:165], v[178:181], v[64:67]
	v_mfma_f32_16x16x32_bf16 v[52:55], v[154:157], v[186:189], v[52:55]
	v_mfma_f32_16x16x32_bf16 v[48:51], v[162:165], v[186:189], v[48:51]
	v_mfma_f32_16x16x32_bf16 v[36:39], v[154:157], v[194:197], v[36:39]
	v_mfma_f32_16x16x32_bf16 v[32:35], v[162:165], v[194:197], v[32:35]
	s_setprio 0
	s_barrier
	s_add_u32 s84, s46, 0x40000
	s_addc_u32 s85, s47, 0
	s_mov_b32 m0, s74
	v_lshl_add_u64 v[150:151], s[84:85], 0, v[130:131]
	global_load_lds_dwordx4 v[150:151], off
	s_mov_b32 m0, s75
	v_lshl_add_u64 v[150:151], s[84:85], 0, v[128:129]
	global_load_lds_dwordx4 v[150:151], off
	s_waitcnt vmcnt(6)
	s_barrier
	s_setprio 1
	v_mfma_f32_16x16x32_bf16 v[124:127], v[198:201], v[166:169], v[124:127]
	v_mfma_f32_16x16x32_bf16 v[120:123], v[206:209], v[166:169], v[120:123]
	v_mfma_f32_16x16x32_bf16 v[116:119], v[198:201], v[174:177], v[116:119]
	v_mfma_f32_16x16x32_bf16 v[112:115], v[206:209], v[174:177], v[112:115]
	v_mfma_f32_16x16x32_bf16 v[108:111], v[198:201], v[182:185], v[108:111]
	v_mfma_f32_16x16x32_bf16 v[104:107], v[206:209], v[182:185], v[104:107]
	v_mfma_f32_16x16x32_bf16 v[100:103], v[198:201], v[190:193], v[100:103]
	v_mfma_f32_16x16x32_bf16 v[96:99], v[206:209], v[190:193], v[96:99]
	v_mfma_f32_16x16x32_bf16 v[124:127], v[202:205], v[170:173], v[124:127]
	v_mfma_f32_16x16x32_bf16 v[120:123], v[210:213], v[170:173], v[120:123]
	v_mfma_f32_16x16x32_bf16 v[116:119], v[202:205], v[178:181], v[116:119]
	v_mfma_f32_16x16x32_bf16 v[112:115], v[210:213], v[178:181], v[112:115]
	v_mfma_f32_16x16x32_bf16 v[108:111], v[202:205], v[186:189], v[108:111]
	v_mfma_f32_16x16x32_bf16 v[104:107], v[210:213], v[186:189], v[104:107]
	v_mfma_f32_16x16x32_bf16 v[100:103], v[202:205], v[194:197], v[100:103]
	v_mfma_f32_16x16x32_bf16 v[96:99], v[210:213], v[194:197], v[96:99]
	s_setprio 0
	s_barrier
	ds_read_b128 v[150:153], v147
	ds_read_b128 v[154:157], v147 offset:1024
	ds_read_b128 v[158:161], v147 offset:2048
	ds_read_b128 v[162:165], v147 offset:3072
	s_add_u32 s82, s82, 0x40000
	s_addc_u32 s83, s83, 0
	s_mov_b32 m0, s56
	v_lshl_add_u64 v[198:199], s[82:83], 0, v[130:131]
	ds_read_b128 v[166:169], v145 offset:32768
	ds_read_b128 v[170:173], v145 offset:33792
	ds_read_b128 v[174:177], v145 offset:34816
	ds_read_b128 v[178:181], v145 offset:35840
	ds_read_b128 v[182:185], v145 offset:36864
	ds_read_b128 v[186:189], v145 offset:37888
	ds_read_b128 v[190:193], v145 offset:38912
	ds_read_b128 v[194:197], v145 offset:39936
	global_load_lds_dwordx4 v[198:199], off
	s_mov_b32 m0, s57
	v_lshl_add_u64 v[198:199], s[82:83], 0, v[128:129]
	global_load_lds_dwordx4 v[198:199], off
	s_waitcnt lgkmcnt(8)
	s_barrier
	s_waitcnt lgkmcnt(0)
	s_setprio 1
	v_mfma_f32_16x16x32_bf16 v[28:31], v[150:153], v[166:169], v[28:31]
	v_mfma_f32_16x16x32_bf16 v[24:27], v[158:161], v[166:169], v[24:27]
	v_mfma_f32_16x16x32_bf16 v[20:23], v[150:153], v[174:177], v[20:23]
	v_mfma_f32_16x16x32_bf16 v[16:19], v[158:161], v[174:177], v[16:19]
	v_mfma_f32_16x16x32_bf16 v[12:15], v[150:153], v[182:185], v[12:15]
	v_mfma_f32_16x16x32_bf16 v[8:11], v[158:161], v[182:185], v[8:11]
	v_mfma_f32_16x16x32_bf16 v[4:7], v[150:153], v[190:193], v[4:7]
	v_mfma_f32_16x16x32_bf16 v[0:3], v[158:161], v[190:193], v[0:3]
	v_mfma_f32_16x16x32_bf16 v[28:31], v[154:157], v[170:173], v[28:31]
	v_mfma_f32_16x16x32_bf16 v[24:27], v[162:165], v[170:173], v[24:27]
	v_mfma_f32_16x16x32_bf16 v[20:23], v[154:157], v[178:181], v[20:23]
	v_mfma_f32_16x16x32_bf16 v[16:19], v[162:165], v[178:181], v[16:19]
	v_mfma_f32_16x16x32_bf16 v[12:15], v[154:157], v[186:189], v[12:15]
	v_mfma_f32_16x16x32_bf16 v[8:11], v[162:165], v[186:189], v[8:11]
	v_mfma_f32_16x16x32_bf16 v[4:7], v[154:157], v[194:197], v[4:7]
	v_mfma_f32_16x16x32_bf16 v[0:3], v[162:165], v[194:197], v[0:3]
	s_setprio 0
	s_barrier
	s_mov_b32 m0, s76
	v_lshl_add_u64 v[214:215], v[214:215], 0, s[2:3]
	ds_read_b128 v[198:201], v148
	ds_read_b128 v[202:205], v148 offset:1024
	ds_read_b128 v[206:209], v148 offset:2048
	ds_read_b128 v[210:213], v148 offset:3072
	global_load_lds_dwordx4 v[214:215], off
	s_mov_b32 m0, s77
	v_lshl_add_u64 v[214:215], v[216:217], 0, s[2:3]
	global_load_lds_dwordx4 v[214:215], off
	s_barrier
	s_waitcnt lgkmcnt(0)
	s_setprio 1
	v_mfma_f32_16x16x32_bf16 v[92:95], v[198:201], v[166:169], v[92:95]
	v_mfma_f32_16x16x32_bf16 v[88:91], v[206:209], v[166:169], v[88:91]
	v_mfma_f32_16x16x32_bf16 v[76:79], v[198:201], v[174:177], v[76:79]
	v_mfma_f32_16x16x32_bf16 v[72:75], v[206:209], v[174:177], v[72:75]
	v_mfma_f32_16x16x32_bf16 v[60:63], v[198:201], v[182:185], v[60:63]
	v_mfma_f32_16x16x32_bf16 v[56:59], v[206:209], v[182:185], v[56:59]
	v_mfma_f32_16x16x32_bf16 v[44:47], v[198:201], v[190:193], v[44:47]
	v_mfma_f32_16x16x32_bf16 v[40:43], v[206:209], v[190:193], v[40:43]
	v_mfma_f32_16x16x32_bf16 v[92:95], v[202:205], v[170:173], v[92:95]
	v_mfma_f32_16x16x32_bf16 v[88:91], v[210:213], v[170:173], v[88:91]
	v_mfma_f32_16x16x32_bf16 v[76:79], v[202:205], v[178:181], v[76:79]
	v_mfma_f32_16x16x32_bf16 v[72:75], v[210:213], v[178:181], v[72:75]
	v_mfma_f32_16x16x32_bf16 v[60:63], v[202:205], v[186:189], v[60:63]
	v_mfma_f32_16x16x32_bf16 v[56:59], v[210:213], v[186:189], v[56:59]
	v_mfma_f32_16x16x32_bf16 v[44:47], v[202:205], v[194:197], v[44:47]
	v_mfma_f32_16x16x32_bf16 v[40:43], v[210:213], v[194:197], v[40:43]
	s_setprio 0
	s_mov_b32 m0, s61
	v_lshl_add_u64 v[214:215], v[218:219], 0, s[2:3]
	s_barrier
	ds_read_b128 v[166:169], v145 offset:49152
	ds_read_b128 v[170:173], v145 offset:50176
	ds_read_b128 v[174:177], v145 offset:51200
	ds_read_b128 v[178:181], v145 offset:52224
	ds_read_b128 v[182:185], v145 offset:53248
	ds_read_b128 v[186:189], v145 offset:54272
	ds_read_b128 v[190:193], v145 offset:55296
	ds_read_b128 v[194:197], v145 offset:56320
	global_load_lds_dwordx4 v[214:215], off
	s_mov_b32 m0, s62
	v_lshl_add_u64 v[214:215], v[222:223], 0, s[2:3]
	global_load_lds_dwordx4 v[214:215], off
	s_barrier
	s_waitcnt lgkmcnt(0)
	s_setprio 1
	v_mfma_f32_16x16x32_bf16 v[84:87], v[150:153], v[166:169], v[84:87]
	v_mfma_f32_16x16x32_bf16 v[80:83], v[158:161], v[166:169], v[80:83]
	v_mfma_f32_16x16x32_bf16 v[68:71], v[150:153], v[174:177], v[68:71]
	v_mfma_f32_16x16x32_bf16 v[64:67], v[158:161], v[174:177], v[64:67]
	v_mfma_f32_16x16x32_bf16 v[52:55], v[150:153], v[182:185], v[52:55]
	v_mfma_f32_16x16x32_bf16 v[48:51], v[158:161], v[182:185], v[48:51]
	v_mfma_f32_16x16x32_bf16 v[36:39], v[150:153], v[190:193], v[36:39]
	v_mfma_f32_16x16x32_bf16 v[32:35], v[158:161], v[190:193], v[32:35]
	v_mfma_f32_16x16x32_bf16 v[84:87], v[154:157], v[170:173], v[84:87]
	v_mfma_f32_16x16x32_bf16 v[80:83], v[162:165], v[170:173], v[80:83]
	v_mfma_f32_16x16x32_bf16 v[68:71], v[154:157], v[178:181], v[68:71]
	v_mfma_f32_16x16x32_bf16 v[64:67], v[162:165], v[178:181], v[64:67]
	v_mfma_f32_16x16x32_bf16 v[52:55], v[154:157], v[186:189], v[52:55]
	v_mfma_f32_16x16x32_bf16 v[48:51], v[162:165], v[186:189], v[48:51]
	v_mfma_f32_16x16x32_bf16 v[36:39], v[154:157], v[194:197], v[36:39]
	v_mfma_f32_16x16x32_bf16 v[32:35], v[162:165], v[194:197], v[32:35]
	s_setprio 0
	s_barrier
	s_add_u32 s46, s46, 0x40080
	s_addc_u32 s47, s47, 0
	s_mov_b32 m0, s78
	v_lshl_add_u64 v[150:151], s[46:47], 0, v[130:131]
	global_load_lds_dwordx4 v[150:151], off
	s_mov_b32 m0, s79
	v_lshl_add_u64 v[150:151], s[46:47], 0, v[128:129]
	global_load_lds_dwordx4 v[150:151], off
	s_waitcnt vmcnt(6)
	s_barrier
; #define G_WAIT_V(n) asm volatile("s_waitcnt vmcnt(" #n ")" ::: "memory")
; #define G_BAR __builtin_amdgcn_s_barrier()
;     ...
;     G_WAIT_V(0);
;     if (wr == 0) G_BAR;
;     G_BAR;
;     __device__ __forceinline__ void epi(const f32x4 (&acc)[2][2][4][2], const Unit& u, int wr, int wc, int fr, int fq) const {
;         const int row0 = u.pm * 256 + wr * 64 + fr, col0 = wc * 32 + 4 * fq;
; #pragma unroll
;         for (int ai = 0; ai < 2; ++ai)
; #pragma unroll
;             for (int m = 0; m < 4; ++m) {
;                 float* rowp = Send + (size_t)u.pn * NG * NCH * 256 + ((size_t)u.g * NCH + row0 + ai * 128 + m * 16) * 256 + col0;
; #pragma unroll
;                 for (int bj = 0; bj < 2; ++bj)
; #pragma unroll
;                     for (int n = 0; n < 2; ++n) *(f32x4*)(rowp + bj * 128 + n * 16) = acc[ai][bj][m][n];
;             }
	s_setprio 1
	v_mfma_f32_16x16x32_bf16 v[124:127], v[198:201], v[166:169], v[124:127]
	v_mfma_f32_16x16x32_bf16 v[120:123], v[206:209], v[166:169], v[120:123]
	v_mfma_f32_16x16x32_bf16 v[116:119], v[198:201], v[174:177], v[116:119]
	v_mfma_f32_16x16x32_bf16 v[112:115], v[206:209], v[174:177], v[112:115]
	v_mfma_f32_16x16x32_bf16 v[108:111], v[198:201], v[182:185], v[108:111]
	v_mfma_f32_16x16x32_bf16 v[104:107], v[206:209], v[182:185], v[104:107]
	v_mfma_f32_16x16x32_bf16 v[100:103], v[198:201], v[190:193], v[100:103]
	v_mfma_f32_16x16x32_bf16 v[96:99], v[206:209], v[190:193], v[96:99]
	v_mfma_f32_16x16x32_bf16 v[124:127], v[202:205], v[170:173], v[124:127]
	v_mfma_f32_16x16x32_bf16 v[120:123], v[210:213], v[170:173], v[120:123]
	v_mfma_f32_16x16x32_bf16 v[116:119], v[202:205], v[178:181], v[116:119]
	v_mfma_f32_16x16x32_bf16 v[112:115], v[210:213], v[178:181], v[112:115]
	v_mfma_f32_16x16x32_bf16 v[108:111], v[202:205], v[186:189], v[108:111]
	v_mfma_f32_16x16x32_bf16 v[104:107], v[210:213], v[186:189], v[104:107]
	v_mfma_f32_16x16x32_bf16 v[100:103], v[202:205], v[194:197], v[100:103]
	v_mfma_f32_16x16x32_bf16 v[96:99], v[210:213], v[194:197], v[96:99]
	s_setprio 0
	s_add_i32 s80, s80, 2
	s_add_u32 s44, s44, 0x100
	s_addc_u32 s45, s45, 0
	s_cmp_gt_u32 s80, 5
	s_barrier
	s_cbranch_scc0 .LBB0_580
	s_lshl_b32 s1, s53, 25
	s_add_u32 s4, s59, s1
	s_addc_u32 s5, s60, 0
	s_ashr_i32 s1, s0, 31
	v_lshl_add_u32 v138, s54, 8, v142
	s_lshl_b64 s[0:1], s[0:1], 19
	v_ashrrev_i32_e32 v139, 31, v138
	s_add_u32 s0, s4, s0
	v_lshlrev_b64 v[138:139], 10, v[138:139]
	s_addc_u32 s1, s5, s1
	v_lshl_add_u64 v[138:139], s[0:1], 0, v[138:139]
	v_lshl_add_u64 v[138:139], v[138:139], 0, v[132:133]
	global_store_dwordx4 v[138:139], v[28:31], off
	global_store_dwordx4 v[138:139], v[24:27], off offset:64
	global_store_dwordx4 v[138:139], v[92:95], off offset:512
	global_store_dwordx4 v[138:139], v[88:91], off offset:576
	v_add_co_u32_e32 v26, vcc, s58, v138
	v_lshl_add_u64 v[24:25], v[138:139], 0, s[18:19]
	s_nop 0
	v_addc_co_u32_e32 v27, vcc, 0, v139, vcc
	global_store_dwordx4 v[26:27], v[20:23], off
	global_store_dwordx4 v[24:25], v[16:19], off offset:64
	global_store_dwordx4 v[24:25], v[76:79], off offset:512
	global_store_dwordx4 v[24:25], v[72:75], off offset:576
	v_add_co_u32_e32 v18, vcc, s63, v138
	v_lshl_add_u64 v[16:17], v[138:139], 0, s[20:21]
	s_nop 0
	v_addc_co_u32_e32 v19, vcc, 0, v139, vcc
	global_store_dwordx4 v[18:19], v[12:15], off
	global_store_dwordx4 v[16:17], v[8:11], off offset:64
	global_store_dwordx4 v[16:17], v[60:63], off offset:512
	global_store_dwordx4 v[16:17], v[56:59], off offset:576
	v_add_co_u32_e32 v10, vcc, s65, v138
	v_lshl_add_u64 v[8:9], v[138:139], 0, s[22:23]
	s_nop 0
	v_addc_co_u32_e32 v11, vcc, 0, v139, vcc
	global_store_dwordx4 v[10:11], v[4:7], off
	global_store_dwordx4 v[8:9], v[0:3], off offset:64
	global_store_dwordx4 v[8:9], v[44:47], off offset:512
	global_store_dwordx4 v[8:9], v[40:43], off offset:576
	v_add_co_u32_e32 v2, vcc, s67, v138
	v_lshl_add_u64 v[0:1], v[138:139], 0, s[24:25]
	s_nop 0
	v_addc_co_u32_e32 v3, vcc, 0, v139, vcc
	global_store_dwordx4 v[2:3], v[84:87], off
	global_store_dwordx4 v[0:1], v[80:83], off offset:64
	global_store_dwordx4 v[0:1], v[124:127], off offset:512
	global_store_dwordx4 v[0:1], v[120:123], off offset:576
	v_add_co_u32_e32 v2, vcc, s68, v138
	v_lshl_add_u64 v[0:1], v[138:139], 0, s[26:27]
	s_nop 0
	v_addc_co_u32_e32 v3, vcc, 0, v139, vcc
	global_store_dwordx4 v[2:3], v[68:71], off
	global_store_dwordx4 v[0:1], v[64:67], off offset:64
	global_store_dwordx4 v[0:1], v[116:119], off offset:512
	global_store_dwordx4 v[0:1], v[112:115], off offset:576
	v_add_co_u32_e32 v2, vcc, s69, v138
	v_lshl_add_u64 v[0:1], v[138:139], 0, s[28:29]
	s_nop 0
	v_addc_co_u32_e32 v3, vcc, 0, v139, vcc
	global_store_dwordx4 v[2:3], v[52:55], off
	global_store_dwordx4 v[0:1], v[48:51], off offset:64
	global_store_dwordx4 v[0:1], v[108:111], off offset:512
	global_store_dwordx4 v[0:1], v[104:107], off offset:576
	v_add_co_u32_e32 v2, vcc, 0x2c000, v138
	s_mov_b32 s54, s72
	s_nop 0
	v_addc_co_u32_e32 v3, vcc, 0, v139, vcc
	v_readlane_b32 s72, v254, 3
	v_readlane_b32 s74, v254, 5
	s_and_b64 vcc, exec, s[36:37]
	s_mov_b32 s0, s34
	s_mov_b32 s53, s71
	s_mov_b64 s[6:7], s[40:41]
	s_mov_b64 s[4:5], s[38:39]
	v_readlane_b32 s73, v254, 4
	v_readlane_b32 s75, v254, 6
	v_lshl_add_u64 v[0:1], v[138:139], 0, s[30:31]
	global_store_dwordx4 v[2:3], v[36:39], off
	global_store_dwordx4 v[0:1], v[32:35], off offset:64
	global_store_dwordx4 v[0:1], v[100:103], off offset:512
	global_store_dwordx4 v[0:1], v[96:99], off offset:576
	s_cbranch_vccz .LBB0_575
	s_waitcnt vmcnt(0)
	s_cmpk_gt_u32 s48, 0xff
	s_cbranch_scc1 .LBB0_584
	s_barrier

; #define G_STAGE_A(buf, h, b0, b1, tt) do { const bool _s2 = P::SEG && (tt) >= P::TS; \
;         const char* _g = _s2 ? (b1) + (ptrdiff_t)((tt) - P::TS) * kA2 + (ptrdiff_t)(h) * hA2 : (b0) + (ptrdiff_t)(tt) * kA + (ptrdiff_t)(h) * hA; \
;         stage2(lds + G_SA(buf, h) + ldsw, _g, _s2 ? voA20 : voA0, _s2 ? voA21 : voA1); } while (0)
; #define G_STAGE_B(buf, h, b0, b1, tt) do { const bool _s2 = P::SEG && (tt) >= P::TS; \
;         const char* _g = _s2 ? (b1) + (ptrdiff_t)((tt) - P::TS) * kB2 + (ptrdiff_t)(h) * hB2 : (b0) + (ptrdiff_t)(tt) * kB + (ptrdiff_t)(h) * hB; \
;         stage2(lds + G_SB(buf, h) + ldsw, _g, _s2 ? voB20 : voB0, _s2 ? voB21 : voB1); } while (0)
; #define G_WAIT_V(n) asm volatile("s_waitcnt vmcnt(" #n ")" ::: "memory")
; #define G_BAR __builtin_amdgcn_s_barrier()
;     __device__ __forceinline__ bool unit(int L, Unit& u) const { u.g = L; return order_mn(L, T / 256, NGU / 256, u.pm, u.pn); }
;     __device__ __forceinline__ bool unit(int L, Unit& u) const { u.g = L; return order_mn(L, T / 256, D / 256, u.pm, u.pn); }
;     __device__ __forceinline__ bool unit(int L, Unit& u) const { u.g = 0; return order_mn(L, T / 256, 8, u.pm, u.pn); }
;     __device__ __forceinline__ bool unit(int L, Unit& u) const { if (L >= NG * 4) return false; u.g = L >> 2; u.pm = (L >> 1) & 1; u.pn = L & 1; return true; }
;     __device__ __forceinline__ bool unit(int L, Unit& u) const { if (L >= NG * 8) return false; u.g = L >> 3; u.pm = (L >> 2) & 1; u.pn = L & 3; return true; }
;     ...
;     const char* cA = p.a0(cur); const char* cB = p.b0(cur);
;     const char* cA2 = P::SEG ? p.a1(cur) : cA; const char* cB2 = P::SEG ? p.b1(cur) : cB;
;     G_STAGE_B(0, 0, cB, cB2, 0); G_STAGE_A(0, 0, cA, cA2, 0); G_STAGE_B(0, 1, cB, cB2, 0); G_STAGE_A(0, 1, cA, cA2, 0);
;     if (wr == 1) G_BAR;
;     G_WAIT_V(4); G_BAR;
;     G_STAGE_B(1, 0, cB, cB2, 1); G_STAGE_A(1, 0, cA, cA2, 1); G_STAGE_B(1, 1, cB, cB2, 1);
;     G_WAIT_V(6); G_BAR;
;     for (;;) {
;         const bool has_next = p.unit((ui + 1) * G + c, nxt);
;         const char* nA = has_next ? p.a0(nxt) : cA; const char* nB = has_next ? p.b0(nxt) : cB;
;         const char* nA2 = P::SEG ? (has_next ? p.a1(nxt) : cA2) : nA; const char* nB2 = P::SEG ? (has_next ? p.b1(nxt) : cB2) : nB;
.LBB0_789:
	s_bfe_u32 s81, s22, 0x10002
	s_and_b64 s[22:23], s[40:41], exec
	s_cselect_b32 s22, s81, s29
	s_cselect_b32 s2, s80, s2
	s_lshl_b32 s24, s22, 8
	s_ashr_i32 s25, s24, 31
	s_lshl_b64 s[22:23], s[24:25], 11
	s_lshl_b64 s[42:43], s[26:27], 20
	s_add_u32 s29, s8, s42
	s_addc_u32 s42, s9, s43
	s_add_u32 s22, s29, s22
	s_addc_u32 s23, s42, s23
	s_lshl_b64 s[24:25], s[24:25], 9
	s_lshl_b64 s[42:43], s[26:27], 18
	s_add_u32 s29, s66, s42
	s_addc_u32 s42, s67, s43
	s_add_u32 s24, s29, s24
	s_addc_u32 s25, s42, s25
	s_lshl_b32 s42, s2, 8
	ds_read_b128 v[0:3], v224
	ds_read_b128 v[4:7], v224 offset:1024
	ds_read_b128 v[8:11], v224 offset:2048
	ds_read_b128 v[12:15], v224 offset:3072
	s_ashr_i32 s43, s42, 31
	s_lshl_b64 s[42:43], s[42:43], 9
	s_lshl_b64 s[26:27], s[26:27], 19
	s_add_u32 s2, s68, s26
	s_addc_u32 s27, s69, s27
	s_add_u32 s26, s2, s42
	s_addc_u32 s27, s27, s43
	s_add_u32 s42, s30, 0x40080
	s_addc_u32 s43, s31, 0
	s_add_i32 s29, s58, 0xc000
	v_lshl_add_u64 v[48:49], s[42:43], 0, v[202:203]
	s_mov_b32 m0, s29
	s_add_i32 s84, s58, 0xe000
	ds_read_b128 v[16:19], v225
	ds_read_b128 v[20:23], v225 offset:1024
	ds_read_b128 v[24:27], v225 offset:2048
	ds_read_b128 v[28:31], v225 offset:3072
	ds_read_b128 v[32:35], v225 offset:4096
	ds_read_b128 v[36:39], v225 offset:5120
	ds_read_b128 v[40:43], v225 offset:6144
	ds_read_b128 v[44:47], v225 offset:7168
	global_load_lds_dwordx4 v[48:49], off
	s_mov_b32 m0, s84
	v_lshl_add_u64 v[48:49], s[42:43], 0, v[198:199]
	global_load_lds_dwordx4 v[48:49], off
	s_waitcnt lgkmcnt(8)
	s_barrier
	s_waitcnt lgkmcnt(0)
	s_setprio 1
	v_mfma_f32_16x16x32_bf16 v[48:51], v[0:3], v[16:19], 0
	v_mfma_f32_16x16x32_bf16 v[52:55], v[8:11], v[16:19], 0
	v_mfma_f32_16x16x32_bf16 v[56:59], v[0:3], v[24:27], 0
	v_mfma_f32_16x16x32_bf16 v[60:63], v[8:11], v[24:27], 0
	v_mfma_f32_16x16x32_bf16 v[64:67], v[0:3], v[32:35], 0
	v_mfma_f32_16x16x32_bf16 v[68:71], v[8:11], v[32:35], 0
	v_mfma_f32_16x16x32_bf16 v[72:75], v[0:3], v[40:43], 0
	v_mfma_f32_16x16x32_bf16 v[76:79], v[8:11], v[40:43], 0
	v_mfma_f32_16x16x32_bf16 v[48:51], v[4:7], v[20:23], v[48:51]
	v_mfma_f32_16x16x32_bf16 v[52:55], v[12:15], v[20:23], v[52:55]
	v_mfma_f32_16x16x32_bf16 v[56:59], v[4:7], v[28:31], v[56:59]
	v_mfma_f32_16x16x32_bf16 v[60:63], v[12:15], v[28:31], v[60:63]
	v_mfma_f32_16x16x32_bf16 v[64:67], v[4:7], v[36:39], v[64:67]
	v_mfma_f32_16x16x32_bf16 v[68:71], v[12:15], v[36:39], v[68:71]
	v_mfma_f32_16x16x32_bf16 v[72:75], v[4:7], v[44:47], v[72:75]
	v_mfma_f32_16x16x32_bf16 v[76:79], v[12:15], v[44:47], v[76:79]
	s_setprio 0
	s_barrier
	v_lshl_add_u64 v[240:241], s[34:35], 0, v[200:201]
	s_add_i32 s2, s76, s57
	v_lshl_add_u64 v[96:97], v[240:241], 0, s[4:5]
	s_mov_b32 m0, s2
	v_lshl_add_u64 v[242:243], s[34:35], 0, v[196:197]
	ds_read_b128 v[80:83], v226
	ds_read_b128 v[84:87], v226 offset:1024
	ds_read_b128 v[88:91], v226 offset:2048
	ds_read_b128 v[92:95], v226 offset:3072
	global_load_lds_dwordx4 v[96:97], off
	v_lshl_add_u64 v[96:97], v[242:243], 0, s[4:5]
	s_add_i32 m0, s2, 0x2000
	s_nop 0
	global_load_lds_dwordx4 v[96:97], off
	s_barrier
	s_waitcnt lgkmcnt(0)
	s_setprio 1
	v_mfma_f32_16x16x32_bf16 v[96:99], v[80:83], v[16:19], 0
	v_mfma_f32_16x16x32_bf16 v[16:19], v[88:91], v[16:19], 0
	v_mfma_f32_16x16x32_bf16 v[100:103], v[80:83], v[24:27], 0
	v_mfma_f32_16x16x32_bf16 v[24:27], v[88:91], v[24:27], 0
	v_mfma_f32_16x16x32_bf16 v[104:107], v[80:83], v[32:35], 0
	v_mfma_f32_16x16x32_bf16 v[32:35], v[88:91], v[32:35], 0
	v_mfma_f32_16x16x32_bf16 v[108:111], v[80:83], v[40:43], 0
	v_mfma_f32_16x16x32_bf16 v[40:43], v[88:91], v[40:43], 0
	v_mfma_f32_16x16x32_bf16 v[96:99], v[84:87], v[20:23], v[96:99]
	v_mfma_f32_16x16x32_bf16 v[16:19], v[92:95], v[20:23], v[16:19]
	v_mfma_f32_16x16x32_bf16 v[20:23], v[84:87], v[28:31], v[100:103]
	v_mfma_f32_16x16x32_bf16 v[24:27], v[92:95], v[28:31], v[24:27]
	v_mfma_f32_16x16x32_bf16 v[28:31], v[84:87], v[36:39], v[104:107]
	v_mfma_f32_16x16x32_bf16 v[32:35], v[92:95], v[36:39], v[32:35]
	v_mfma_f32_16x16x32_bf16 v[36:39], v[84:87], v[44:47], v[108:111]
	v_mfma_f32_16x16x32_bf16 v[40:43], v[92:95], v[44:47], v[40:43]
	s_setprio 0
	v_lshl_add_u64 v[244:245], s[30:31], 0, v[202:203]
	s_mov_b32 m0, s58
	v_lshl_add_u64 v[128:129], v[244:245], 0, s[6:7]
	v_lshl_add_u64 v[246:247], s[30:31], 0, v[198:199]
	s_barrier
	ds_read_b128 v[44:47], v225 offset:16384
	ds_read_b128 v[100:103], v225 offset:17408
	ds_read_b128 v[104:107], v225 offset:18432
	ds_read_b128 v[108:111], v225 offset:19456
	ds_read_b128 v[112:115], v225 offset:20480
	ds_read_b128 v[116:119], v225 offset:21504
	ds_read_b128 v[120:123], v225 offset:22528
	ds_read_b128 v[124:127], v225 offset:23552
	global_load_lds_dwordx4 v[128:129], off
	s_mov_b32 m0, s61
	v_lshl_add_u64 v[128:129], v[246:247], 0, s[6:7]
	global_load_lds_dwordx4 v[128:129], off
	s_barrier
	s_waitcnt lgkmcnt(0)
	s_setprio 1
	v_mfma_f32_16x16x32_bf16 v[128:131], v[0:3], v[44:47], 0
	v_mfma_f32_16x16x32_bf16 v[132:135], v[8:11], v[44:47], 0
	v_mfma_f32_16x16x32_bf16 v[136:139], v[0:3], v[104:107], 0
	v_mfma_f32_16x16x32_bf16 v[140:143], v[8:11], v[104:107], 0
	v_mfma_f32_16x16x32_bf16 v[144:147], v[0:3], v[112:115], 0
	v_mfma_f32_16x16x32_bf16 v[148:151], v[8:11], v[112:115], 0
	v_mfma_f32_16x16x32_bf16 v[0:3], v[0:3], v[120:123], 0
	v_mfma_f32_16x16x32_bf16 v[8:11], v[8:11], v[120:123], 0
	v_mfma_f32_16x16x32_bf16 v[128:131], v[4:7], v[100:103], v[128:131]
	v_mfma_f32_16x16x32_bf16 v[136:139], v[4:7], v[108:111], v[136:139]
	v_mfma_f32_16x16x32_bf16 v[144:147], v[4:7], v[116:119], v[144:147]
	v_mfma_f32_16x16x32_bf16 v[0:3], v[4:7], v[124:127], v[0:3]
	v_mfma_f32_16x16x32_bf16 v[4:7], v[12:15], v[124:127], v[8:11]
	v_mfma_f32_16x16x32_bf16 v[132:135], v[12:15], v[100:103], v[132:135]
	v_mfma_f32_16x16x32_bf16 v[140:143], v[12:15], v[108:111], v[140:143]
	v_mfma_f32_16x16x32_bf16 v[148:151], v[12:15], v[116:119], v[148:151]
	s_setprio 0
	s_barrier
	s_add_i32 s2, s77, s57
	s_mov_b32 m0, s2
	s_nop 0
	global_load_lds_dwordx4 v[240:241], off
	s_add_i32 m0, s2, 0x2000
	s_nop 0
	global_load_lds_dwordx4 v[242:243], off
	s_waitcnt vmcnt(6)
	s_barrier
	s_setprio 1
	v_mfma_f32_16x16x32_bf16 v[8:11], v[80:83], v[44:47], 0
	v_mfma_f32_16x16x32_bf16 v[12:15], v[88:91], v[44:47], 0
	v_mfma_f32_16x16x32_bf16 v[44:47], v[80:83], v[104:107], 0
	v_mfma_f32_16x16x32_bf16 v[104:107], v[88:91], v[104:107], 0
	v_mfma_f32_16x16x32_bf16 v[152:155], v[80:83], v[112:115], 0
	v_mfma_f32_16x16x32_bf16 v[112:115], v[88:91], v[112:115], 0
	v_mfma_f32_16x16x32_bf16 v[80:83], v[80:83], v[120:123], 0
	v_mfma_f32_16x16x32_bf16 v[88:91], v[88:91], v[120:123], 0
	v_mfma_f32_16x16x32_bf16 v[156:159], v[84:87], v[100:103], v[8:11]
	v_mfma_f32_16x16x32_bf16 v[160:163], v[92:95], v[100:103], v[12:15]
	v_mfma_f32_16x16x32_bf16 v[164:167], v[84:87], v[108:111], v[44:47]
	v_mfma_f32_16x16x32_bf16 v[168:171], v[92:95], v[108:111], v[104:107]
	v_mfma_f32_16x16x32_bf16 v[152:155], v[84:87], v[116:119], v[152:155]
	v_mfma_f32_16x16x32_bf16 v[172:175], v[92:95], v[116:119], v[112:115]
	v_mfma_f32_16x16x32_bf16 v[176:179], v[84:87], v[124:127], v[80:83]
	v_mfma_f32_16x16x32_bf16 v[180:183], v[92:95], v[124:127], v[88:91]
	s_setprio 0
	s_add_i32 s2, 0, 0x18000
	v_add_u32_e32 v80, s2, v222
	s_barrier
	ds_read_b128 v[8:11], v80
	ds_read_b128 v[12:15], v80 offset:1024
	ds_read_b128 v[44:47], v80 offset:2048
	ds_read_b128 v[184:187], v80 offset:3072
	s_add_u32 s42, s30, 0x40100
	s_addc_u32 s43, s31, 0
	s_mov_b32 m0, s64
	v_lshl_add_u64 v[88:89], s[42:43], 0, v[202:203]
	ds_read_b128 v[80:83], v225 offset:32768
	ds_read_b128 v[84:87], v225 offset:33792
	ds_read_b128 v[100:103], v225 offset:34816
	ds_read_b128 v[188:191], v225 offset:35840
	ds_read_b128 v[112:115], v225 offset:36864
	ds_read_b128 v[212:215], v225 offset:37888
	ds_read_b128 v[116:119], v225 offset:38912
	ds_read_b128 v[216:219], v225 offset:39936
	global_load_lds_dwordx4 v[88:89], off
	s_mov_b32 m0, s65
	v_lshl_add_u64 v[88:89], s[42:43], 0, v[198:199]
	global_load_lds_dwordx4 v[88:89], off
	s_waitcnt lgkmcnt(8)
	s_barrier
	s_waitcnt lgkmcnt(0)
	s_setprio 1
	v_mfma_f32_16x16x32_bf16 v[48:51], v[8:11], v[80:83], v[48:51]
	v_mfma_f32_16x16x32_bf16 v[52:55], v[44:47], v[80:83], v[52:55]
	v_mfma_f32_16x16x32_bf16 v[56:59], v[8:11], v[100:103], v[56:59]
	v_mfma_f32_16x16x32_bf16 v[60:63], v[44:47], v[100:103], v[60:63]
	v_mfma_f32_16x16x32_bf16 v[64:67], v[8:11], v[112:115], v[64:67]
	v_mfma_f32_16x16x32_bf16 v[68:71], v[44:47], v[112:115], v[68:71]
	v_mfma_f32_16x16x32_bf16 v[72:75], v[8:11], v[116:119], v[72:75]
	v_mfma_f32_16x16x32_bf16 v[228:231], v[44:47], v[116:119], v[76:79]
	v_mfma_f32_16x16x32_bf16 v[124:127], v[12:15], v[84:87], v[48:51]
	v_mfma_f32_16x16x32_bf16 v[120:123], v[184:187], v[84:87], v[52:55]
	v_mfma_f32_16x16x32_bf16 v[108:111], v[12:15], v[188:191], v[56:59]
	v_mfma_f32_16x16x32_bf16 v[104:107], v[184:187], v[188:191], v[60:63]
	v_mfma_f32_16x16x32_bf16 v[92:95], v[12:15], v[212:215], v[64:67]
	v_mfma_f32_16x16x32_bf16 v[88:91], v[184:187], v[212:215], v[68:71]
	v_mfma_f32_16x16x32_bf16 v[76:79], v[12:15], v[216:219], v[72:75]
	v_mfma_f32_16x16x32_bf16 v[72:75], v[184:187], v[216:219], v[228:231]
	s_setprio 0
	s_barrier
	s_add_i32 s44, 0, 0x1c000
	s_add_u32 s42, s34, 0xffffe800
	v_add_u32_e32 v56, s44, v222
	s_addc_u32 s43, s35, -1
	s_add_i32 s2, s2, s57
	ds_read_b128 v[48:51], v56
	ds_read_b128 v[228:231], v56 offset:1024
	ds_read_b128 v[52:55], v56 offset:2048
	ds_read_b128 v[232:235], v56 offset:3072
	v_lshl_add_u64 v[56:57], s[42:43], 0, v[200:201]
	s_mov_b32 m0, s2
	s_nop 0
	global_load_lds_dwordx4 v[56:57], off
	v_lshl_add_u64 v[56:57], s[42:43], 0, v[196:197]
	s_add_i32 m0, s2, 0x2000
	s_nop 0
	global_load_lds_dwordx4 v[56:57], off
	s_barrier
;     ...
;         G_PAIR(0, 1);
; #pragma unroll 1
;         for (int t = 2; t < nt; t += 2) G_PAIR(t, 0);
	s_waitcnt lgkmcnt(0)
	s_setprio 1
	v_mfma_f32_16x16x32_bf16 v[56:59], v[48:51], v[80:83], v[96:99]
	v_mfma_f32_16x16x32_bf16 v[16:19], v[52:55], v[80:83], v[16:19]
	v_mfma_f32_16x16x32_bf16 v[20:23], v[48:51], v[100:103], v[20:23]
	v_mfma_f32_16x16x32_bf16 v[24:27], v[52:55], v[100:103], v[24:27]
	v_mfma_f32_16x16x32_bf16 v[28:31], v[48:51], v[112:115], v[28:31]
	v_mfma_f32_16x16x32_bf16 v[32:35], v[52:55], v[112:115], v[32:35]
	v_mfma_f32_16x16x32_bf16 v[36:39], v[48:51], v[116:119], v[36:39]
	v_mfma_f32_16x16x32_bf16 v[40:43], v[52:55], v[116:119], v[40:43]
	v_mfma_f32_16x16x32_bf16 v[116:119], v[228:231], v[84:87], v[56:59]
	v_mfma_f32_16x16x32_bf16 v[112:115], v[232:235], v[84:87], v[16:19]
	v_mfma_f32_16x16x32_bf16 v[100:103], v[228:231], v[188:191], v[20:23]
	v_mfma_f32_16x16x32_bf16 v[96:99], v[232:235], v[188:191], v[24:27]
	v_mfma_f32_16x16x32_bf16 v[84:87], v[228:231], v[212:215], v[28:31]
	v_mfma_f32_16x16x32_bf16 v[80:83], v[232:235], v[212:215], v[32:35]
	v_mfma_f32_16x16x32_bf16 v[68:71], v[228:231], v[216:219], v[36:39]
	v_mfma_f32_16x16x32_bf16 v[64:67], v[232:235], v[216:219], v[40:43]
	s_setprio 0
	s_mov_b32 m0, s72
	v_lshl_add_u64 v[24:25], v[244:245], 0, s[12:13]
	s_barrier
	ds_read_b128 v[16:19], v225 offset:49152
	ds_read_b128 v[20:23], v225 offset:50176
	ds_read_b128 v[32:35], v225 offset:51200
	ds_read_b128 v[188:191], v225 offset:52224
	ds_read_b128 v[36:39], v225 offset:53248
	ds_read_b128 v[212:215], v225 offset:54272
	ds_read_b128 v[216:219], v225 offset:55296
	ds_read_b128 v[236:239], v225 offset:56320
	global_load_lds_dwordx4 v[24:25], off
	s_mov_b32 m0, s73
	v_lshl_add_u64 v[24:25], v[246:247], 0, s[12:13]
	global_load_lds_dwordx4 v[24:25], off
	s_barrier
	s_waitcnt lgkmcnt(0)
	s_setprio 1
	v_mfma_f32_16x16x32_bf16 v[24:27], v[8:11], v[16:19], v[128:131]
	v_mfma_f32_16x16x32_bf16 v[28:31], v[44:47], v[16:19], v[132:135]
	v_mfma_f32_16x16x32_bf16 v[40:43], v[8:11], v[32:35], v[136:139]
	v_mfma_f32_16x16x32_bf16 v[128:131], v[44:47], v[32:35], v[140:143]
	v_mfma_f32_16x16x32_bf16 v[132:135], v[8:11], v[36:39], v[144:147]
	v_mfma_f32_16x16x32_bf16 v[136:139], v[44:47], v[36:39], v[148:151]
	v_mfma_f32_16x16x32_bf16 v[0:3], v[8:11], v[216:219], v[0:3]
	v_mfma_f32_16x16x32_bf16 v[4:7], v[44:47], v[216:219], v[4:7]
	v_mfma_f32_16x16x32_bf16 v[60:63], v[12:15], v[20:23], v[24:27]
	v_mfma_f32_16x16x32_bf16 v[56:59], v[184:187], v[20:23], v[28:31]
	v_mfma_f32_16x16x32_bf16 v[44:47], v[12:15], v[188:191], v[40:43]
	v_mfma_f32_16x16x32_bf16 v[40:43], v[184:187], v[188:191], v[128:131]
	v_mfma_f32_16x16x32_bf16 v[28:31], v[12:15], v[212:215], v[132:135]
	v_mfma_f32_16x16x32_bf16 v[24:27], v[184:187], v[212:215], v[136:139]
	v_mfma_f32_16x16x32_bf16 v[12:15], v[12:15], v[236:239], v[0:3]
	v_mfma_f32_16x16x32_bf16 v[8:11], v[184:187], v[236:239], v[4:7]
	s_setprio 0
	s_barrier
	s_add_i32 s2, s44, s57
	v_lshl_add_u64 v[0:1], v[240:241], 0, s[14:15]
	s_mov_b32 m0, s2
	s_nop 0
	global_load_lds_dwordx4 v[0:1], off
	v_lshl_add_u64 v[0:1], v[242:243], 0, s[14:15]
	s_add_i32 m0, s2, 0x2000
	s_nop 0
	global_load_lds_dwordx4 v[0:1], off
	s_waitcnt vmcnt(6)
	s_barrier
	s_setprio 1
	v_mfma_f32_16x16x32_bf16 v[0:3], v[48:51], v[16:19], v[156:159]
	v_mfma_f32_16x16x32_bf16 v[4:7], v[52:55], v[16:19], v[160:163]
	v_mfma_f32_16x16x32_bf16 v[16:19], v[48:51], v[32:35], v[164:167]
	v_mfma_f32_16x16x32_bf16 v[32:35], v[52:55], v[32:35], v[168:171]
	v_mfma_f32_16x16x32_bf16 v[128:131], v[48:51], v[36:39], v[152:155]
	v_mfma_f32_16x16x32_bf16 v[132:135], v[52:55], v[36:39], v[172:175]
	v_mfma_f32_16x16x32_bf16 v[136:139], v[48:51], v[216:219], v[176:179]
	v_mfma_f32_16x16x32_bf16 v[140:143], v[52:55], v[216:219], v[180:183]
	v_mfma_f32_16x16x32_bf16 v[52:55], v[228:231], v[20:23], v[0:3]
	v_mfma_f32_16x16x32_bf16 v[48:51], v[232:235], v[20:23], v[4:7]
	v_mfma_f32_16x16x32_bf16 v[36:39], v[228:231], v[188:191], v[16:19]
	v_mfma_f32_16x16x32_bf16 v[32:35], v[232:235], v[188:191], v[32:35]
	v_mfma_f32_16x16x32_bf16 v[20:23], v[228:231], v[212:215], v[128:131]
	v_mfma_f32_16x16x32_bf16 v[16:19], v[232:235], v[212:215], v[132:135]
	v_mfma_f32_16x16x32_bf16 v[4:7], v[228:231], v[236:239], v[136:139]
	v_mfma_f32_16x16x32_bf16 v[0:3], v[232:235], v[236:239], v[140:143]
	s_setprio 0
	s_add_u32 s42, s30, 0x40180
	s_addc_u32 s43, s31, 0
	s_mov_b32 s86, 2
	s_mov_b32 s85, -16
	s_barrier

.LBB0_800:
	s_mov_b32 m0, s58
	v_lshl_add_u64 v[228:229], s[48:49], 0, v[218:219]
	global_load_lds_dwordx4 v[228:229], off
	s_mov_b32 m0, s61
	v_lshl_add_u64 v[228:229], s[48:49], 0, v[216:217]
	global_load_lds_dwordx4 v[228:229], off
	s_barrier
	s_waitcnt lgkmcnt(0)
	s_setprio 1
	v_mfma_f32_16x16x32_bf16 v[60:63], v[136:139], v[176:179], v[60:63]
	v_mfma_f32_16x16x32_bf16 v[56:59], v[144:147], v[176:179], v[56:59]
	v_mfma_f32_16x16x32_bf16 v[44:47], v[136:139], v[180:183], v[44:47]
	v_mfma_f32_16x16x32_bf16 v[40:43], v[144:147], v[180:183], v[40:43]
	v_mfma_f32_16x16x32_bf16 v[228:231], v[136:139], v[184:187], v[28:31]
	v_mfma_f32_16x16x32_bf16 v[232:235], v[144:147], v[184:187], v[24:27]
	v_mfma_f32_16x16x32_bf16 v[136:139], v[136:139], v[188:191], v[12:15]
	v_mfma_f32_16x16x32_bf16 v[144:147], v[144:147], v[188:191], v[8:11]
	v_mfma_f32_16x16x32_bf16 v[8:11], v[128:131], v[160:163], v[60:63]
	v_mfma_f32_16x16x32_bf16 v[12:15], v[132:135], v[160:163], v[56:59]
	v_mfma_f32_16x16x32_bf16 v[24:27], v[128:131], v[164:167], v[44:47]
	v_mfma_f32_16x16x32_bf16 v[28:31], v[132:135], v[164:167], v[40:43]
	v_mfma_f32_16x16x32_bf16 v[40:43], v[128:131], v[168:171], v[228:231]
	v_mfma_f32_16x16x32_bf16 v[44:47], v[132:135], v[168:171], v[232:235]
	v_mfma_f32_16x16x32_bf16 v[56:59], v[128:131], v[172:175], v[136:139]
	v_mfma_f32_16x16x32_bf16 v[60:63], v[132:135], v[172:175], v[144:147]
	s_setprio 0
	s_barrier
	s_mov_b64 s[50:51], -1
	s_and_b64 vcc, exec, s[46:47]
	s_cbranch_vccz .LBB0_802
	s_mov_b32 s45, s3
	s_lshl_b64 s[48:49], s[44:45], 11
	s_sub_u32 s2, 0, s48
	s_subb_u32 s45, 0, s49
	s_add_u32 s2, s91, s2
	s_addc_u32 s45, s90, s45
	s_add_u32 s48, s2, 0x1000
	s_addc_u32 s49, s45, 0
	s_mov_b64 s[50:51], 0

.LBB0_804:
	s_mov_b32 m0, s62
	v_lshl_add_u64 v[128:129], s[48:49], 0, v[214:215]
	global_load_lds_dwordx4 v[128:129], off
	s_mov_b32 m0, s63
	v_lshl_add_u64 v[128:129], s[48:49], 0, v[212:213]
	global_load_lds_dwordx4 v[128:129], off
	s_waitcnt vmcnt(6)
	s_barrier
	s_setprio 1
	v_mfma_f32_16x16x32_bf16 v[52:55], v[152:155], v[176:179], v[52:55]
	v_mfma_f32_16x16x32_bf16 v[48:51], v[156:159], v[176:179], v[48:51]
	v_mfma_f32_16x16x32_bf16 v[36:39], v[152:155], v[180:183], v[36:39]
	v_mfma_f32_16x16x32_bf16 v[32:35], v[156:159], v[180:183], v[32:35]
	v_mfma_f32_16x16x32_bf16 v[128:131], v[152:155], v[184:187], v[20:23]
	v_mfma_f32_16x16x32_bf16 v[132:135], v[156:159], v[184:187], v[16:19]
	v_mfma_f32_16x16x32_bf16 v[136:139], v[152:155], v[188:191], v[4:7]
	v_mfma_f32_16x16x32_bf16 v[144:147], v[156:159], v[188:191], v[0:3]
	v_mfma_f32_16x16x32_bf16 v[0:3], v[140:143], v[160:163], v[52:55]
	v_mfma_f32_16x16x32_bf16 v[4:7], v[148:151], v[160:163], v[48:51]
	v_mfma_f32_16x16x32_bf16 v[16:19], v[140:143], v[164:167], v[36:39]
	v_mfma_f32_16x16x32_bf16 v[20:23], v[148:151], v[164:167], v[32:35]
	v_mfma_f32_16x16x32_bf16 v[32:35], v[140:143], v[168:171], v[128:131]
	v_mfma_f32_16x16x32_bf16 v[36:39], v[148:151], v[168:171], v[132:135]
	v_mfma_f32_16x16x32_bf16 v[48:51], v[140:143], v[172:175], v[136:139]
	v_mfma_f32_16x16x32_bf16 v[52:55], v[148:151], v[172:175], v[144:147]
	s_setprio 0
	v_add_u32_e32 v132, 0x18000, v208
	s_barrier
	ds_read_b128 v[136:139], v132
	ds_read_b128 v[128:131], v132 offset:1024
	ds_read_b128 v[140:143], v132 offset:2048
	ds_read_b128 v[132:135], v132 offset:3072
	ds_read_b128 v[176:179], v225 offset:32768
	ds_read_b128 v[160:163], v225 offset:33792
	ds_read_b128 v[180:183], v225 offset:34816
	ds_read_b128 v[164:167], v225 offset:35840
	ds_read_b128 v[184:187], v225 offset:36864
	ds_read_b128 v[168:171], v225 offset:37888
	ds_read_b128 v[188:191], v225 offset:38912
	ds_read_b128 v[172:175], v225 offset:39936
	s_mov_b64 s[50:51], -1
	s_and_b64 vcc, exec, s[46:47]
	s_cbranch_vccz .LBB0_806
	s_lshl_b32 s2, s44, 7
	s_add_u32 s2, s95, s2
	s_addc_u32 s45, s94, 0
	s_add_u32 s48, s2, 0x40000
	s_addc_u32 s49, s45, 0
	s_mov_b64 s[50:51], 0

.LBB0_808:
	s_mov_b32 m0, s64
	v_lshl_add_u64 v[144:145], s[48:49], 0, v[218:219]
	global_load_lds_dwordx4 v[144:145], off
	v_lshl_add_u64 v[144:145], s[48:49], 0, v[216:217]
	s_mov_b32 m0, s65
	s_or_b32 s48, s44, 1
	global_load_lds_dwordx4 v[144:145], off
	s_waitcnt lgkmcnt(8)
	s_barrier
	s_waitcnt lgkmcnt(0)
	s_setprio 1
	v_mfma_f32_16x16x32_bf16 v[72:75], v[136:139], v[176:179], v[72:75]
	v_mfma_f32_16x16x32_bf16 v[76:79], v[140:143], v[176:179], v[76:79]
	v_mfma_f32_16x16x32_bf16 v[88:91], v[136:139], v[180:183], v[88:91]
	v_mfma_f32_16x16x32_bf16 v[92:95], v[140:143], v[180:183], v[92:95]
	v_mfma_f32_16x16x32_bf16 v[144:147], v[136:139], v[184:187], v[104:107]
	v_mfma_f32_16x16x32_bf16 v[148:151], v[140:143], v[184:187], v[108:111]
	v_mfma_f32_16x16x32_bf16 v[152:155], v[136:139], v[188:191], v[120:123]
	v_mfma_f32_16x16x32_bf16 v[156:159], v[140:143], v[188:191], v[124:127]
	v_mfma_f32_16x16x32_bf16 v[124:127], v[128:131], v[160:163], v[72:75]
	v_mfma_f32_16x16x32_bf16 v[120:123], v[132:135], v[160:163], v[76:79]
	v_mfma_f32_16x16x32_bf16 v[108:111], v[128:131], v[164:167], v[88:91]
	v_mfma_f32_16x16x32_bf16 v[104:107], v[132:135], v[164:167], v[92:95]
	v_mfma_f32_16x16x32_bf16 v[92:95], v[128:131], v[168:171], v[144:147]
	v_mfma_f32_16x16x32_bf16 v[88:91], v[132:135], v[168:171], v[148:151]
	v_mfma_f32_16x16x32_bf16 v[76:79], v[128:131], v[172:175], v[152:155]
	v_mfma_f32_16x16x32_bf16 v[72:75], v[132:135], v[172:175], v[156:159]
	s_setprio 0
	s_barrier
	v_add_u32_e32 v148, 0x1c000, v208
	ds_read_b128 v[152:155], v148
	ds_read_b128 v[144:147], v148 offset:1024
	ds_read_b128 v[156:159], v148 offset:2048
	ds_read_b128 v[148:151], v148 offset:3072
	s_mov_b64 s[52:53], -1
	s_and_b64 vcc, exec, s[46:47]
	s_cbranch_vccz .LBB0_810
	s_mov_b32 s49, s3
	s_lshl_b64 s[50:51], s[48:49], 11
	s_sub_u32 s2, 0, s50
	s_subb_u32 s45, 0, s51
	s_add_u32 s50, s91, s2
	s_addc_u32 s51, s90, s45
	s_mov_b64 s[52:53], 0

.LBB0_812:
	s_mov_b32 m0, s70
	v_lshl_add_u64 v[216:217], s[50:51], 0, v[214:215]
	global_load_lds_dwordx4 v[216:217], off
	s_mov_b32 m0, s71
	v_lshl_add_u64 v[216:217], s[50:51], 0, v[212:213]
	global_load_lds_dwordx4 v[216:217], off
	s_barrier
	s_waitcnt lgkmcnt(0)
	s_setprio 1
	v_mfma_f32_16x16x32_bf16 v[64:67], v[152:155], v[176:179], v[64:67]
	v_mfma_f32_16x16x32_bf16 v[68:71], v[156:159], v[176:179], v[68:71]
	v_mfma_f32_16x16x32_bf16 v[80:83], v[152:155], v[180:183], v[80:83]
	v_mfma_f32_16x16x32_bf16 v[84:87], v[156:159], v[180:183], v[84:87]
	v_mfma_f32_16x16x32_bf16 v[176:179], v[152:155], v[184:187], v[96:99]
	v_mfma_f32_16x16x32_bf16 v[180:183], v[156:159], v[184:187], v[100:103]
	v_mfma_f32_16x16x32_bf16 v[184:187], v[152:155], v[188:191], v[112:115]
	v_mfma_f32_16x16x32_bf16 v[188:191], v[156:159], v[188:191], v[116:119]
	v_mfma_f32_16x16x32_bf16 v[116:119], v[144:147], v[160:163], v[64:67]
	v_mfma_f32_16x16x32_bf16 v[112:115], v[148:151], v[160:163], v[68:71]
	v_mfma_f32_16x16x32_bf16 v[100:103], v[144:147], v[164:167], v[80:83]
	v_mfma_f32_16x16x32_bf16 v[96:99], v[148:151], v[164:167], v[84:87]
	v_mfma_f32_16x16x32_bf16 v[84:87], v[144:147], v[168:171], v[176:179]
	v_mfma_f32_16x16x32_bf16 v[80:83], v[148:151], v[168:171], v[180:183]
	v_mfma_f32_16x16x32_bf16 v[68:71], v[144:147], v[172:175], v[184:187]
	v_mfma_f32_16x16x32_bf16 v[64:67], v[148:151], v[172:175], v[188:191]
	s_setprio 0
	s_barrier
	ds_read_b128 v[176:179], v225 offset:49152
	ds_read_b128 v[160:163], v225 offset:50176
	ds_read_b128 v[180:183], v225 offset:51200
	ds_read_b128 v[164:167], v225 offset:52224
	ds_read_b128 v[184:187], v225 offset:53248
	ds_read_b128 v[168:171], v225 offset:54272
	ds_read_b128 v[188:191], v225 offset:55296
	ds_read_b128 v[172:175], v225 offset:56320
	s_mov_b64 s[52:53], -1
	s_and_b64 vcc, exec, s[46:47]
	s_cbranch_vccz .LBB0_814
	s_lshl_b32 s2, s48, 7
	s_add_u32 s50, s95, s2
	s_addc_u32 s51, s94, 0
	s_mov_b64 s[52:53], 0

.LBB0_816:
	s_mov_b32 m0, s72
	v_lshl_add_u64 v[218:219], s[50:51], 0, v[218:219]
	global_load_lds_dwordx4 v[218:219], off
	s_mov_b32 m0, s73
	v_lshl_add_u64 v[216:217], s[50:51], 0, v[216:217]
	global_load_lds_dwordx4 v[216:217], off
	s_barrier
	s_waitcnt lgkmcnt(0)
	s_setprio 1
	v_mfma_f32_16x16x32_bf16 v[8:11], v[136:139], v[176:179], v[8:11]
	v_mfma_f32_16x16x32_bf16 v[12:15], v[140:143], v[176:179], v[12:15]
	v_mfma_f32_16x16x32_bf16 v[24:27], v[136:139], v[180:183], v[24:27]
	v_mfma_f32_16x16x32_bf16 v[28:31], v[140:143], v[180:183], v[28:31]
	v_mfma_f32_16x16x32_bf16 v[216:219], v[136:139], v[184:187], v[40:43]
	v_mfma_f32_16x16x32_bf16 v[228:231], v[140:143], v[184:187], v[44:47]
	v_mfma_f32_16x16x32_bf16 v[136:139], v[136:139], v[188:191], v[56:59]
	v_mfma_f32_16x16x32_bf16 v[140:143], v[140:143], v[188:191], v[60:63]
	v_mfma_f32_16x16x32_bf16 v[60:63], v[128:131], v[160:163], v[8:11]
	v_mfma_f32_16x16x32_bf16 v[56:59], v[132:135], v[160:163], v[12:15]
	v_mfma_f32_16x16x32_bf16 v[44:47], v[128:131], v[164:167], v[24:27]
	v_mfma_f32_16x16x32_bf16 v[40:43], v[132:135], v[164:167], v[28:31]
	v_mfma_f32_16x16x32_bf16 v[28:31], v[128:131], v[168:171], v[216:219]
	v_mfma_f32_16x16x32_bf16 v[24:27], v[132:135], v[168:171], v[228:231]
	v_mfma_f32_16x16x32_bf16 v[12:15], v[128:131], v[172:175], v[136:139]
	v_mfma_f32_16x16x32_bf16 v[8:11], v[132:135], v[172:175], v[140:143]
	s_setprio 0
	s_barrier
	s_mov_b64 s[50:51], -1
	s_and_b64 vcc, exec, s[46:47]
	s_cbranch_vccz .LBB0_818
	s_mov_b32 s49, s3
	s_lshl_b64 s[46:47], s[48:49], 11
	s_sub_u32 s2, 0, s46
	s_subb_u32 s45, 0, s47
	s_add_u32 s2, s91, s2
	s_addc_u32 s45, s90, s45
	s_add_u32 s46, s2, 0x1000
	s_addc_u32 s47, s45, 0
	s_mov_b64 s[50:51], 0

;     ...
;         G_PAIR(0, 1);
; #pragma unroll 1
;         for (int t = 2; t < nt; t += 2) G_PAIR(t, 0);
.LBB0_820:
	s_mov_b32 m0, s74
	v_lshl_add_u64 v[128:129], s[46:47], 0, v[214:215]
	global_load_lds_dwordx4 v[128:129], off
	s_mov_b32 m0, s75
	v_lshl_add_u64 v[128:129], s[46:47], 0, v[212:213]
	global_load_lds_dwordx4 v[128:129], off
	s_waitcnt vmcnt(6)
	s_barrier
	s_setprio 1
	v_mfma_f32_16x16x32_bf16 v[0:3], v[152:155], v[176:179], v[0:3]
	v_mfma_f32_16x16x32_bf16 v[4:7], v[156:159], v[176:179], v[4:7]
	v_mfma_f32_16x16x32_bf16 v[16:19], v[152:155], v[180:183], v[16:19]
	v_mfma_f32_16x16x32_bf16 v[20:23], v[156:159], v[180:183], v[20:23]
	v_mfma_f32_16x16x32_bf16 v[128:131], v[152:155], v[184:187], v[32:35]
	v_mfma_f32_16x16x32_bf16 v[132:135], v[156:159], v[184:187], v[36:39]
	v_mfma_f32_16x16x32_bf16 v[136:139], v[152:155], v[188:191], v[48:51]
	v_mfma_f32_16x16x32_bf16 v[140:143], v[156:159], v[188:191], v[52:55]
	v_mfma_f32_16x16x32_bf16 v[52:55], v[144:147], v[160:163], v[0:3]
	v_mfma_f32_16x16x32_bf16 v[48:51], v[148:151], v[160:163], v[4:7]
	v_mfma_f32_16x16x32_bf16 v[36:39], v[144:147], v[164:167], v[16:19]
	v_mfma_f32_16x16x32_bf16 v[32:35], v[148:151], v[164:167], v[20:23]
	v_mfma_f32_16x16x32_bf16 v[20:23], v[144:147], v[168:171], v[128:131]
	v_mfma_f32_16x16x32_bf16 v[16:19], v[148:151], v[168:171], v[132:135]
	v_mfma_f32_16x16x32_bf16 v[4:7], v[144:147], v[172:175], v[136:139]
	v_mfma_f32_16x16x32_bf16 v[0:3], v[148:151], v[172:175], v[140:143]
	s_setprio 0
	s_add_u32 s42, s42, 0x100
	s_addc_u32 s43, s43, 0
	s_add_i32 s85, s85, 2
	s_cmp_gt_u32 s86, 17
	s_barrier
	s_cbranch_scc1 .LBB0_786
	s_mov_b32 s86, s87
	s_branch .LBB0_790

.LBB0_919:
	s_ashr_i32 s19, s18, 31
	s_waitcnt lgkmcnt(0)
	ds_read_b128 v[0:3], v172
	ds_read_b128 v[4:7], v172 offset:1024
	ds_read_b128 v[8:11], v172 offset:2048
	ds_read_b128 v[12:15], v172 offset:3072
	s_lshl_b64 s[20:21], s[18:19], 19
	s_add_u32 s20, s37, s20
	s_addc_u32 s21, s38, s21
	s_ashr_i32 s17, s16, 31
	s_lshl_b64 s[22:23], s[16:17], 19
	s_add_u32 s22, s39, s22
	s_addc_u32 s23, s40, s23
	s_add_u32 s30, s24, 0x40080
	s_addc_u32 s31, s25, 0
	s_mov_b32 m0, s48
	v_lshl_add_u64 v[48:49], s[30:31], 0, v[146:147]
	ds_read_b128 v[16:19], v173
	ds_read_b128 v[20:23], v173 offset:1024
	ds_read_b128 v[24:27], v173 offset:2048
	ds_read_b128 v[28:31], v173 offset:3072
	ds_read_b128 v[32:35], v173 offset:4096
	ds_read_b128 v[36:39], v173 offset:5120
	ds_read_b128 v[40:43], v173 offset:6144
	ds_read_b128 v[44:47], v173 offset:7168
	global_load_lds_dwordx4 v[48:49], off
	s_mov_b32 m0, s49
	v_lshl_add_u64 v[48:49], s[30:31], 0, v[142:143]
	global_load_lds_dwordx4 v[48:49], off
	s_waitcnt lgkmcnt(8)
	s_barrier
	s_waitcnt lgkmcnt(0)
	s_setprio 1
	v_mfma_f32_16x16x32_bf16 v[48:51], v[0:3], v[16:19], 0
	v_mfma_f32_16x16x32_bf16 v[52:55], v[8:11], v[16:19], 0
	v_mfma_f32_16x16x32_bf16 v[56:59], v[0:3], v[24:27], 0
	v_mfma_f32_16x16x32_bf16 v[60:63], v[8:11], v[24:27], 0
	v_mfma_f32_16x16x32_bf16 v[64:67], v[0:3], v[32:35], 0
	v_mfma_f32_16x16x32_bf16 v[68:71], v[8:11], v[32:35], 0
	v_mfma_f32_16x16x32_bf16 v[72:75], v[0:3], v[40:43], 0
	v_mfma_f32_16x16x32_bf16 v[76:79], v[8:11], v[40:43], 0
	v_mfma_f32_16x16x32_bf16 v[48:51], v[4:7], v[20:23], v[48:51]
	v_mfma_f32_16x16x32_bf16 v[52:55], v[12:15], v[20:23], v[52:55]
	v_mfma_f32_16x16x32_bf16 v[56:59], v[4:7], v[28:31], v[56:59]
	v_mfma_f32_16x16x32_bf16 v[60:63], v[12:15], v[28:31], v[60:63]
	v_mfma_f32_16x16x32_bf16 v[64:67], v[4:7], v[36:39], v[64:67]
	v_mfma_f32_16x16x32_bf16 v[68:71], v[12:15], v[36:39], v[68:71]
	v_mfma_f32_16x16x32_bf16 v[72:75], v[4:7], v[44:47], v[72:75]
	v_mfma_f32_16x16x32_bf16 v[76:79], v[12:15], v[44:47], v[76:79]
	s_setprio 0
	s_barrier
	v_lshl_add_u64 v[168:169], s[26:27], 0, v[144:145]
	s_mov_b32 m0, s50
	v_lshl_add_u64 v[96:97], v[168:169], 0, s[10:11]
	v_lshl_add_u64 v[218:219], s[26:27], 0, v[140:141]
	ds_read_b128 v[80:83], v174
	ds_read_b128 v[84:87], v174 offset:1024
	ds_read_b128 v[88:91], v174 offset:2048
	ds_read_b128 v[92:95], v174 offset:3072
	global_load_lds_dwordx4 v[96:97], off
	s_mov_b32 m0, s51
	v_lshl_add_u64 v[96:97], v[218:219], 0, s[10:11]
	global_load_lds_dwordx4 v[96:97], off
	s_barrier
	s_waitcnt lgkmcnt(0)
	s_setprio 1
	v_mfma_f32_16x16x32_bf16 v[96:99], v[80:83], v[16:19], 0
	v_mfma_f32_16x16x32_bf16 v[16:19], v[88:91], v[16:19], 0
	v_mfma_f32_16x16x32_bf16 v[100:103], v[80:83], v[24:27], 0
	v_mfma_f32_16x16x32_bf16 v[24:27], v[88:91], v[24:27], 0
	v_mfma_f32_16x16x32_bf16 v[104:107], v[80:83], v[32:35], 0
	v_mfma_f32_16x16x32_bf16 v[32:35], v[88:91], v[32:35], 0
	v_mfma_f32_16x16x32_bf16 v[108:111], v[80:83], v[40:43], 0
	v_mfma_f32_16x16x32_bf16 v[40:43], v[88:91], v[40:43], 0
	v_mfma_f32_16x16x32_bf16 v[120:123], v[84:87], v[20:23], v[96:99]
	v_mfma_f32_16x16x32_bf16 v[16:19], v[92:95], v[20:23], v[16:19]
	v_mfma_f32_16x16x32_bf16 v[20:23], v[84:87], v[28:31], v[100:103]
	v_mfma_f32_16x16x32_bf16 v[24:27], v[92:95], v[28:31], v[24:27]
	v_mfma_f32_16x16x32_bf16 v[28:31], v[84:87], v[36:39], v[104:107]
	v_mfma_f32_16x16x32_bf16 v[32:35], v[92:95], v[36:39], v[32:35]
	v_mfma_f32_16x16x32_bf16 v[36:39], v[84:87], v[44:47], v[108:111]
	v_mfma_f32_16x16x32_bf16 v[40:43], v[92:95], v[44:47], v[40:43]
	s_setprio 0
	v_lshl_add_u64 v[242:243], s[24:25], 0, v[146:147]
	s_mov_b32 m0, s41
	v_lshl_add_u64 v[128:129], v[242:243], 0, s[10:11]
	v_lshl_add_u64 v[244:245], s[24:25], 0, v[142:143]
	s_barrier
	ds_read_b128 v[44:47], v173 offset:16384
	ds_read_b128 v[96:99], v173 offset:17408
	ds_read_b128 v[100:103], v173 offset:18432
	ds_read_b128 v[104:107], v173 offset:19456
	ds_read_b128 v[108:111], v173 offset:20480
	ds_read_b128 v[112:115], v173 offset:21504
	ds_read_b128 v[116:119], v173 offset:22528
	ds_read_b128 v[124:127], v173 offset:23552
	global_load_lds_dwordx4 v[128:129], off
	s_mov_b32 m0, s42
	v_lshl_add_u64 v[128:129], v[244:245], 0, s[10:11]
	global_load_lds_dwordx4 v[128:129], off
	s_barrier
	s_waitcnt lgkmcnt(0)
	s_setprio 1
	v_mfma_f32_16x16x32_bf16 v[128:131], v[0:3], v[44:47], 0
	v_mfma_f32_16x16x32_bf16 v[132:135], v[8:11], v[44:47], 0
	v_mfma_f32_16x16x32_bf16 v[136:139], v[0:3], v[100:103], 0
	v_mfma_f32_16x16x32_bf16 v[152:155], v[8:11], v[100:103], 0
	v_mfma_f32_16x16x32_bf16 v[156:159], v[0:3], v[108:111], 0
	v_mfma_f32_16x16x32_bf16 v[160:163], v[8:11], v[108:111], 0
	v_mfma_f32_16x16x32_bf16 v[0:3], v[0:3], v[116:119], 0
	v_mfma_f32_16x16x32_bf16 v[8:11], v[8:11], v[116:119], 0
	v_mfma_f32_16x16x32_bf16 v[164:167], v[4:7], v[96:99], v[128:131]
	v_mfma_f32_16x16x32_bf16 v[136:139], v[4:7], v[104:107], v[136:139]
	v_mfma_f32_16x16x32_bf16 v[156:159], v[4:7], v[112:115], v[156:159]
	v_mfma_f32_16x16x32_bf16 v[0:3], v[4:7], v[124:127], v[0:3]
	v_mfma_f32_16x16x32_bf16 v[4:7], v[12:15], v[124:127], v[8:11]
	v_mfma_f32_16x16x32_bf16 v[132:135], v[12:15], v[96:99], v[132:135]
	v_mfma_f32_16x16x32_bf16 v[152:155], v[12:15], v[104:107], v[152:155]
	v_mfma_f32_16x16x32_bf16 v[160:163], v[12:15], v[112:115], v[160:163]
	s_setprio 0
	s_barrier
	s_add_u32 s30, s26, 0x40100
	s_addc_u32 s31, s27, 0
	s_mov_b32 m0, s52
	v_lshl_add_u64 v[8:9], s[30:31], 0, v[144:145]
	global_load_lds_dwordx4 v[8:9], off
	s_mov_b32 m0, s53
	v_lshl_add_u64 v[8:9], s[30:31], 0, v[140:141]
	global_load_lds_dwordx4 v[8:9], off
	s_waitcnt vmcnt(6)
	s_barrier
	s_setprio 1
	v_mfma_f32_16x16x32_bf16 v[8:11], v[80:83], v[44:47], 0
	v_mfma_f32_16x16x32_bf16 v[12:15], v[88:91], v[44:47], 0
	v_mfma_f32_16x16x32_bf16 v[44:47], v[80:83], v[100:103], 0
	v_mfma_f32_16x16x32_bf16 v[100:103], v[88:91], v[100:103], 0
	v_mfma_f32_16x16x32_bf16 v[128:131], v[80:83], v[108:111], 0
	v_mfma_f32_16x16x32_bf16 v[108:111], v[88:91], v[108:111], 0
	v_mfma_f32_16x16x32_bf16 v[80:83], v[80:83], v[116:119], 0
	v_mfma_f32_16x16x32_bf16 v[88:91], v[88:91], v[116:119], 0
	v_mfma_f32_16x16x32_bf16 v[8:11], v[84:87], v[96:99], v[8:11]
	v_mfma_f32_16x16x32_bf16 v[12:15], v[92:95], v[96:99], v[12:15]
	v_mfma_f32_16x16x32_bf16 v[44:47], v[84:87], v[104:107], v[44:47]
	v_mfma_f32_16x16x32_bf16 v[178:181], v[92:95], v[104:107], v[100:103]
	v_mfma_f32_16x16x32_bf16 v[182:185], v[84:87], v[112:115], v[128:131]
	v_mfma_f32_16x16x32_bf16 v[186:189], v[92:95], v[112:115], v[108:111]
	v_mfma_f32_16x16x32_bf16 v[190:193], v[84:87], v[124:127], v[80:83]
	v_mfma_f32_16x16x32_bf16 v[194:197], v[92:95], v[124:127], v[88:91]
	s_setprio 0
	s_barrier
	ds_read_b128 v[198:201], v176
	ds_read_b128 v[202:205], v176 offset:1024
	ds_read_b128 v[206:209], v176 offset:2048
	ds_read_b128 v[210:213], v176 offset:3072
	s_add_u32 s30, s24, 0x40100
	s_addc_u32 s31, s25, 0
	s_mov_b32 m0, s43
	v_lshl_add_u64 v[80:81], s[30:31], 0, v[146:147]
	ds_read_b128 v[88:91], v173 offset:32768
	ds_read_b128 v[92:95], v173 offset:33792
	ds_read_b128 v[104:107], v173 offset:34816
	ds_read_b128 v[214:217], v173 offset:35840
	ds_read_b128 v[108:111], v173 offset:36864
	ds_read_b128 v[222:225], v173 offset:37888
	ds_read_b128 v[124:127], v173 offset:38912
	ds_read_b128 v[226:229], v173 offset:39936
	global_load_lds_dwordx4 v[80:81], off
	s_mov_b32 m0, s44
	v_lshl_add_u64 v[80:81], s[30:31], 0, v[142:143]
	global_load_lds_dwordx4 v[80:81], off
	s_waitcnt lgkmcnt(8)
	s_barrier
	s_waitcnt lgkmcnt(0)
	s_setprio 1
	v_mfma_f32_16x16x32_bf16 v[48:51], v[198:201], v[88:91], v[48:51]
	v_mfma_f32_16x16x32_bf16 v[52:55], v[206:209], v[88:91], v[52:55]
	v_mfma_f32_16x16x32_bf16 v[56:59], v[198:201], v[104:107], v[56:59]
	v_mfma_f32_16x16x32_bf16 v[60:63], v[206:209], v[104:107], v[60:63]
	v_mfma_f32_16x16x32_bf16 v[64:67], v[198:201], v[108:111], v[64:67]
	v_mfma_f32_16x16x32_bf16 v[68:71], v[206:209], v[108:111], v[68:71]
	v_mfma_f32_16x16x32_bf16 v[72:75], v[198:201], v[124:127], v[72:75]
	v_mfma_f32_16x16x32_bf16 v[76:79], v[206:209], v[124:127], v[76:79]
	v_mfma_f32_16x16x32_bf16 v[116:119], v[202:205], v[92:95], v[48:51]
	v_mfma_f32_16x16x32_bf16 v[112:115], v[210:213], v[92:95], v[52:55]
	v_mfma_f32_16x16x32_bf16 v[100:103], v[202:205], v[214:217], v[56:59]
	v_mfma_f32_16x16x32_bf16 v[96:99], v[210:213], v[214:217], v[60:63]
	v_mfma_f32_16x16x32_bf16 v[84:87], v[202:205], v[222:225], v[64:67]
	v_mfma_f32_16x16x32_bf16 v[80:83], v[210:213], v[222:225], v[68:71]
	v_mfma_f32_16x16x32_bf16 v[68:71], v[202:205], v[226:229], v[72:75]
	v_mfma_f32_16x16x32_bf16 v[64:67], v[210:213], v[226:229], v[76:79]
	s_setprio 0
	s_barrier
	s_mov_b32 m0, s54
	v_lshl_add_u64 v[48:49], v[168:169], 0, s[12:13]
	ds_read_b128 v[56:59], v177
	ds_read_b128 v[230:233], v177 offset:1024
	ds_read_b128 v[60:63], v177 offset:2048
	ds_read_b128 v[234:237], v177 offset:3072
	global_load_lds_dwordx4 v[48:49], off
	s_mov_b32 m0, s55
	v_lshl_add_u64 v[48:49], v[218:219], 0, s[12:13]
	global_load_lds_dwordx4 v[48:49], off
	s_barrier
	s_waitcnt lgkmcnt(0)
	s_setprio 1
	v_mfma_f32_16x16x32_bf16 v[48:51], v[56:59], v[88:91], v[120:123]
	v_mfma_f32_16x16x32_bf16 v[16:19], v[60:63], v[88:91], v[16:19]
	v_mfma_f32_16x16x32_bf16 v[20:23], v[56:59], v[104:107], v[20:23]
	v_mfma_f32_16x16x32_bf16 v[24:27], v[60:63], v[104:107], v[24:27]
	v_mfma_f32_16x16x32_bf16 v[28:31], v[56:59], v[108:111], v[28:31]
	v_mfma_f32_16x16x32_bf16 v[32:35], v[60:63], v[108:111], v[32:35]
	v_mfma_f32_16x16x32_bf16 v[36:39], v[56:59], v[124:127], v[36:39]
	v_mfma_f32_16x16x32_bf16 v[40:43], v[60:63], v[124:127], v[40:43]
	v_mfma_f32_16x16x32_bf16 v[128:131], v[230:233], v[92:95], v[48:51]
	v_mfma_f32_16x16x32_bf16 v[124:127], v[234:237], v[92:95], v[16:19]
	v_mfma_f32_16x16x32_bf16 v[108:111], v[230:233], v[214:217], v[20:23]
	v_mfma_f32_16x16x32_bf16 v[104:107], v[234:237], v[214:217], v[24:27]
	v_mfma_f32_16x16x32_bf16 v[92:95], v[230:233], v[222:225], v[28:31]
	v_mfma_f32_16x16x32_bf16 v[88:91], v[234:237], v[222:225], v[32:35]
	v_mfma_f32_16x16x32_bf16 v[76:79], v[230:233], v[226:229], v[36:39]
	v_mfma_f32_16x16x32_bf16 v[72:75], v[234:237], v[226:229], v[40:43]
	s_setprio 0
	s_mov_b32 m0, s46
	v_lshl_add_u64 v[16:17], v[242:243], 0, s[12:13]
	s_barrier
	ds_read_b128 v[24:27], v173 offset:49152
	ds_read_b128 v[28:31], v173 offset:50176
	ds_read_b128 v[40:43], v173 offset:51200
	ds_read_b128 v[120:123], v173 offset:52224
	ds_read_b128 v[214:217], v173 offset:53248
	ds_read_b128 v[222:225], v173 offset:54272
	ds_read_b128 v[226:229], v173 offset:55296
	ds_read_b128 v[238:241], v173 offset:56320
	global_load_lds_dwordx4 v[16:17], off
	s_mov_b32 m0, s47
	v_lshl_add_u64 v[16:17], v[244:245], 0, s[12:13]
	global_load_lds_dwordx4 v[16:17], off
	s_barrier
;     __device__ __forceinline__ bool unit(int L, Unit& u) const { u.g = L; return order_mn(L, T / 256, NGU / 256, u.pm, u.pn); }
;     __device__ __forceinline__ bool unit(int L, Unit& u) const { u.g = L; return order_mn(L, T / 256, D / 256, u.pm, u.pn); }
;     __device__ __forceinline__ bool unit(int L, Unit& u) const { u.g = 0; return order_mn(L, T / 256, 8, u.pm, u.pn); }
;     __device__ __forceinline__ bool unit(int L, Unit& u) const { if (L >= NG * 4) return false; u.g = L >> 2; u.pm = (L >> 1) & 1; u.pn = L & 1; return true; }
;     __device__ __forceinline__ bool unit(int L, Unit& u) const { if (L >= NG * 8) return false; u.g = L >> 3; u.pm = (L >> 2) & 1; u.pn = L & 3; return true; }
;     ...
;         const bool has_next = p.unit((ui + 1) * G + c, nxt);
;         const char* nA = has_next ? p.a0(nxt) : cA; const char* nB = has_next ? p.b0(nxt) : cB;
;         const char* nA2 = P::SEG ? (has_next ? p.a1(nxt) : cA2) : nA; const char* nB2 = P::SEG ? (has_next ? p.b1(nxt) : cB2) : nB;
	s_waitcnt lgkmcnt(0)
	s_setprio 1
	v_mfma_f32_16x16x32_bf16 v[16:19], v[198:201], v[24:27], v[164:167]
	v_mfma_f32_16x16x32_bf16 v[20:23], v[206:209], v[24:27], v[132:135]
	v_mfma_f32_16x16x32_bf16 v[32:35], v[198:201], v[40:43], v[136:139]
	v_mfma_f32_16x16x32_bf16 v[132:135], v[206:209], v[40:43], v[152:155]
	v_mfma_f32_16x16x32_bf16 v[136:139], v[198:201], v[214:217], v[156:159]
	v_mfma_f32_16x16x32_bf16 v[152:155], v[206:209], v[214:217], v[160:163]
	v_mfma_f32_16x16x32_bf16 v[0:3], v[198:201], v[226:229], v[0:3]
	v_mfma_f32_16x16x32_bf16 v[156:159], v[206:209], v[226:229], v[4:7]
	v_mfma_f32_16x16x32_bf16 v[52:55], v[202:205], v[28:31], v[16:19]
	v_mfma_f32_16x16x32_bf16 v[48:51], v[210:213], v[28:31], v[20:23]
	v_mfma_f32_16x16x32_bf16 v[36:39], v[202:205], v[120:123], v[32:35]
	v_mfma_f32_16x16x32_bf16 v[32:35], v[210:213], v[120:123], v[132:135]
	v_mfma_f32_16x16x32_bf16 v[20:23], v[202:205], v[222:225], v[136:139]
	v_mfma_f32_16x16x32_bf16 v[16:19], v[210:213], v[222:225], v[152:155]
	v_mfma_f32_16x16x32_bf16 v[4:7], v[202:205], v[238:241], v[0:3]
	v_mfma_f32_16x16x32_bf16 v[0:3], v[210:213], v[238:241], v[156:159]
	s_setprio 0
	s_barrier
	s_add_u32 s30, s26, 0x40180
	s_addc_u32 s31, s27, 0
	s_mov_b32 m0, s56
	v_lshl_add_u64 v[132:133], s[30:31], 0, v[144:145]
	global_load_lds_dwordx4 v[132:133], off
	v_lshl_add_u64 v[132:133], s[30:31], 0, v[140:141]
	s_mov_b32 m0, s57
	s_mov_b64 s[30:31], 0x40180
	global_load_lds_dwordx4 v[132:133], off
	s_waitcnt vmcnt(6)
	s_barrier
	s_setprio 1
	v_mfma_f32_16x16x32_bf16 v[8:11], v[56:59], v[24:27], v[8:11]
	v_mfma_f32_16x16x32_bf16 v[12:15], v[60:63], v[24:27], v[12:15]
	v_mfma_f32_16x16x32_bf16 v[24:27], v[56:59], v[40:43], v[44:47]
	v_mfma_f32_16x16x32_bf16 v[40:43], v[60:63], v[40:43], v[178:181]
	v_mfma_f32_16x16x32_bf16 v[132:135], v[56:59], v[214:217], v[182:185]
	v_mfma_f32_16x16x32_bf16 v[136:139], v[60:63], v[214:217], v[186:189]
	v_mfma_f32_16x16x32_bf16 v[152:155], v[56:59], v[226:229], v[190:193]
	v_mfma_f32_16x16x32_bf16 v[156:159], v[60:63], v[226:229], v[194:197]
	v_mfma_f32_16x16x32_bf16 v[60:63], v[230:233], v[28:31], v[8:11]
	v_mfma_f32_16x16x32_bf16 v[56:59], v[234:237], v[28:31], v[12:15]
	v_mfma_f32_16x16x32_bf16 v[44:47], v[230:233], v[120:123], v[24:27]
	v_mfma_f32_16x16x32_bf16 v[40:43], v[234:237], v[120:123], v[40:43]
	v_mfma_f32_16x16x32_bf16 v[28:31], v[230:233], v[222:225], v[132:135]
	v_mfma_f32_16x16x32_bf16 v[24:27], v[234:237], v[222:225], v[136:139]
	v_mfma_f32_16x16x32_bf16 v[12:15], v[230:233], v[238:241], v[152:155]
	v_mfma_f32_16x16x32_bf16 v[8:11], v[234:237], v[238:241], v[156:159]
	s_setprio 0
	v_lshl_add_u64 v[120:121], s[24:25], 0, v[148:149]
	v_lshl_add_u64 v[122:123], s[24:25], 0, v[150:151]
	s_mov_b32 s17, 0
	s_barrier
.LBB0_920:
	ds_read_b128 v[132:135], v172
	ds_read_b128 v[136:139], v172 offset:1024
	ds_read_b128 v[152:155], v172 offset:2048
	ds_read_b128 v[156:159], v172 offset:3072
	s_mov_b32 m0, s48
	v_lshl_add_u64 v[168:169], v[120:121], 0, s[30:31]
	ds_read_b128 v[160:163], v173
	ds_read_b128 v[164:167], v173 offset:1024
	ds_read_b128 v[178:181], v173 offset:2048
	ds_read_b128 v[182:185], v173 offset:3072
	ds_read_b128 v[186:189], v173 offset:4096
	ds_read_b128 v[190:193], v173 offset:5120
	ds_read_b128 v[194:197], v173 offset:6144
	ds_read_b128 v[198:201], v173 offset:7168
	global_load_lds_dwordx4 v[168:169], off
	s_mov_b32 m0, s49
	v_lshl_add_u64 v[168:169], v[122:123], 0, s[30:31]
	global_load_lds_dwordx4 v[168:169], off
	s_waitcnt lgkmcnt(8)
	s_barrier
	s_waitcnt lgkmcnt(0)
	s_setprio 1
	v_mfma_f32_16x16x32_bf16 v[116:119], v[132:135], v[160:163], v[116:119]
	s_add_i32 s19, s30, 0xfffc0080
	v_mfma_f32_16x16x32_bf16 v[112:115], v[152:155], v[160:163], v[112:115]
	s_cmp_eq_u32 s17, 12
	v_mfma_f32_16x16x32_bf16 v[100:103], v[132:135], v[178:181], v[100:103]
	s_cselect_b64 s[34:35], -1, 0
	v_mfma_f32_16x16x32_bf16 v[96:99], v[152:155], v[178:181], v[96:99]
	s_and_b64 s[60:61], s[34:35], exec
	v_mfma_f32_16x16x32_bf16 v[84:87], v[132:135], v[186:189], v[84:87]
	s_cselect_b32 s19, 0, s19
	v_mfma_f32_16x16x32_bf16 v[80:83], v[152:155], v[186:189], v[80:83]
	s_and_b64 s[34:35], s[28:29], s[34:35]
	v_mfma_f32_16x16x32_bf16 v[68:71], v[132:135], v[194:197], v[68:71]
	s_and_b64 s[34:35], s[34:35], exec
	v_mfma_f32_16x16x32_bf16 v[64:67], v[152:155], v[194:197], v[64:67]
	s_cselect_b32 s61, s21, s25
	v_mfma_f32_16x16x32_bf16 v[116:119], v[136:139], v[164:167], v[116:119]
	s_cselect_b32 s60, s20, s24
	v_mfma_f32_16x16x32_bf16 v[112:115], v[156:159], v[164:167], v[112:115]
	s_cselect_b32 s35, s23, s27
	v_mfma_f32_16x16x32_bf16 v[100:103], v[136:139], v[182:185], v[100:103]
	s_cselect_b32 s34, s22, s26
	v_mfma_f32_16x16x32_bf16 v[96:99], v[156:159], v[182:185], v[96:99]
	v_mfma_f32_16x16x32_bf16 v[84:87], v[136:139], v[190:193], v[84:87]
	v_mfma_f32_16x16x32_bf16 v[80:83], v[156:159], v[190:193], v[80:83]
	v_mfma_f32_16x16x32_bf16 v[68:71], v[136:139], v[198:201], v[68:71]
	v_mfma_f32_16x16x32_bf16 v[64:67], v[156:159], v[198:201], v[64:67]
	s_setprio 0
	s_barrier
	s_add_u32 s34, s34, s19
	s_addc_u32 s35, s35, 0
	s_mov_b32 m0, s50
	v_lshl_add_u64 v[168:169], s[34:35], 0, v[144:145]
	ds_read_b128 v[202:205], v174
	ds_read_b128 v[206:209], v174 offset:1024
	ds_read_b128 v[210:213], v174 offset:2048
	ds_read_b128 v[214:217], v174 offset:3072
	global_load_lds_dwordx4 v[168:169], off
	s_mov_b32 m0, s51
	v_lshl_add_u64 v[218:219], s[34:35], 0, v[140:141]
	global_load_lds_dwordx4 v[218:219], off
	s_barrier
	s_waitcnt lgkmcnt(0)
	s_setprio 1
	v_mfma_f32_16x16x32_bf16 v[128:131], v[202:205], v[160:163], v[128:131]
	v_mfma_f32_16x16x32_bf16 v[124:127], v[210:213], v[160:163], v[124:127]
	v_mfma_f32_16x16x32_bf16 v[108:111], v[202:205], v[178:181], v[108:111]
	v_mfma_f32_16x16x32_bf16 v[104:107], v[210:213], v[178:181], v[104:107]
	v_mfma_f32_16x16x32_bf16 v[92:95], v[202:205], v[186:189], v[92:95]
	v_mfma_f32_16x16x32_bf16 v[88:91], v[210:213], v[186:189], v[88:91]
	v_mfma_f32_16x16x32_bf16 v[76:79], v[202:205], v[194:197], v[76:79]
	v_mfma_f32_16x16x32_bf16 v[72:75], v[210:213], v[194:197], v[72:75]
	v_mfma_f32_16x16x32_bf16 v[128:131], v[206:209], v[164:167], v[128:131]
	v_mfma_f32_16x16x32_bf16 v[124:127], v[214:217], v[164:167], v[124:127]
	v_mfma_f32_16x16x32_bf16 v[108:111], v[206:209], v[182:185], v[108:111]
	v_mfma_f32_16x16x32_bf16 v[104:107], v[214:217], v[182:185], v[104:107]
	v_mfma_f32_16x16x32_bf16 v[92:95], v[206:209], v[190:193], v[92:95]
	v_mfma_f32_16x16x32_bf16 v[88:91], v[214:217], v[190:193], v[88:91]
	v_mfma_f32_16x16x32_bf16 v[76:79], v[206:209], v[198:201], v[76:79]
	v_mfma_f32_16x16x32_bf16 v[72:75], v[214:217], v[198:201], v[72:75]
	s_setprio 0
	s_add_u32 s60, s60, s19
	s_addc_u32 s61, s61, 0
	s_mov_b32 m0, s41
	v_lshl_add_u64 v[222:223], s[60:61], 0, v[146:147]
	s_barrier
	ds_read_b128 v[160:163], v173 offset:16384
	ds_read_b128 v[164:167], v173 offset:17408
	ds_read_b128 v[178:181], v173 offset:18432
	ds_read_b128 v[182:185], v173 offset:19456
	ds_read_b128 v[186:189], v173 offset:20480
	ds_read_b128 v[190:193], v173 offset:21504
	ds_read_b128 v[194:197], v173 offset:22528
	ds_read_b128 v[198:201], v173 offset:23552
	global_load_lds_dwordx4 v[222:223], off
	s_mov_b32 m0, s42
	v_lshl_add_u64 v[224:225], s[60:61], 0, v[142:143]
	global_load_lds_dwordx4 v[224:225], off
	s_barrier
	s_waitcnt lgkmcnt(0)
	s_setprio 1
	v_mfma_f32_16x16x32_bf16 v[52:55], v[132:135], v[160:163], v[52:55]
	v_mfma_f32_16x16x32_bf16 v[48:51], v[152:155], v[160:163], v[48:51]
	v_mfma_f32_16x16x32_bf16 v[36:39], v[132:135], v[178:181], v[36:39]
	v_mfma_f32_16x16x32_bf16 v[32:35], v[152:155], v[178:181], v[32:35]
	v_mfma_f32_16x16x32_bf16 v[20:23], v[132:135], v[186:189], v[20:23]
	v_mfma_f32_16x16x32_bf16 v[16:19], v[152:155], v[186:189], v[16:19]
	v_mfma_f32_16x16x32_bf16 v[4:7], v[132:135], v[194:197], v[4:7]
	v_mfma_f32_16x16x32_bf16 v[0:3], v[152:155], v[194:197], v[0:3]
	v_mfma_f32_16x16x32_bf16 v[52:55], v[136:139], v[164:167], v[52:55]
	v_mfma_f32_16x16x32_bf16 v[48:51], v[156:159], v[164:167], v[48:51]
	v_mfma_f32_16x16x32_bf16 v[36:39], v[136:139], v[182:185], v[36:39]
	v_mfma_f32_16x16x32_bf16 v[32:35], v[156:159], v[182:185], v[32:35]
	v_mfma_f32_16x16x32_bf16 v[20:23], v[136:139], v[190:193], v[20:23]
	v_mfma_f32_16x16x32_bf16 v[16:19], v[156:159], v[190:193], v[16:19]
	v_mfma_f32_16x16x32_bf16 v[4:7], v[136:139], v[198:201], v[4:7]
	v_mfma_f32_16x16x32_bf16 v[0:3], v[156:159], v[198:201], v[0:3]
	s_setprio 0
	s_barrier
	s_add_u32 s62, s34, 0x40000
	s_addc_u32 s63, s35, 0
	s_mov_b32 m0, s52
	v_lshl_add_u64 v[132:133], s[62:63], 0, v[144:145]
	global_load_lds_dwordx4 v[132:133], off
	s_mov_b32 m0, s53
	v_lshl_add_u64 v[132:133], s[62:63], 0, v[140:141]
	global_load_lds_dwordx4 v[132:133], off
	s_waitcnt vmcnt(6)
	s_barrier
	s_setprio 1
	v_mfma_f32_16x16x32_bf16 v[60:63], v[202:205], v[160:163], v[60:63]
	v_mfma_f32_16x16x32_bf16 v[56:59], v[210:213], v[160:163], v[56:59]
	v_mfma_f32_16x16x32_bf16 v[44:47], v[202:205], v[178:181], v[44:47]
	v_mfma_f32_16x16x32_bf16 v[40:43], v[210:213], v[178:181], v[40:43]
	v_mfma_f32_16x16x32_bf16 v[28:31], v[202:205], v[186:189], v[28:31]
	v_mfma_f32_16x16x32_bf16 v[24:27], v[210:213], v[186:189], v[24:27]
	v_mfma_f32_16x16x32_bf16 v[12:15], v[202:205], v[194:197], v[12:15]
	v_mfma_f32_16x16x32_bf16 v[8:11], v[210:213], v[194:197], v[8:11]
	v_mfma_f32_16x16x32_bf16 v[60:63], v[206:209], v[164:167], v[60:63]
	v_mfma_f32_16x16x32_bf16 v[56:59], v[214:217], v[164:167], v[56:59]
	v_mfma_f32_16x16x32_bf16 v[44:47], v[206:209], v[182:185], v[44:47]
	v_mfma_f32_16x16x32_bf16 v[40:43], v[214:217], v[182:185], v[40:43]
	v_mfma_f32_16x16x32_bf16 v[28:31], v[206:209], v[190:193], v[28:31]
	v_mfma_f32_16x16x32_bf16 v[24:27], v[214:217], v[190:193], v[24:27]
	v_mfma_f32_16x16x32_bf16 v[12:15], v[206:209], v[198:201], v[12:15]
	v_mfma_f32_16x16x32_bf16 v[8:11], v[214:217], v[198:201], v[8:11]
	s_setprio 0
	s_barrier
	ds_read_b128 v[132:135], v176
	ds_read_b128 v[136:139], v176 offset:1024
	ds_read_b128 v[152:155], v176 offset:2048
	ds_read_b128 v[156:159], v176 offset:3072
	s_add_u32 s60, s60, 0x40000
	s_addc_u32 s61, s61, 0
	s_mov_b32 m0, s43
	v_lshl_add_u64 v[202:203], s[60:61], 0, v[146:147]
	ds_read_b128 v[160:163], v173 offset:32768
	ds_read_b128 v[164:167], v173 offset:33792
	ds_read_b128 v[178:181], v173 offset:34816
	ds_read_b128 v[182:185], v173 offset:35840
	ds_read_b128 v[186:189], v173 offset:36864
	ds_read_b128 v[190:193], v173 offset:37888
	ds_read_b128 v[194:197], v173 offset:38912
	ds_read_b128 v[198:201], v173 offset:39936
	global_load_lds_dwordx4 v[202:203], off
	s_mov_b32 m0, s44
	v_lshl_add_u64 v[202:203], s[60:61], 0, v[142:143]
	global_load_lds_dwordx4 v[202:203], off
	s_waitcnt lgkmcnt(8)
	s_barrier
	s_waitcnt lgkmcnt(0)
	s_setprio 1
	v_mfma_f32_16x16x32_bf16 v[116:119], v[132:135], v[160:163], v[116:119]
	v_mfma_f32_16x16x32_bf16 v[112:115], v[152:155], v[160:163], v[112:115]
	v_mfma_f32_16x16x32_bf16 v[100:103], v[132:135], v[178:181], v[100:103]
	v_mfma_f32_16x16x32_bf16 v[96:99], v[152:155], v[178:181], v[96:99]
	v_mfma_f32_16x16x32_bf16 v[84:87], v[132:135], v[186:189], v[84:87]
	v_mfma_f32_16x16x32_bf16 v[80:83], v[152:155], v[186:189], v[80:83]
	v_mfma_f32_16x16x32_bf16 v[68:71], v[132:135], v[194:197], v[68:71]
	v_mfma_f32_16x16x32_bf16 v[64:67], v[152:155], v[194:197], v[64:67]
	v_mfma_f32_16x16x32_bf16 v[116:119], v[136:139], v[164:167], v[116:119]
	v_mfma_f32_16x16x32_bf16 v[112:115], v[156:159], v[164:167], v[112:115]
	v_mfma_f32_16x16x32_bf16 v[100:103], v[136:139], v[182:185], v[100:103]
	v_mfma_f32_16x16x32_bf16 v[96:99], v[156:159], v[182:185], v[96:99]
	v_mfma_f32_16x16x32_bf16 v[84:87], v[136:139], v[190:193], v[84:87]
	v_mfma_f32_16x16x32_bf16 v[80:83], v[156:159], v[190:193], v[80:83]
	v_mfma_f32_16x16x32_bf16 v[68:71], v[136:139], v[198:201], v[68:71]
	v_mfma_f32_16x16x32_bf16 v[64:67], v[156:159], v[198:201], v[64:67]
	s_setprio 0
	s_barrier
	s_mov_b32 m0, s54
	v_lshl_add_u64 v[168:169], v[168:169], 0, s[6:7]
	ds_read_b128 v[202:205], v177
	ds_read_b128 v[206:209], v177 offset:1024
	ds_read_b128 v[210:213], v177 offset:2048
	ds_read_b128 v[214:217], v177 offset:3072
	global_load_lds_dwordx4 v[168:169], off
	s_mov_b32 m0, s55
	v_lshl_add_u64 v[168:169], v[218:219], 0, s[6:7]
	global_load_lds_dwordx4 v[168:169], off
	s_barrier
	s_waitcnt lgkmcnt(0)
	s_setprio 1
	v_mfma_f32_16x16x32_bf16 v[128:131], v[202:205], v[160:163], v[128:131]
	v_mfma_f32_16x16x32_bf16 v[124:127], v[210:213], v[160:163], v[124:127]
	v_mfma_f32_16x16x32_bf16 v[108:111], v[202:205], v[178:181], v[108:111]
	v_mfma_f32_16x16x32_bf16 v[104:107], v[210:213], v[178:181], v[104:107]
	v_mfma_f32_16x16x32_bf16 v[92:95], v[202:205], v[186:189], v[92:95]
	v_mfma_f32_16x16x32_bf16 v[88:91], v[210:213], v[186:189], v[88:91]
	v_mfma_f32_16x16x32_bf16 v[76:79], v[202:205], v[194:197], v[76:79]
	v_mfma_f32_16x16x32_bf16 v[72:75], v[210:213], v[194:197], v[72:75]
	v_mfma_f32_16x16x32_bf16 v[128:131], v[206:209], v[164:167], v[128:131]
	v_mfma_f32_16x16x32_bf16 v[124:127], v[214:217], v[164:167], v[124:127]
	v_mfma_f32_16x16x32_bf16 v[108:111], v[206:209], v[182:185], v[108:111]
	v_mfma_f32_16x16x32_bf16 v[104:107], v[214:217], v[182:185], v[104:107]
	v_mfma_f32_16x16x32_bf16 v[92:95], v[206:209], v[190:193], v[92:95]
	v_mfma_f32_16x16x32_bf16 v[88:91], v[214:217], v[190:193], v[88:91]
	v_mfma_f32_16x16x32_bf16 v[76:79], v[206:209], v[198:201], v[76:79]
	v_mfma_f32_16x16x32_bf16 v[72:75], v[214:217], v[198:201], v[72:75]
	s_setprio 0
	s_mov_b32 m0, s46
	v_lshl_add_u64 v[168:169], v[222:223], 0, s[6:7]
	s_barrier
	ds_read_b128 v[160:163], v173 offset:49152
	ds_read_b128 v[164:167], v173 offset:50176
	ds_read_b128 v[178:181], v173 offset:51200
	ds_read_b128 v[182:185], v173 offset:52224
	ds_read_b128 v[186:189], v173 offset:53248
	ds_read_b128 v[190:193], v173 offset:54272
	ds_read_b128 v[194:197], v173 offset:55296
	ds_read_b128 v[198:201], v173 offset:56320
	global_load_lds_dwordx4 v[168:169], off
	s_mov_b32 m0, s47
	v_lshl_add_u64 v[168:169], v[224:225], 0, s[6:7]
	global_load_lds_dwordx4 v[168:169], off
	s_barrier
	s_waitcnt lgkmcnt(0)
	s_setprio 1
	v_mfma_f32_16x16x32_bf16 v[52:55], v[132:135], v[160:163], v[52:55]
	v_mfma_f32_16x16x32_bf16 v[48:51], v[152:155], v[160:163], v[48:51]
	v_mfma_f32_16x16x32_bf16 v[36:39], v[132:135], v[178:181], v[36:39]
	v_mfma_f32_16x16x32_bf16 v[32:35], v[152:155], v[178:181], v[32:35]
	v_mfma_f32_16x16x32_bf16 v[20:23], v[132:135], v[186:189], v[20:23]
	v_mfma_f32_16x16x32_bf16 v[16:19], v[152:155], v[186:189], v[16:19]
	v_mfma_f32_16x16x32_bf16 v[4:7], v[132:135], v[194:197], v[4:7]
	v_mfma_f32_16x16x32_bf16 v[0:3], v[152:155], v[194:197], v[0:3]
	v_mfma_f32_16x16x32_bf16 v[52:55], v[136:139], v[164:167], v[52:55]
	v_mfma_f32_16x16x32_bf16 v[48:51], v[156:159], v[164:167], v[48:51]
	v_mfma_f32_16x16x32_bf16 v[36:39], v[136:139], v[182:185], v[36:39]
	v_mfma_f32_16x16x32_bf16 v[32:35], v[156:159], v[182:185], v[32:35]
	v_mfma_f32_16x16x32_bf16 v[20:23], v[136:139], v[190:193], v[20:23]
	v_mfma_f32_16x16x32_bf16 v[16:19], v[156:159], v[190:193], v[16:19]
	v_mfma_f32_16x16x32_bf16 v[4:7], v[136:139], v[198:201], v[4:7]
	v_mfma_f32_16x16x32_bf16 v[0:3], v[156:159], v[198:201], v[0:3]
	s_setprio 0
	s_barrier
	s_add_u32 s34, s34, 0x40080
	s_addc_u32 s35, s35, 0
	s_mov_b32 m0, s56
	v_lshl_add_u64 v[132:133], s[34:35], 0, v[144:145]
	global_load_lds_dwordx4 v[132:133], off
	s_mov_b32 m0, s57
	v_lshl_add_u64 v[132:133], s[34:35], 0, v[140:141]
	global_load_lds_dwordx4 v[132:133], off
	s_waitcnt vmcnt(6)
	s_barrier
; __device__ __forceinline__ unsigned pk2(float lo, float hi) { unsigned r; asm volatile("v_cvt_pk_bf16_f32 %0, %1, %2" : "=v"(r) : "v"(lo), "v"(hi)); return r; }
; __device__ __forceinline__ unsigned pk2(float lo, float hi) { return f2bf(lo) | (f2bf(hi) << 16); }
; __device__ __forceinline__ float fast_sigmoid(float z) { return __builtin_amdgcn_rcpf(1.0f + __expf(-z)); }
;     ...
;         G_PAIR(0, 1);
; #pragma unroll 1
;         for (int t = 2; t < nt; t += 2) G_PAIR(t, 0);
;     __device__ __forceinline__ void epi(const f32x4 (&acc)[2][2][4][2], const Unit& u, int wr, int wc, int fr, int fq) const {
;         const int row0 = u.pm * 256 + wr * 64 + fr, col0 = u.pn * 128 + wc * 32 + 8 * fq;
; #pragma unroll
;         for (int ai = 0; ai < 2; ++ai) {
;             u32x4 xo[4];
; #pragma unroll
;             for (int m = 0; m < 4; ++m) xo[m] = *(const u32x4*)(xb + (size_t)(row0 + ai * 128 + m * 16) * D + col0);
; #pragma unroll
;             for (int m = 0; m < 4; ++m) {
;                 const int row = row0 + ai * 128 + m * 16; const size_t off = (size_t)row * D + col0;
;                 const u32x4 o = xo[m]; const f32x4 a0v = acc[ai][0][m][0], a1v = acc[ai][0][m][1], b0v = acc[ai][1][m][0], b1v = acc[ai][1][m][1];
;                 const float v0 = bf_lo(o.x) + coef * a0v[0] * fast_sigmoid(b0v[0]), v1 = bf_hi(o.x) + coef * a0v[1] * fast_sigmoid(b0v[1]);
;                 const float v2 = bf_lo(o.y) + coef * a0v[2] * fast_sigmoid(b0v[2]), v3 = bf_hi(o.y) + coef * a0v[3] * fast_sigmoid(b0v[3]);
;                 const float v4 = bf_lo(o.z) + coef * a1v[0] * fast_sigmoid(b1v[0]), v5 = bf_hi(o.z) + coef * a1v[1] * fast_sigmoid(b1v[1]);
;                 const float v6 = bf_lo(o.w) + coef * a1v[2] * fast_sigmoid(b1v[2]), v7 = bf_hi(o.w) + coef * a1v[3] * fast_sigmoid(b1v[3]);
;                 u32x4 w; w.x = pk2(v0, v1); w.y = pk2(v2, v3); w.z = pk2(v4, v5); w.w = pk2(v6, v7);
;                 *(u32x4*)(xb + off) = w;
;                 float ss = ((v0 * v0 + v1 * v1) + (v2 * v2 + v3 * v3)) + ((v4 * v4 + v5 * v5) + (v6 * v6 + v7 * v7));
;                 ss += __shfl_xor(ss, 16); ss += __shfl_xor(ss, 32);
;                 if (fq == 0) rowss[(size_t)row * 32 + u.pn * 4 + wc] = ss;
	s_setprio 1
	v_mfma_f32_16x16x32_bf16 v[60:63], v[202:205], v[160:163], v[60:63]
	v_mfma_f32_16x16x32_bf16 v[56:59], v[210:213], v[160:163], v[56:59]
	v_mfma_f32_16x16x32_bf16 v[44:47], v[202:205], v[178:181], v[44:47]
	v_mfma_f32_16x16x32_bf16 v[40:43], v[210:213], v[178:181], v[40:43]
	v_mfma_f32_16x16x32_bf16 v[28:31], v[202:205], v[186:189], v[28:31]
	v_mfma_f32_16x16x32_bf16 v[24:27], v[210:213], v[186:189], v[24:27]
	v_mfma_f32_16x16x32_bf16 v[12:15], v[202:205], v[194:197], v[12:15]
	v_mfma_f32_16x16x32_bf16 v[8:11], v[210:213], v[194:197], v[8:11]
	v_mfma_f32_16x16x32_bf16 v[60:63], v[206:209], v[164:167], v[60:63]
	v_mfma_f32_16x16x32_bf16 v[56:59], v[214:217], v[164:167], v[56:59]
	v_mfma_f32_16x16x32_bf16 v[44:47], v[206:209], v[182:185], v[44:47]
	v_mfma_f32_16x16x32_bf16 v[40:43], v[214:217], v[182:185], v[40:43]
	v_mfma_f32_16x16x32_bf16 v[28:31], v[206:209], v[190:193], v[28:31]
	v_mfma_f32_16x16x32_bf16 v[24:27], v[214:217], v[190:193], v[24:27]
	v_mfma_f32_16x16x32_bf16 v[12:15], v[206:209], v[198:201], v[12:15]
	v_mfma_f32_16x16x32_bf16 v[8:11], v[214:217], v[198:201], v[8:11]
	s_setprio 0
	s_add_i32 s17, s17, 2
	s_add_u32 s30, s30, 0x100
	s_addc_u32 s31, s31, 0
	s_cmp_gt_u32 s17, 13
	s_barrier
	s_cbranch_scc0 .LBB0_920
	v_lshl_or_b32 v152, s59, 7, v171
	v_lshl_add_u32 v156, s8, 8, v170
	v_ashrrev_i32_e32 v153, 31, v152
	v_lshlrev_b64 v[182:183], 1, v[152:153]
	v_ashrrev_i32_e32 v157, 31, v156
	v_lshl_add_u64 v[154:155], s[0:1], 0, v[182:183]
	v_lshlrev_b64 v[184:185], 11, v[156:157]
	v_lshl_add_u64 v[120:121], v[154:155], 0, v[184:185]
	global_load_dwordx4 v[178:181], v[120:121], off
	v_or_b32_e32 v166, 16, v156
	v_or_b32_e32 v162, 32, v156
	v_or_b32_e32 v158, 48, v156
	v_ashrrev_i32_e32 v167, 31, v166
	v_ashrrev_i32_e32 v163, 31, v162
	v_ashrrev_i32_e32 v159, 31, v158
	v_lshlrev_b64 v[168:169], 11, v[166:167]
	v_lshlrev_b64 v[164:165], 11, v[162:163]
	v_lshlrev_b64 v[160:161], 11, v[158:159]
	v_lshl_add_u64 v[120:121], v[154:155], 0, v[168:169]
	v_lshl_add_u64 v[122:123], v[154:155], 0, v[164:165]
	v_lshl_add_u64 v[186:187], v[154:155], 0, v[160:161]
	global_load_dwordx4 v[136:139], v[120:121], off
	global_load_dwordx4 v[132:135], v[122:123], off
	s_nop 0
	global_load_dwordx4 v[120:123], v[186:187], off
	v_mul_f32_e32 v129, 0xbfb8aa3b, v129
	v_mul_f32_e32 v131, 0xbfb8aa3b, v131
	v_mul_f32_e32 v125, 0xbfb8aa3b, v125
	v_mul_f32_e32 v127, 0xbfb8aa3b, v127
	v_mul_f32_e32 v128, 0xbfb8aa3b, v128
	v_mul_f32_e32 v130, 0xbfb8aa3b, v130
	v_mul_f32_e32 v124, 0xbfb8aa3b, v124
	v_mul_f32_e32 v126, 0xbfb8aa3b, v126
	v_exp_f32_e32 v129, v129
	v_exp_f32_e32 v131, v131
	v_exp_f32_e32 v125, v125
	v_exp_f32_e32 v127, v127
	v_exp_f32_e32 v128, v128
	v_exp_f32_e32 v130, v130
	v_exp_f32_e32 v189, v124
	v_exp_f32_e32 v126, v126
	v_and_b32_e32 v187, 64, v175
	v_xor_b32_e32 v186, 16, v175
	v_add_u32_e32 v187, 64, v187
	v_cmp_lt_i32_e32 vcc, v186, v187
	v_add_f32_e32 v129, 1.0, v129
	v_add_f32_e32 v131, 1.0, v131
	v_add_f32_e32 v125, 1.0, v125
	v_add_f32_e32 v127, 1.0, v127
	v_cndmask_b32_e32 v124, v175, v186, vcc
	v_add_f32_e32 v128, 1.0, v128
	v_add_f32_e32 v130, 1.0, v130
	v_add_f32_e32 v186, 1.0, v189
	v_add_f32_e32 v126, 1.0, v126
	v_rcp_f32_e32 v129, v129
	v_rcp_f32_e32 v131, v131
	v_rcp_f32_e32 v125, v125
	v_rcp_f32_e32 v127, v127
	v_rcp_f32_e32 v128, v128
	v_rcp_f32_e32 v130, v130
	v_rcp_f32_e32 v186, v186
	v_rcp_f32_e32 v126, v126
	v_lshlrev_b32_e32 v124, 2, v124
	v_xor_b32_e32 v188, 32, v175
	v_cmp_lt_i32_e32 vcc, v188, v187
	s_lshl_b32 s24, s59, 2
	s_ashr_i32 s25, s24, 31
	s_waitcnt vmcnt(0)
	v_lshlrev_b32_e32 v189, 16, v178
	v_and_b32_e32 v178, 0xffff0000, v178
	v_lshlrev_b32_e32 v190, 16, v179
	v_and_b32_e32 v179, 0xffff0000, v179
	v_lshlrev_b32_e32 v191, 16, v180
	v_and_b32_e32 v180, 0xffff0000, v180
	v_lshlrev_b32_e32 v192, 16, v181
	v_and_b32_e32 v181, 0xffff0000, v181
	v_fmac_f32_e32 v178, v117, v129
	v_fmac_f32_e32 v179, v119, v131
	v_fmac_f32_e32 v180, v113, v125
	v_fmac_f32_e32 v181, v115, v127
	v_fmac_f32_e32 v189, v116, v128
	v_fmac_f32_e32 v190, v118, v130
	v_fmac_f32_e32 v191, v112, v186
	v_fmac_f32_e32 v192, v114, v126
	v_mul_f32_e32 v112, v178, v178
	v_mul_f32_e32 v113, v179, v179
	v_mul_f32_e32 v114, v180, v180
	v_mul_f32_e32 v115, v181, v181
	v_fmac_f32_e32 v112, v189, v189
	v_fmac_f32_e32 v113, v190, v190
	v_fmac_f32_e32 v114, v191, v191
	v_fmac_f32_e32 v115, v192, v192
	v_add_f32_e32 v112, v112, v113
	v_add_f32_e32 v113, v114, v115
	v_add_f32_e32 v112, v112, v113
	ds_bpermute_b32 v113, v124, v112
	v_lshl_add_u64 v[126:127], s[0:1], 0, v[184:185]
	v_lshl_add_u64 v[126:127], v[126:127], 0, v[182:183]
	v_cvt_pk_bf16_f32 v116, v189, v178
	v_cvt_pk_bf16_f32 v117, v190, v179
	s_waitcnt lgkmcnt(0)
	v_add_f32_e32 v113, v112, v113
	v_cndmask_b32_e32 v112, v175, v188, vcc
	v_lshlrev_b32_e32 v112, 2, v112
	ds_bpermute_b32 v114, v112, v113
	v_cvt_pk_bf16_f32 v118, v191, v180
	v_cvt_pk_bf16_f32 v119, v192, v181
	global_store_dwordx4 v[126:127], v[116:119], off
	s_and_saveexec_b64 s[26:27], s[4:5]
	s_cbranch_execz .LBB0_923
	v_lshlrev_b64 v[116:117], 7, v[156:157]
	v_lshl_add_u64 v[116:117], s[2:3], 0, v[116:117]
	v_lshl_add_u64 v[116:117], s[24:25], 2, v[116:117]
	s_lshl_b32 s8, s45, 2
	v_lshl_add_u64 v[116:117], v[116:117], 0, s[8:9]
	s_waitcnt lgkmcnt(0)
	v_add_f32_e32 v113, v113, v114
	global_store_dword v[116:117], v113, off

.LBB0_1670:
	s_waitcnt lgkmcnt(0)
	ds_read_b128 v[0:3], v173
	ds_read_b128 v[4:7], v173 offset:1024
	ds_read_b128 v[8:11], v173 offset:2048
	ds_read_b128 v[12:15], v173 offset:3072
	s_lshl_b64 s[22:23], s[16:17], 17
	s_add_u32 s22, s35, s22
	s_addc_u32 s23, s36, s23
	s_add_u32 s52, s24, 0x40080
	s_addc_u32 s53, s25, 0
	s_mov_b32 m0, s47
	v_lshl_add_u64 v[48:49], s[52:53], 0, v[150:151]
	ds_read_b128 v[16:19], v174
	ds_read_b128 v[20:23], v174 offset:1024
	ds_read_b128 v[24:27], v174 offset:2048
	ds_read_b128 v[28:31], v174 offset:3072
	ds_read_b128 v[32:35], v174 offset:4096
	ds_read_b128 v[36:39], v174 offset:5120
	ds_read_b128 v[40:43], v174 offset:6144
	ds_read_b128 v[44:47], v174 offset:7168
	global_load_lds_dwordx4 v[48:49], off
	s_mov_b32 m0, s48
	v_lshl_add_u64 v[48:49], s[52:53], 0, v[146:147]
	global_load_lds_dwordx4 v[48:49], off
	s_waitcnt lgkmcnt(8)
	s_barrier
	s_waitcnt lgkmcnt(0)
	s_setprio 1
	v_mfma_f32_16x16x32_bf16 v[48:51], v[0:3], v[16:19], 0
	v_mfma_f32_16x16x32_bf16 v[52:55], v[8:11], v[16:19], 0
	v_mfma_f32_16x16x32_bf16 v[56:59], v[0:3], v[24:27], 0
	v_mfma_f32_16x16x32_bf16 v[60:63], v[8:11], v[24:27], 0
	v_mfma_f32_16x16x32_bf16 v[64:67], v[0:3], v[32:35], 0
	v_mfma_f32_16x16x32_bf16 v[68:71], v[8:11], v[32:35], 0
	v_mfma_f32_16x16x32_bf16 v[72:75], v[0:3], v[40:43], 0
	v_mfma_f32_16x16x32_bf16 v[76:79], v[8:11], v[40:43], 0
	v_mfma_f32_16x16x32_bf16 v[48:51], v[4:7], v[20:23], v[48:51]
	v_mfma_f32_16x16x32_bf16 v[52:55], v[12:15], v[20:23], v[52:55]
	v_mfma_f32_16x16x32_bf16 v[56:59], v[4:7], v[28:31], v[56:59]
	v_mfma_f32_16x16x32_bf16 v[60:63], v[12:15], v[28:31], v[60:63]
	v_mfma_f32_16x16x32_bf16 v[64:67], v[4:7], v[36:39], v[64:67]
	v_mfma_f32_16x16x32_bf16 v[68:71], v[12:15], v[36:39], v[68:71]
	v_mfma_f32_16x16x32_bf16 v[72:75], v[4:7], v[44:47], v[72:75]
	v_mfma_f32_16x16x32_bf16 v[76:79], v[12:15], v[44:47], v[76:79]
	s_setprio 0
	s_barrier
	v_lshl_add_u64 v[168:169], s[26:27], 0, v[148:149]
	s_mov_b32 m0, s49
	v_lshl_add_u64 v[96:97], v[168:169], 0, s[10:11]
	v_lshl_add_u64 v[212:213], s[26:27], 0, v[144:145]
	ds_read_b128 v[80:83], v175
	ds_read_b128 v[84:87], v175 offset:1024
	ds_read_b128 v[88:91], v175 offset:2048
	ds_read_b128 v[92:95], v175 offset:3072
	global_load_lds_dwordx4 v[96:97], off
	s_mov_b32 m0, s50
	v_lshl_add_u64 v[96:97], v[212:213], 0, s[10:11]
	global_load_lds_dwordx4 v[96:97], off
	s_barrier
	s_waitcnt lgkmcnt(0)
	s_setprio 1
	v_mfma_f32_16x16x32_bf16 v[96:99], v[80:83], v[16:19], 0
	v_mfma_f32_16x16x32_bf16 v[16:19], v[88:91], v[16:19], 0
	v_mfma_f32_16x16x32_bf16 v[100:103], v[80:83], v[24:27], 0
	v_mfma_f32_16x16x32_bf16 v[24:27], v[88:91], v[24:27], 0
	v_mfma_f32_16x16x32_bf16 v[104:107], v[80:83], v[32:35], 0
	v_mfma_f32_16x16x32_bf16 v[32:35], v[88:91], v[32:35], 0
	v_mfma_f32_16x16x32_bf16 v[108:111], v[80:83], v[40:43], 0
	v_mfma_f32_16x16x32_bf16 v[40:43], v[88:91], v[40:43], 0
	v_mfma_f32_16x16x32_bf16 v[96:99], v[84:87], v[20:23], v[96:99]
	v_mfma_f32_16x16x32_bf16 v[16:19], v[92:95], v[20:23], v[16:19]
	v_mfma_f32_16x16x32_bf16 v[20:23], v[84:87], v[28:31], v[100:103]
	v_mfma_f32_16x16x32_bf16 v[24:27], v[92:95], v[28:31], v[24:27]
	v_mfma_f32_16x16x32_bf16 v[28:31], v[84:87], v[36:39], v[104:107]
	v_mfma_f32_16x16x32_bf16 v[32:35], v[92:95], v[36:39], v[32:35]
	v_mfma_f32_16x16x32_bf16 v[36:39], v[84:87], v[44:47], v[108:111]
	v_mfma_f32_16x16x32_bf16 v[40:43], v[92:95], v[44:47], v[40:43]
	s_setprio 0
	v_lshl_add_u64 v[214:215], s[24:25], 0, v[150:151]
	s_mov_b32 m0, s38
	v_lshl_add_u64 v[128:129], v[214:215], 0, s[10:11]
	v_lshl_add_u64 v[216:217], s[24:25], 0, v[146:147]
	s_barrier
	ds_read_b128 v[44:47], v174 offset:16384
	ds_read_b128 v[100:103], v174 offset:17408
	ds_read_b128 v[104:107], v174 offset:18432
	ds_read_b128 v[108:111], v174 offset:19456
	ds_read_b128 v[112:115], v174 offset:20480
	ds_read_b128 v[116:119], v174 offset:21504
	ds_read_b128 v[120:123], v174 offset:22528
	ds_read_b128 v[124:127], v174 offset:23552
	global_load_lds_dwordx4 v[128:129], off
	s_mov_b32 m0, s39
	v_lshl_add_u64 v[128:129], v[216:217], 0, s[10:11]
	global_load_lds_dwordx4 v[128:129], off
	s_barrier
	s_waitcnt lgkmcnt(0)
	s_setprio 1
	v_mfma_f32_16x16x32_bf16 v[128:131], v[0:3], v[44:47], 0
	v_mfma_f32_16x16x32_bf16 v[132:135], v[8:11], v[44:47], 0
	v_mfma_f32_16x16x32_bf16 v[136:139], v[0:3], v[104:107], 0
	v_mfma_f32_16x16x32_bf16 v[140:143], v[8:11], v[104:107], 0
	v_mfma_f32_16x16x32_bf16 v[152:155], v[0:3], v[112:115], 0
	v_mfma_f32_16x16x32_bf16 v[156:159], v[8:11], v[112:115], 0
	v_mfma_f32_16x16x32_bf16 v[0:3], v[0:3], v[120:123], 0
	v_mfma_f32_16x16x32_bf16 v[8:11], v[8:11], v[120:123], 0
	v_mfma_f32_16x16x32_bf16 v[128:131], v[4:7], v[100:103], v[128:131]
	v_mfma_f32_16x16x32_bf16 v[136:139], v[4:7], v[108:111], v[136:139]
	v_mfma_f32_16x16x32_bf16 v[140:143], v[12:15], v[108:111], v[140:143]
	v_mfma_f32_16x16x32_bf16 v[152:155], v[4:7], v[116:119], v[152:155]
	v_mfma_f32_16x16x32_bf16 v[156:159], v[12:15], v[116:119], v[156:159]
	v_mfma_f32_16x16x32_bf16 v[0:3], v[4:7], v[124:127], v[0:3]
	v_mfma_f32_16x16x32_bf16 v[4:7], v[12:15], v[124:127], v[8:11]
	v_mfma_f32_16x16x32_bf16 v[132:135], v[12:15], v[100:103], v[132:135]
	s_setprio 0
	s_barrier
	s_add_u32 s52, s26, 0x10100
	s_addc_u32 s53, s27, 0
	s_add_i32 s19, s46, s37
	v_lshl_add_u64 v[8:9], s[52:53], 0, v[148:149]
	s_mov_b32 m0, s19
	s_add_i32 s17, s19, 0x2000
	global_load_lds_dwordx4 v[8:9], off
	s_mov_b32 m0, s17
	v_lshl_add_u64 v[8:9], s[52:53], 0, v[144:145]
	global_load_lds_dwordx4 v[8:9], off
	s_waitcnt vmcnt(6)
	s_barrier
	s_setprio 1
	v_mfma_f32_16x16x32_bf16 v[8:11], v[80:83], v[44:47], 0
	v_mfma_f32_16x16x32_bf16 v[12:15], v[88:91], v[44:47], 0
	v_mfma_f32_16x16x32_bf16 v[44:47], v[80:83], v[104:107], 0
	v_mfma_f32_16x16x32_bf16 v[104:107], v[88:91], v[104:107], 0
	v_mfma_f32_16x16x32_bf16 v[160:163], v[80:83], v[112:115], 0
	v_mfma_f32_16x16x32_bf16 v[112:115], v[88:91], v[112:115], 0
	v_mfma_f32_16x16x32_bf16 v[80:83], v[80:83], v[120:123], 0
	v_mfma_f32_16x16x32_bf16 v[88:91], v[88:91], v[120:123], 0
	v_mfma_f32_16x16x32_bf16 v[8:11], v[84:87], v[100:103], v[8:11]
	v_mfma_f32_16x16x32_bf16 v[12:15], v[92:95], v[100:103], v[12:15]
	v_mfma_f32_16x16x32_bf16 v[44:47], v[84:87], v[108:111], v[44:47]
	v_mfma_f32_16x16x32_bf16 v[100:103], v[92:95], v[108:111], v[104:107]
	v_mfma_f32_16x16x32_bf16 v[104:107], v[84:87], v[116:119], v[160:163]
	v_mfma_f32_16x16x32_bf16 v[108:111], v[92:95], v[116:119], v[112:115]
	v_mfma_f32_16x16x32_bf16 v[80:83], v[84:87], v[124:127], v[80:83]
	v_mfma_f32_16x16x32_bf16 v[84:87], v[92:95], v[124:127], v[88:91]
	s_setprio 0
	s_add_i32 s51, 0, 0x18000
	v_add_u32_e32 v221, s51, v171
	s_barrier
	ds_read_b128 v[88:91], v221
	ds_read_b128 v[92:95], v221 offset:1024
	ds_read_b128 v[112:115], v221 offset:2048
	ds_read_b128 v[116:119], v221 offset:3072
	s_add_u32 s52, s24, 0x40100
	s_addc_u32 s53, s25, 0
	s_mov_b32 m0, s40
	v_lshl_add_u64 v[196:197], s[52:53], 0, v[150:151]
	ds_read_b128 v[120:123], v174 offset:32768
	ds_read_b128 v[124:127], v174 offset:33792
	ds_read_b128 v[160:163], v174 offset:34816
	ds_read_b128 v[164:167], v174 offset:35840
	ds_read_b128 v[180:183], v174 offset:36864
	ds_read_b128 v[184:187], v174 offset:37888
	ds_read_b128 v[188:191], v174 offset:38912
	ds_read_b128 v[192:195], v174 offset:39936
	global_load_lds_dwordx4 v[196:197], off
	s_mov_b32 m0, s41
	v_lshl_add_u64 v[196:197], s[52:53], 0, v[146:147]
	global_load_lds_dwordx4 v[196:197], off
	s_waitcnt lgkmcnt(8)
	s_barrier
	s_waitcnt lgkmcnt(0)
	s_setprio 1
	v_mfma_f32_16x16x32_bf16 v[48:51], v[88:91], v[120:123], v[48:51]
	v_mfma_f32_16x16x32_bf16 v[52:55], v[112:115], v[120:123], v[52:55]
	v_mfma_f32_16x16x32_bf16 v[56:59], v[88:91], v[160:163], v[56:59]
	v_mfma_f32_16x16x32_bf16 v[60:63], v[112:115], v[160:163], v[60:63]
	v_mfma_f32_16x16x32_bf16 v[64:67], v[88:91], v[180:183], v[64:67]
	v_mfma_f32_16x16x32_bf16 v[68:71], v[112:115], v[180:183], v[68:71]
	v_mfma_f32_16x16x32_bf16 v[72:75], v[88:91], v[188:191], v[72:75]
	v_mfma_f32_16x16x32_bf16 v[76:79], v[112:115], v[188:191], v[76:79]
	v_mfma_f32_16x16x32_bf16 v[48:51], v[92:95], v[124:127], v[48:51]
	v_mfma_f32_16x16x32_bf16 v[52:55], v[116:119], v[124:127], v[52:55]
	v_mfma_f32_16x16x32_bf16 v[56:59], v[92:95], v[164:167], v[56:59]
	v_mfma_f32_16x16x32_bf16 v[60:63], v[116:119], v[164:167], v[60:63]
	v_mfma_f32_16x16x32_bf16 v[64:67], v[92:95], v[184:187], v[64:67]
	v_mfma_f32_16x16x32_bf16 v[68:71], v[116:119], v[184:187], v[68:71]
	v_mfma_f32_16x16x32_bf16 v[72:75], v[92:95], v[192:195], v[72:75]
	v_mfma_f32_16x16x32_bf16 v[76:79], v[116:119], v[192:195], v[76:79]
	s_setprio 0
	s_barrier
	s_add_i32 s54, 0, 0x1c000
	s_add_i32 s53, s51, s37
	v_add_u32_e32 v226, s54, v171
	v_lshl_add_u64 v[168:169], v[168:169], 0, s[12:13]
	s_mov_b32 m0, s53
	s_add_i32 s51, s53, 0x2000
	ds_read_b128 v[196:199], v226
	ds_read_b128 v[200:203], v226 offset:1024
	ds_read_b128 v[204:207], v226 offset:2048
	ds_read_b128 v[208:211], v226 offset:3072
	global_load_lds_dwordx4 v[168:169], off
	s_mov_b32 m0, s51
	v_lshl_add_u64 v[168:169], v[212:213], 0, s[12:13]
	global_load_lds_dwordx4 v[168:169], off
	s_barrier
	s_waitcnt lgkmcnt(0)
	s_setprio 1
	v_mfma_f32_16x16x32_bf16 v[96:99], v[196:199], v[120:123], v[96:99]
	v_mfma_f32_16x16x32_bf16 v[16:19], v[204:207], v[120:123], v[16:19]
	v_mfma_f32_16x16x32_bf16 v[20:23], v[196:199], v[160:163], v[20:23]
	v_mfma_f32_16x16x32_bf16 v[24:27], v[204:207], v[160:163], v[24:27]
	v_mfma_f32_16x16x32_bf16 v[28:31], v[196:199], v[180:183], v[28:31]
	v_mfma_f32_16x16x32_bf16 v[32:35], v[204:207], v[180:183], v[32:35]
	v_mfma_f32_16x16x32_bf16 v[36:39], v[196:199], v[188:191], v[36:39]
	v_mfma_f32_16x16x32_bf16 v[40:43], v[204:207], v[188:191], v[40:43]
	v_mfma_f32_16x16x32_bf16 v[96:99], v[200:203], v[124:127], v[96:99]
	v_mfma_f32_16x16x32_bf16 v[16:19], v[208:211], v[124:127], v[16:19]
	v_mfma_f32_16x16x32_bf16 v[20:23], v[200:203], v[164:167], v[20:23]
	v_mfma_f32_16x16x32_bf16 v[24:27], v[208:211], v[164:167], v[24:27]
	v_mfma_f32_16x16x32_bf16 v[28:31], v[200:203], v[184:187], v[28:31]
	v_mfma_f32_16x16x32_bf16 v[32:35], v[208:211], v[184:187], v[32:35]
	v_mfma_f32_16x16x32_bf16 v[36:39], v[200:203], v[192:195], v[36:39]
	v_mfma_f32_16x16x32_bf16 v[40:43], v[208:211], v[192:195], v[40:43]
	s_setprio 0
	s_mov_b32 m0, s43
	v_lshl_add_u64 v[168:169], v[214:215], 0, s[12:13]
	s_barrier
	ds_read_b128 v[120:123], v174 offset:49152
	ds_read_b128 v[124:127], v174 offset:50176
	ds_read_b128 v[160:163], v174 offset:51200
	ds_read_b128 v[164:167], v174 offset:52224
	ds_read_b128 v[180:183], v174 offset:53248
	ds_read_b128 v[184:187], v174 offset:54272
	ds_read_b128 v[188:191], v174 offset:55296
	ds_read_b128 v[192:195], v174 offset:56320
	global_load_lds_dwordx4 v[168:169], off
	s_mov_b32 m0, s44
	v_lshl_add_u64 v[168:169], v[216:217], 0, s[12:13]
	global_load_lds_dwordx4 v[168:169], off
	s_barrier
;     __device__ __forceinline__ bool unit(int L, Unit& u) const { u.g = L; return order_mn(L, T / 256, NGU / 256, u.pm, u.pn); }
;     __device__ __forceinline__ bool unit(int L, Unit& u) const { u.g = L; return order_mn(L, T / 256, D / 256, u.pm, u.pn); }
;     __device__ __forceinline__ bool unit(int L, Unit& u) const { u.g = 0; return order_mn(L, T / 256, 8, u.pm, u.pn); }
;     __device__ __forceinline__ bool unit(int L, Unit& u) const { if (L >= NG * 4) return false; u.g = L >> 2; u.pm = (L >> 1) & 1; u.pn = L & 1; return true; }
;     __device__ __forceinline__ bool unit(int L, Unit& u) const { if (L >= NG * 8) return false; u.g = L >> 3; u.pm = (L >> 2) & 1; u.pn = L & 3; return true; }
;     ...
;         const bool has_next = p.unit((ui + 1) * G + c, nxt);
;         const char* nA = has_next ? p.a0(nxt) : cA; const char* nB = has_next ? p.b0(nxt) : cB;
;         const char* nA2 = P::SEG ? (has_next ? p.a1(nxt) : cA2) : nA; const char* nB2 = P::SEG ? (has_next ? p.b1(nxt) : cB2) : nB;
	s_waitcnt lgkmcnt(0)
	s_setprio 1
	v_mfma_f32_16x16x32_bf16 v[128:131], v[88:91], v[120:123], v[128:131]
	v_mfma_f32_16x16x32_bf16 v[132:135], v[112:115], v[120:123], v[132:135]
	v_mfma_f32_16x16x32_bf16 v[136:139], v[88:91], v[160:163], v[136:139]
	v_mfma_f32_16x16x32_bf16 v[140:143], v[112:115], v[160:163], v[140:143]
	v_mfma_f32_16x16x32_bf16 v[152:155], v[88:91], v[180:183], v[152:155]
	v_mfma_f32_16x16x32_bf16 v[156:159], v[112:115], v[180:183], v[156:159]
	v_mfma_f32_16x16x32_bf16 v[0:3], v[88:91], v[188:191], v[0:3]
	v_mfma_f32_16x16x32_bf16 v[4:7], v[112:115], v[188:191], v[4:7]
	v_mfma_f32_16x16x32_bf16 v[88:91], v[92:95], v[124:127], v[128:131]
	v_mfma_f32_16x16x32_bf16 v[112:115], v[116:119], v[124:127], v[132:135]
	v_mfma_f32_16x16x32_bf16 v[128:131], v[92:95], v[164:167], v[136:139]
	v_mfma_f32_16x16x32_bf16 v[132:135], v[116:119], v[164:167], v[140:143]
	v_mfma_f32_16x16x32_bf16 v[136:139], v[92:95], v[184:187], v[152:155]
	v_mfma_f32_16x16x32_bf16 v[140:143], v[116:119], v[184:187], v[156:159]
	v_mfma_f32_16x16x32_bf16 v[0:3], v[92:95], v[192:195], v[0:3]
	v_mfma_f32_16x16x32_bf16 v[4:7], v[116:119], v[192:195], v[4:7]
	s_setprio 0
	s_barrier
	s_add_u32 s56, s26, 0x10180
	s_addc_u32 s57, s27, 0
	s_add_i32 s54, s54, s37
	v_lshl_add_u64 v[92:93], s[56:57], 0, v[148:149]
	s_mov_b32 m0, s54
	s_add_i32 s52, s54, 0x2000
	global_load_lds_dwordx4 v[92:93], off
	s_mov_b32 m0, s52
	v_lshl_add_u64 v[92:93], s[56:57], 0, v[144:145]
	global_load_lds_dwordx4 v[92:93], off
	s_waitcnt vmcnt(6)
	s_barrier
	s_setprio 1
	v_mfma_f32_16x16x32_bf16 v[8:11], v[196:199], v[120:123], v[8:11]
	s_and_b64 s[28:29], s[28:29], exec
	s_cselect_b32 s27, s23, s27
	s_cselect_b32 s26, s22, s26
	v_mfma_f32_16x16x32_bf16 v[12:15], v[204:207], v[120:123], v[12:15]
	v_mfma_f32_16x16x32_bf16 v[44:47], v[196:199], v[160:163], v[44:47]
	v_mfma_f32_16x16x32_bf16 v[92:95], v[204:207], v[160:163], v[100:103]
	v_mfma_f32_16x16x32_bf16 v[100:103], v[196:199], v[180:183], v[104:107]
	v_mfma_f32_16x16x32_bf16 v[104:107], v[204:207], v[180:183], v[108:111]
	v_mfma_f32_16x16x32_bf16 v[80:83], v[196:199], v[188:191], v[80:83]
	v_mfma_f32_16x16x32_bf16 v[84:87], v[204:207], v[188:191], v[84:87]
	v_mfma_f32_16x16x32_bf16 v[8:11], v[200:203], v[124:127], v[8:11]
	v_mfma_f32_16x16x32_bf16 v[12:15], v[208:211], v[124:127], v[12:15]
	v_mfma_f32_16x16x32_bf16 v[44:47], v[200:203], v[164:167], v[44:47]
	v_mfma_f32_16x16x32_bf16 v[92:95], v[208:211], v[164:167], v[92:95]
	v_mfma_f32_16x16x32_bf16 v[100:103], v[200:203], v[184:187], v[100:103]
	v_mfma_f32_16x16x32_bf16 v[104:107], v[208:211], v[184:187], v[104:107]
	v_mfma_f32_16x16x32_bf16 v[80:83], v[200:203], v[192:195], v[80:83]
	v_mfma_f32_16x16x32_bf16 v[84:87], v[208:211], v[192:195], v[84:87]
	s_setprio 0
	s_barrier
	ds_read_b128 v[108:111], v173
	ds_read_b128 v[116:119], v173 offset:1024
	ds_read_b128 v[120:123], v173 offset:2048
	ds_read_b128 v[124:127], v173 offset:3072
	s_add_u32 s24, s24, 0x40180
	s_addc_u32 s25, s25, 0
	s_mov_b32 m0, s47
	v_lshl_add_u64 v[168:169], s[24:25], 0, v[150:151]
	ds_read_b128 v[152:155], v174
	ds_read_b128 v[156:159], v174 offset:1024
	ds_read_b128 v[160:163], v174 offset:2048
	ds_read_b128 v[164:167], v174 offset:3072
	ds_read_b128 v[180:183], v174 offset:4096
	ds_read_b128 v[184:187], v174 offset:5120
	ds_read_b128 v[188:191], v174 offset:6144
	ds_read_b128 v[192:195], v174 offset:7168
	global_load_lds_dwordx4 v[168:169], off
	s_mov_b32 m0, s48
	v_lshl_add_u64 v[168:169], s[24:25], 0, v[146:147]
	global_load_lds_dwordx4 v[168:169], off
	s_waitcnt lgkmcnt(8)
	s_barrier
	s_waitcnt lgkmcnt(0)
	s_setprio 1
	v_mfma_f32_16x16x32_bf16 v[48:51], v[108:111], v[152:155], v[48:51]
	v_mfma_f32_16x16x32_bf16 v[52:55], v[120:123], v[152:155], v[52:55]
	v_mfma_f32_16x16x32_bf16 v[56:59], v[108:111], v[160:163], v[56:59]
	v_mfma_f32_16x16x32_bf16 v[60:63], v[120:123], v[160:163], v[60:63]
	v_mfma_f32_16x16x32_bf16 v[64:67], v[108:111], v[180:183], v[64:67]
	v_mfma_f32_16x16x32_bf16 v[68:71], v[120:123], v[180:183], v[68:71]
	v_mfma_f32_16x16x32_bf16 v[72:75], v[108:111], v[188:191], v[72:75]
	v_mfma_f32_16x16x32_bf16 v[76:79], v[120:123], v[188:191], v[76:79]
	v_mfma_f32_16x16x32_bf16 v[48:51], v[116:119], v[156:159], v[48:51]
	v_mfma_f32_16x16x32_bf16 v[52:55], v[124:127], v[156:159], v[52:55]
	v_mfma_f32_16x16x32_bf16 v[56:59], v[116:119], v[164:167], v[56:59]
	v_mfma_f32_16x16x32_bf16 v[60:63], v[124:127], v[164:167], v[60:63]
	v_mfma_f32_16x16x32_bf16 v[64:67], v[116:119], v[184:187], v[64:67]
	v_mfma_f32_16x16x32_bf16 v[68:71], v[124:127], v[184:187], v[68:71]
	v_mfma_f32_16x16x32_bf16 v[72:75], v[116:119], v[192:195], v[72:75]
	v_mfma_f32_16x16x32_bf16 v[76:79], v[124:127], v[192:195], v[76:79]
	s_setprio 0
	s_barrier
	s_mov_b32 m0, s49
	v_lshl_add_u64 v[168:169], s[26:27], 0, v[148:149]
	ds_read_b128 v[196:199], v175
	ds_read_b128 v[200:203], v175 offset:1024
	ds_read_b128 v[204:207], v175 offset:2048
	ds_read_b128 v[208:211], v175 offset:3072
	global_load_lds_dwordx4 v[168:169], off
	s_mov_b32 m0, s50
	v_lshl_add_u64 v[230:231], s[26:27], 0, v[144:145]
	global_load_lds_dwordx4 v[230:231], off
	s_barrier
	s_waitcnt lgkmcnt(0)
	s_setprio 1
	v_mfma_f32_16x16x32_bf16 v[96:99], v[196:199], v[152:155], v[96:99]
	v_mfma_f32_16x16x32_bf16 v[16:19], v[204:207], v[152:155], v[16:19]
	v_mfma_f32_16x16x32_bf16 v[20:23], v[196:199], v[160:163], v[20:23]
	v_mfma_f32_16x16x32_bf16 v[24:27], v[204:207], v[160:163], v[24:27]
	v_mfma_f32_16x16x32_bf16 v[28:31], v[196:199], v[180:183], v[28:31]
	v_mfma_f32_16x16x32_bf16 v[32:35], v[204:207], v[180:183], v[32:35]
	v_mfma_f32_16x16x32_bf16 v[36:39], v[196:199], v[188:191], v[36:39]
	v_mfma_f32_16x16x32_bf16 v[40:43], v[204:207], v[188:191], v[40:43]
	v_mfma_f32_16x16x32_bf16 v[152:155], v[200:203], v[156:159], v[96:99]
	v_mfma_f32_16x16x32_bf16 v[16:19], v[208:211], v[156:159], v[16:19]
	v_mfma_f32_16x16x32_bf16 v[20:23], v[200:203], v[164:167], v[20:23]
	v_mfma_f32_16x16x32_bf16 v[24:27], v[208:211], v[164:167], v[24:27]
	v_mfma_f32_16x16x32_bf16 v[28:31], v[200:203], v[184:187], v[28:31]
	v_mfma_f32_16x16x32_bf16 v[32:35], v[208:211], v[184:187], v[32:35]
	v_mfma_f32_16x16x32_bf16 v[36:39], v[200:203], v[192:195], v[36:39]
	v_mfma_f32_16x16x32_bf16 v[40:43], v[208:211], v[192:195], v[40:43]
	s_setprio 0
	s_mov_b32 m0, s38
	v_lshl_add_u64 v[234:235], s[20:21], 0, v[150:151]
	s_barrier
	ds_read_b128 v[96:99], v174 offset:16384
	ds_read_b128 v[156:159], v174 offset:17408
	ds_read_b128 v[160:163], v174 offset:18432
	ds_read_b128 v[164:167], v174 offset:19456
	ds_read_b128 v[180:183], v174 offset:20480
	ds_read_b128 v[184:187], v174 offset:21504
	ds_read_b128 v[188:191], v174 offset:22528
	ds_read_b128 v[192:195], v174 offset:23552
	global_load_lds_dwordx4 v[234:235], off
	s_mov_b32 m0, s39
	v_lshl_add_u64 v[236:237], s[20:21], 0, v[146:147]
	global_load_lds_dwordx4 v[236:237], off
	s_barrier
	s_waitcnt lgkmcnt(0)
	s_setprio 1
	v_mfma_f32_16x16x32_bf16 v[88:91], v[108:111], v[96:99], v[88:91]
	v_mfma_f32_16x16x32_bf16 v[112:115], v[120:123], v[96:99], v[112:115]
	v_mfma_f32_16x16x32_bf16 v[136:139], v[108:111], v[180:183], v[136:139]
	v_mfma_f32_16x16x32_bf16 v[140:143], v[120:123], v[180:183], v[140:143]
	v_mfma_f32_16x16x32_bf16 v[0:3], v[108:111], v[188:191], v[0:3]
	v_mfma_f32_16x16x32_bf16 v[4:7], v[120:123], v[188:191], v[4:7]
	v_mfma_f32_16x16x32_bf16 v[128:131], v[108:111], v[160:163], v[128:131]
	v_mfma_f32_16x16x32_bf16 v[132:135], v[120:123], v[160:163], v[132:135]
	v_mfma_f32_16x16x32_bf16 v[88:91], v[116:119], v[156:159], v[88:91]
	v_mfma_f32_16x16x32_bf16 v[112:115], v[124:127], v[156:159], v[112:115]
	v_mfma_f32_16x16x32_bf16 v[136:139], v[116:119], v[184:187], v[136:139]
	v_mfma_f32_16x16x32_bf16 v[140:143], v[124:127], v[184:187], v[140:143]
	v_mfma_f32_16x16x32_bf16 v[0:3], v[116:119], v[192:195], v[0:3]
	v_mfma_f32_16x16x32_bf16 v[4:7], v[124:127], v[192:195], v[4:7]
	v_mfma_f32_16x16x32_bf16 v[212:215], v[116:119], v[164:167], v[128:131]
	v_mfma_f32_16x16x32_bf16 v[216:219], v[124:127], v[164:167], v[132:135]
	s_setprio 0
	s_barrier
	s_add_u32 s24, s26, 0x10000
	s_addc_u32 s25, s27, 0
	s_mov_b32 m0, s19
	v_lshl_add_u64 v[108:109], s[24:25], 0, v[148:149]
	global_load_lds_dwordx4 v[108:109], off
	s_mov_b32 m0, s17
	v_lshl_add_u64 v[108:109], s[24:25], 0, v[144:145]
	global_load_lds_dwordx4 v[108:109], off
	s_waitcnt vmcnt(6)
	s_barrier
	s_setprio 1
	v_mfma_f32_16x16x32_bf16 v[8:11], v[196:199], v[96:99], v[8:11]
	v_mfma_f32_16x16x32_bf16 v[12:15], v[204:207], v[96:99], v[12:15]
	v_mfma_f32_16x16x32_bf16 v[44:47], v[196:199], v[160:163], v[44:47]
	v_mfma_f32_16x16x32_bf16 v[92:95], v[204:207], v[160:163], v[92:95]
	v_mfma_f32_16x16x32_bf16 v[96:99], v[196:199], v[180:183], v[100:103]
	v_mfma_f32_16x16x32_bf16 v[100:103], v[204:207], v[180:183], v[104:107]
	v_mfma_f32_16x16x32_bf16 v[80:83], v[196:199], v[188:191], v[80:83]
	v_mfma_f32_16x16x32_bf16 v[84:87], v[204:207], v[188:191], v[84:87]
	v_mfma_f32_16x16x32_bf16 v[124:127], v[200:203], v[156:159], v[8:11]
	v_mfma_f32_16x16x32_bf16 v[156:159], v[208:211], v[156:159], v[12:15]
	v_mfma_f32_16x16x32_bf16 v[160:163], v[200:203], v[164:167], v[44:47]
	v_mfma_f32_16x16x32_bf16 v[164:167], v[208:211], v[164:167], v[92:95]
	v_mfma_f32_16x16x32_bf16 v[180:183], v[200:203], v[184:187], v[96:99]
	v_mfma_f32_16x16x32_bf16 v[100:103], v[208:211], v[184:187], v[100:103]
	v_mfma_f32_16x16x32_bf16 v[184:187], v[200:203], v[192:195], v[80:83]
	v_mfma_f32_16x16x32_bf16 v[188:191], v[208:211], v[192:195], v[84:87]
	s_setprio 0
	s_barrier
	ds_read_b128 v[8:11], v221
	ds_read_b128 v[12:15], v221 offset:1024
	ds_read_b128 v[44:47], v221 offset:2048
	ds_read_b128 v[192:195], v221 offset:3072
	s_add_u32 s24, s20, 0x40000
	s_addc_u32 s25, s21, 0
	s_mov_b32 m0, s40
	v_lshl_add_u64 v[92:93], s[24:25], 0, v[150:151]
	ds_read_b128 v[80:83], v174 offset:32768
	ds_read_b128 v[84:87], v174 offset:33792
	ds_read_b128 v[104:107], v174 offset:34816
	ds_read_b128 v[196:199], v174 offset:35840
	ds_read_b128 v[108:111], v174 offset:36864
	ds_read_b128 v[200:203], v174 offset:37888
	ds_read_b128 v[204:207], v174 offset:38912
	ds_read_b128 v[208:211], v174 offset:39936
	global_load_lds_dwordx4 v[92:93], off
	s_mov_b32 m0, s41
	v_lshl_add_u64 v[92:93], s[24:25], 0, v[146:147]
	global_load_lds_dwordx4 v[92:93], off
	s_waitcnt lgkmcnt(8)
	s_barrier
	s_waitcnt lgkmcnt(0)
	s_setprio 1
	v_mfma_f32_16x16x32_bf16 v[52:55], v[44:47], v[80:83], v[52:55]
	v_mfma_f32_16x16x32_bf16 v[56:59], v[8:11], v[104:107], v[56:59]
	v_mfma_f32_16x16x32_bf16 v[60:63], v[44:47], v[104:107], v[60:63]
	v_mfma_f32_16x16x32_bf16 v[64:67], v[8:11], v[108:111], v[64:67]
	v_mfma_f32_16x16x32_bf16 v[68:71], v[44:47], v[108:111], v[68:71]
	v_mfma_f32_16x16x32_bf16 v[72:75], v[8:11], v[204:207], v[72:75]
	v_mfma_f32_16x16x32_bf16 v[222:225], v[44:47], v[204:207], v[76:79]
	v_mfma_f32_16x16x32_bf16 v[48:51], v[8:11], v[80:83], v[48:51]
	v_mfma_f32_16x16x32_bf16 v[128:131], v[192:195], v[84:87], v[52:55]
	v_mfma_f32_16x16x32_bf16 v[120:123], v[12:15], v[196:199], v[56:59]
	v_mfma_f32_16x16x32_bf16 v[116:119], v[192:195], v[196:199], v[60:63]
	v_mfma_f32_16x16x32_bf16 v[96:99], v[12:15], v[200:203], v[64:67]
	v_mfma_f32_16x16x32_bf16 v[92:95], v[192:195], v[200:203], v[68:71]
	v_mfma_f32_16x16x32_bf16 v[76:79], v[12:15], v[208:211], v[72:75]
	v_mfma_f32_16x16x32_bf16 v[72:75], v[192:195], v[208:211], v[222:225]
	v_mfma_f32_16x16x32_bf16 v[132:135], v[12:15], v[84:87], v[48:51]
	s_setprio 0
	s_barrier
	s_mov_b32 m0, s53
	v_lshl_add_u64 v[48:49], v[168:169], 0, s[6:7]
	ds_read_b128 v[56:59], v226
	ds_read_b128 v[222:225], v226 offset:1024
	ds_read_b128 v[60:63], v226 offset:2048
	ds_read_b128 v[226:229], v226 offset:3072
	global_load_lds_dwordx4 v[48:49], off
	s_mov_b32 m0, s51
	v_lshl_add_u64 v[48:49], v[230:231], 0, s[6:7]
	global_load_lds_dwordx4 v[48:49], off
	s_barrier
	s_waitcnt lgkmcnt(0)
	s_setprio 1
	v_mfma_f32_16x16x32_bf16 v[48:51], v[56:59], v[80:83], v[152:155]
	v_mfma_f32_16x16x32_bf16 v[16:19], v[60:63], v[80:83], v[16:19]
	v_mfma_f32_16x16x32_bf16 v[20:23], v[56:59], v[104:107], v[20:23]
	v_mfma_f32_16x16x32_bf16 v[24:27], v[60:63], v[104:107], v[24:27]
	v_mfma_f32_16x16x32_bf16 v[28:31], v[56:59], v[108:111], v[28:31]
	v_mfma_f32_16x16x32_bf16 v[32:35], v[60:63], v[108:111], v[32:35]
	v_mfma_f32_16x16x32_bf16 v[36:39], v[56:59], v[204:207], v[36:39]
	v_mfma_f32_16x16x32_bf16 v[40:43], v[60:63], v[204:207], v[40:43]
	v_mfma_f32_16x16x32_bf16 v[204:207], v[222:225], v[84:87], v[48:51]
	v_mfma_f32_16x16x32_bf16 v[230:233], v[226:229], v[84:87], v[16:19]
	v_mfma_f32_16x16x32_bf16 v[108:111], v[222:225], v[196:199], v[20:23]
	v_mfma_f32_16x16x32_bf16 v[104:107], v[226:229], v[196:199], v[24:27]
	v_mfma_f32_16x16x32_bf16 v[84:87], v[222:225], v[200:203], v[28:31]
	v_mfma_f32_16x16x32_bf16 v[80:83], v[226:229], v[200:203], v[32:35]
	v_mfma_f32_16x16x32_bf16 v[68:71], v[222:225], v[208:211], v[36:39]
	v_mfma_f32_16x16x32_bf16 v[64:67], v[226:229], v[208:211], v[40:43]
	s_setprio 0
	s_mov_b32 m0, s43
	v_lshl_add_u64 v[24:25], v[234:235], 0, s[6:7]
	s_barrier
	ds_read_b128 v[16:19], v174 offset:49152
	ds_read_b128 v[20:23], v174 offset:50176
	ds_read_b128 v[32:35], v174 offset:51200
	ds_read_b128 v[152:155], v174 offset:52224
	ds_read_b128 v[36:39], v174 offset:53248
	ds_read_b128 v[196:199], v174 offset:54272
	ds_read_b128 v[200:203], v174 offset:55296
	ds_read_b128 v[208:211], v174 offset:56320
	global_load_lds_dwordx4 v[24:25], off
	s_mov_b32 m0, s44
	v_lshl_add_u64 v[24:25], v[236:237], 0, s[6:7]
	global_load_lds_dwordx4 v[24:25], off
	s_barrier
	s_waitcnt lgkmcnt(0)
	s_setprio 1
	v_mfma_f32_16x16x32_bf16 v[24:27], v[8:11], v[16:19], v[88:91]
	v_mfma_f32_16x16x32_bf16 v[28:31], v[44:47], v[16:19], v[112:115]
	v_mfma_f32_16x16x32_bf16 v[40:43], v[8:11], v[32:35], v[212:215]
	v_mfma_f32_16x16x32_bf16 v[88:91], v[44:47], v[32:35], v[216:219]
	v_mfma_f32_16x16x32_bf16 v[112:115], v[8:11], v[36:39], v[136:139]
	v_mfma_f32_16x16x32_bf16 v[136:139], v[44:47], v[36:39], v[140:143]
	v_mfma_f32_16x16x32_bf16 v[0:3], v[8:11], v[200:203], v[0:3]
	v_mfma_f32_16x16x32_bf16 v[4:7], v[44:47], v[200:203], v[4:7]
	v_mfma_f32_16x16x32_bf16 v[52:55], v[12:15], v[20:23], v[24:27]
	v_mfma_f32_16x16x32_bf16 v[48:51], v[192:195], v[20:23], v[28:31]
	v_mfma_f32_16x16x32_bf16 v[44:47], v[12:15], v[152:155], v[40:43]
	v_mfma_f32_16x16x32_bf16 v[40:43], v[192:195], v[152:155], v[88:91]
	v_mfma_f32_16x16x32_bf16 v[28:31], v[12:15], v[196:199], v[112:115]
	v_mfma_f32_16x16x32_bf16 v[24:27], v[192:195], v[196:199], v[136:139]
	v_mfma_f32_16x16x32_bf16 v[12:15], v[12:15], v[208:211], v[0:3]
	v_mfma_f32_16x16x32_bf16 v[8:11], v[192:195], v[208:211], v[4:7]
	s_setprio 0
	s_barrier
	s_add_u32 s24, s26, 0x10080
	s_addc_u32 s25, s27, 0
	s_mov_b32 m0, s54
	v_lshl_add_u64 v[0:1], s[24:25], 0, v[148:149]
	global_load_lds_dwordx4 v[0:1], off
	s_mov_b32 m0, s52
	v_lshl_add_u64 v[0:1], s[24:25], 0, v[144:145]
	global_load_lds_dwordx4 v[0:1], off
	s_waitcnt vmcnt(6)
	s_barrier
; __device__ __forceinline__ unsigned pk2(float lo, float hi) { unsigned r; asm volatile("v_cvt_pk_bf16_f32 %0, %1, %2" : "=v"(r) : "v"(lo), "v"(hi)); return r; }
; __device__ __forceinline__ unsigned pk2(float lo, float hi) { return f2bf(lo) | (f2bf(hi) << 16); }
;     ...
;         G_PAIR(0, 1);
;     __device__ __forceinline__ void epi(const f32x4 (&acc)[2][2][4][2], const Unit& u, int wr, int wc, int fr, int fq) const {
;         if ((PROBE & 64) && coef == 0.f) { dry_epi(acc, pool, rowss); return; }
;         ConvHost<3> ch; ch.begin(cj, u.g, 22, wr * 4 + wc, fq * 16 + fr);
;         const int row0 = u.pm * 256 + wr * 64 + fr, col0 = u.pn * 256 + wc * 32 + 8 * fq;
; #pragma unroll
;         for (int ai = 0; ai < 2; ++ai) {
;             u32x4 xo[4][2];
; #pragma unroll
;             for (int m = 0; m < 4; ++m)
; #pragma unroll
;                 for (int bj = 0; bj < 2; ++bj) xo[m][bj] = *(const u32x4*)(xb + (size_t)(row0 + ai * 128 + m * 16) * D + col0 + bj * 128);
; #pragma unroll
;             for (int m = 0; m < 4; ++m) {
;                 const int row = row0 + ai * 128 + m * 16; const size_t off = (size_t)row * D + col0; float ss = 0.f;
; #pragma unroll
;                 for (int bj = 0; bj < 2; ++bj) {
;                     const u32x4 o = xo[m][bj]; const f32x4 a0v = acc[ai][bj][m][0], a1v = acc[ai][bj][m][1];
;                     const float v0 = bf_lo(o.x) + coef * a0v[0], v1 = bf_hi(o.x) + coef * a0v[1], v2 = bf_lo(o.y) + coef * a0v[2], v3 = bf_hi(o.y) + coef * a0v[3];
;                     const float v4 = bf_lo(o.z) + coef * a1v[0], v5 = bf_hi(o.z) + coef * a1v[1], v6 = bf_lo(o.w) + coef * a1v[2], v7 = bf_hi(o.w) + coef * a1v[3];
;                     u32x4 w; w.x = pk2(v0, v1); w.y = pk2(v2, v3); w.z = pk2(v4, v5); w.w = pk2(v6, v7);
;                     *(u32x4*)(xb + off + bj * 128) = w;
;                     ss += ((v0 * v0 + v1 * v1) + (v2 * v2 + v3 * v3)) + ((v4 * v4 + v5 * v5) + (v6 * v6 + v7 * v7));
;                 }
;                 ss += __shfl_xor(ss, 16); ss += __shfl_xor(ss, 32);
;                 if (fq == 0) rowss[(size_t)row * 32 + u.pn * 4 + wc] = ss;
;             }
	s_setprio 1
	v_mfma_f32_16x16x32_bf16 v[0:3], v[56:59], v[16:19], v[124:127]
	v_mfma_f32_16x16x32_bf16 v[4:7], v[60:63], v[16:19], v[156:159]
	v_mfma_f32_16x16x32_bf16 v[16:19], v[56:59], v[32:35], v[160:163]
	v_mfma_f32_16x16x32_bf16 v[32:35], v[60:63], v[32:35], v[164:167]
	v_mfma_f32_16x16x32_bf16 v[88:91], v[56:59], v[36:39], v[180:183]
	v_mfma_f32_16x16x32_bf16 v[100:103], v[60:63], v[36:39], v[100:103]
	v_mfma_f32_16x16x32_bf16 v[112:115], v[56:59], v[200:203], v[184:187]
	v_mfma_f32_16x16x32_bf16 v[124:127], v[60:63], v[200:203], v[188:191]
	v_mfma_f32_16x16x32_bf16 v[60:63], v[222:225], v[20:23], v[0:3]
	v_mfma_f32_16x16x32_bf16 v[56:59], v[226:229], v[20:23], v[4:7]
	v_mfma_f32_16x16x32_bf16 v[36:39], v[222:225], v[152:155], v[16:19]
	v_mfma_f32_16x16x32_bf16 v[32:35], v[226:229], v[152:155], v[32:35]
	v_mfma_f32_16x16x32_bf16 v[20:23], v[222:225], v[196:199], v[88:91]
	v_mfma_f32_16x16x32_bf16 v[16:19], v[226:229], v[196:199], v[100:103]
	v_mfma_f32_16x16x32_bf16 v[4:7], v[222:225], v[208:211], v[112:115]
	v_mfma_f32_16x16x32_bf16 v[0:3], v[226:229], v[208:211], v[124:127]
	s_setprio 0
	v_lshl_or_b32 v152, s45, 8, v172
	v_lshl_add_u32 v156, s8, 8, v170
	v_ashrrev_i32_e32 v153, 31, v152
	v_lshlrev_b64 v[190:191], 1, v[152:153]
	v_ashrrev_i32_e32 v157, 31, v156
	v_lshl_add_u64 v[154:155], s[0:1], 0, v[190:191]
	v_lshlrev_b64 v[192:193], 11, v[156:157]
	v_lshl_add_u64 v[88:89], v[154:155], 0, v[192:193]
	s_barrier
	global_load_dwordx4 v[182:185], v[88:89], off
	global_load_dwordx4 v[186:189], v[88:89], off offset:256
	v_or_b32_e32 v166, 16, v156
	v_or_b32_e32 v162, 32, v156
	v_or_b32_e32 v158, 48, v156
	v_ashrrev_i32_e32 v167, 31, v166
	v_ashrrev_i32_e32 v163, 31, v162
	v_ashrrev_i32_e32 v159, 31, v158
	v_lshlrev_b64 v[168:169], 11, v[166:167]
	v_lshlrev_b64 v[164:165], 11, v[162:163]
	v_lshlrev_b64 v[160:161], 11, v[158:159]
	v_lshl_add_u64 v[88:89], v[154:155], 0, v[168:169]
	v_lshl_add_u64 v[90:91], v[154:155], 0, v[164:165]
	v_lshl_add_u64 v[180:181], v[154:155], 0, v[160:161]
	global_load_dwordx4 v[140:143], v[88:89], off
	global_load_dwordx4 v[136:139], v[88:89], off offset:256
	global_load_dwordx4 v[124:127], v[90:91], off
	global_load_dwordx4 v[112:115], v[90:91], off offset:256
	global_load_dwordx4 v[100:103], v[180:181], off
	s_nop 0
	global_load_dwordx4 v[88:91], v[180:181], off offset:256
	v_lshl_add_u64 v[192:193], s[0:1], 0, v[192:193]
	v_lshl_add_u64 v[190:191], v[192:193], 0, v[190:191]
	v_cmp_lt_i32_e32 vcc, v177, v178
	s_waitcnt vmcnt(0)
	v_lshlrev_b32_e32 v181, 16, v182
	v_and_b32_e32 v182, 0xffff0000, v182
	v_lshlrev_b32_e32 v192, 16, v183
	v_and_b32_e32 v183, 0xffff0000, v183
	v_lshlrev_b32_e32 v193, 16, v184
	v_and_b32_e32 v184, 0xffff0000, v184
	v_lshlrev_b32_e32 v194, 16, v185
	v_and_b32_e32 v185, 0xffff0000, v185
	v_lshlrev_b32_e32 v195, 16, v186
	v_and_b32_e32 v186, 0xffff0000, v186
	v_lshlrev_b32_e32 v196, 16, v187
	v_and_b32_e32 v187, 0xffff0000, v187
	v_lshlrev_b32_e32 v197, 16, v188
	v_and_b32_e32 v188, 0xffff0000, v188
	v_lshlrev_b32_e32 v198, 16, v189
	v_and_b32_e32 v189, 0xffff0000, v189
	v_add_f32_e32 v133, v133, v182
	v_add_f32_e32 v135, v135, v183
	v_add_f32_e32 v182, v129, v184
	v_add_f32_e32 v131, v131, v185
	v_add_f32_e32 v185, v205, v186
	v_add_f32_e32 v187, v207, v187
	v_add_f32_e32 v188, v231, v188
	v_add_f32_e32 v189, v233, v189
	v_add_f32_e32 v132, v132, v181
	v_add_f32_e32 v134, v134, v192
	v_add_f32_e32 v181, v128, v193
	v_add_f32_e32 v183, v130, v194
	v_add_f32_e32 v184, v204, v195
	v_add_f32_e32 v186, v206, v196
	v_add_f32_e32 v192, v230, v197
	v_add_f32_e32 v193, v232, v198
	v_cvt_pk_bf16_f32 v128, v132, v133
	v_cvt_pk_bf16_f32 v129, v134, v135
	v_mul_f32_e32 v130, v133, v133
	v_mul_f32_e32 v133, v135, v135
	v_mul_f32_e32 v135, v182, v182
	v_mul_f32_e32 v194, v131, v131
	v_mul_f32_e32 v195, v185, v185
	v_mul_f32_e32 v196, v187, v187
	v_mul_f32_e32 v197, v188, v188
	v_mul_f32_e32 v198, v189, v189
	v_fmac_f32_e32 v130, v132, v132
	v_fmac_f32_e32 v133, v134, v134
	v_fmac_f32_e32 v135, v181, v181
	v_fmac_f32_e32 v194, v183, v183
	v_fmac_f32_e32 v195, v184, v184
	v_fmac_f32_e32 v196, v186, v186
	v_fmac_f32_e32 v197, v192, v192
	v_fmac_f32_e32 v198, v193, v193
	v_add_f32_e32 v130, v130, v133
	v_add_f32_e32 v132, v135, v194
	v_add_f32_e32 v133, v195, v196
	v_add_f32_e32 v134, v197, v198
	v_cndmask_b32_e32 v180, v176, v177, vcc
	v_add_f32_e32 v130, v130, v132
	v_add_f32_e32 v132, v133, v134
	v_lshlrev_b32_e32 v180, 2, v180
	v_add_f32_e32 v133, v130, v132
	ds_bpermute_b32 v134, v180, v133
	v_cmp_lt_i32_e32 vcc, v179, v178
	v_cvt_pk_bf16_f32 v130, v181, v182
	v_cvt_pk_bf16_f32 v131, v183, v131
	global_store_dwordx4 v[190:191], v[128:131], off
	v_cvt_pk_bf16_f32 v132, v184, v185
	s_nop 1
	v_cndmask_b32_e32 v128, v176, v179, vcc
	s_waitcnt lgkmcnt(0)
	v_add_f32_e32 v129, v133, v134
	v_lshlrev_b32_e32 v128, 2, v128
	ds_bpermute_b32 v130, v128, v129
	v_cvt_pk_bf16_f32 v133, v186, v187
	v_cvt_pk_bf16_f32 v134, v192, v188
	v_cvt_pk_bf16_f32 v135, v193, v189
	global_store_dwordx4 v[190:191], v[132:135], off offset:256
	s_and_saveexec_b64 s[24:25], s[4:5]
	s_cbranch_execz .LBB0_1672
	s_waitcnt lgkmcnt(0)
	v_add_f32_e32 v129, v129, v130
	s_lshl_b32 s26, s45, 2
	v_lshlrev_b64 v[130:131], 7, v[156:157]
	s_ashr_i32 s27, s26, 31
	v_lshl_add_u64 v[130:131], s[2:3], 0, v[130:131]
	v_lshl_add_u64 v[130:131], s[26:27], 2, v[130:131]
	s_lshl_b32 s8, s42, 2
	v_lshl_add_u64 v[130:131], v[130:131], 0, s[8:9]
	global_store_dword v[130:131], v129, off

.LBB0_1905:
	s_waitcnt lgkmcnt(0)
	ds_read_b128 v[0:3], v185
	ds_read_b128 v[4:7], v185 offset:1024
	ds_read_b128 v[8:11], v185 offset:2048
	ds_read_b128 v[12:15], v185 offset:3072
	s_add_u32 s24, s20, 0xb0080
	s_addc_u32 s25, s21, 0
	s_mov_b32 m0, s45
	v_lshl_add_u64 v[48:49], s[24:25], 0, v[152:153]
	ds_read_b128 v[16:19], v186
	ds_read_b128 v[20:23], v186 offset:1024
	ds_read_b128 v[24:27], v186 offset:2048
	ds_read_b128 v[28:31], v186 offset:3072
	ds_read_b128 v[32:35], v186 offset:4096
	ds_read_b128 v[36:39], v186 offset:5120
	ds_read_b128 v[40:43], v186 offset:6144
	ds_read_b128 v[44:47], v186 offset:7168
	global_load_lds_dwordx4 v[48:49], off
	s_mov_b32 m0, s46
	v_lshl_add_u64 v[48:49], s[24:25], 0, v[156:157]
	global_load_lds_dwordx4 v[48:49], off
	s_waitcnt lgkmcnt(8)
	s_barrier
	s_waitcnt lgkmcnt(0)
	s_setprio 1
	v_mfma_f32_16x16x32_bf16 v[48:51], v[0:3], v[16:19], 0
	v_mfma_f32_16x16x32_bf16 v[52:55], v[8:11], v[16:19], 0
	v_mfma_f32_16x16x32_bf16 v[56:59], v[0:3], v[24:27], 0
	v_mfma_f32_16x16x32_bf16 v[60:63], v[8:11], v[24:27], 0
	v_mfma_f32_16x16x32_bf16 v[64:67], v[0:3], v[32:35], 0
	v_mfma_f32_16x16x32_bf16 v[68:71], v[8:11], v[32:35], 0
	v_mfma_f32_16x16x32_bf16 v[72:75], v[0:3], v[40:43], 0
	v_mfma_f32_16x16x32_bf16 v[76:79], v[8:11], v[40:43], 0
	v_mfma_f32_16x16x32_bf16 v[48:51], v[4:7], v[20:23], v[48:51]
	v_mfma_f32_16x16x32_bf16 v[52:55], v[12:15], v[20:23], v[52:55]
	v_mfma_f32_16x16x32_bf16 v[56:59], v[4:7], v[28:31], v[56:59]
	v_mfma_f32_16x16x32_bf16 v[60:63], v[12:15], v[28:31], v[60:63]
	v_mfma_f32_16x16x32_bf16 v[64:67], v[4:7], v[36:39], v[64:67]
	v_mfma_f32_16x16x32_bf16 v[68:71], v[12:15], v[36:39], v[68:71]
	v_mfma_f32_16x16x32_bf16 v[72:75], v[4:7], v[44:47], v[72:75]
	v_mfma_f32_16x16x32_bf16 v[76:79], v[12:15], v[44:47], v[76:79]
	s_setprio 0
	s_barrier
	v_lshl_add_u64 v[180:181], s[22:23], 0, v[154:155]
	s_mov_b32 m0, s47
	v_lshl_add_u64 v[96:97], v[180:181], 0, s[12:13]
	v_lshl_add_u64 v[218:219], s[22:23], 0, v[158:159]
	ds_read_b128 v[80:83], v187
	ds_read_b128 v[84:87], v187 offset:1024
	ds_read_b128 v[88:91], v187 offset:2048
	ds_read_b128 v[92:95], v187 offset:3072
	global_load_lds_dwordx4 v[96:97], off
	s_mov_b32 m0, s48
	v_lshl_add_u64 v[96:97], v[218:219], 0, s[12:13]
	global_load_lds_dwordx4 v[96:97], off
	s_barrier
	s_waitcnt lgkmcnt(0)
	s_setprio 1
	v_mfma_f32_16x16x32_bf16 v[96:99], v[80:83], v[16:19], 0
	v_mfma_f32_16x16x32_bf16 v[16:19], v[88:91], v[16:19], 0
	v_mfma_f32_16x16x32_bf16 v[100:103], v[80:83], v[24:27], 0
	v_mfma_f32_16x16x32_bf16 v[24:27], v[88:91], v[24:27], 0
	v_mfma_f32_16x16x32_bf16 v[104:107], v[80:83], v[32:35], 0
	v_mfma_f32_16x16x32_bf16 v[32:35], v[88:91], v[32:35], 0
	v_mfma_f32_16x16x32_bf16 v[108:111], v[80:83], v[40:43], 0
	v_mfma_f32_16x16x32_bf16 v[40:43], v[88:91], v[40:43], 0
	v_mfma_f32_16x16x32_bf16 v[96:99], v[84:87], v[20:23], v[96:99]
	v_mfma_f32_16x16x32_bf16 v[16:19], v[92:95], v[20:23], v[16:19]
	v_mfma_f32_16x16x32_bf16 v[20:23], v[84:87], v[28:31], v[100:103]
	v_mfma_f32_16x16x32_bf16 v[24:27], v[92:95], v[28:31], v[24:27]
	v_mfma_f32_16x16x32_bf16 v[28:31], v[84:87], v[36:39], v[104:107]
	v_mfma_f32_16x16x32_bf16 v[32:35], v[92:95], v[36:39], v[32:35]
	v_mfma_f32_16x16x32_bf16 v[36:39], v[84:87], v[44:47], v[108:111]
	v_mfma_f32_16x16x32_bf16 v[40:43], v[92:95], v[44:47], v[40:43]
	s_setprio 0
	v_lshl_add_u64 v[242:243], s[20:21], 0, v[152:153]
	s_mov_b32 m0, s37
	v_lshl_add_u64 v[128:129], v[242:243], 0, s[12:13]
	v_lshl_add_u64 v[244:245], s[20:21], 0, v[156:157]
	s_barrier
	ds_read_b128 v[44:47], v186 offset:16384
	ds_read_b128 v[100:103], v186 offset:17408
	ds_read_b128 v[104:107], v186 offset:18432
	ds_read_b128 v[108:111], v186 offset:19456
	ds_read_b128 v[112:115], v186 offset:20480
	ds_read_b128 v[116:119], v186 offset:21504
	ds_read_b128 v[120:123], v186 offset:22528
	ds_read_b128 v[124:127], v186 offset:23552
	global_load_lds_dwordx4 v[128:129], off
	s_mov_b32 m0, s38
	v_lshl_add_u64 v[128:129], v[244:245], 0, s[12:13]
	global_load_lds_dwordx4 v[128:129], off
	s_barrier
	s_waitcnt lgkmcnt(0)
	s_setprio 1
	v_mfma_f32_16x16x32_bf16 v[128:131], v[0:3], v[44:47], 0
	v_mfma_f32_16x16x32_bf16 v[132:135], v[8:11], v[44:47], 0
	v_mfma_f32_16x16x32_bf16 v[136:139], v[0:3], v[104:107], 0
	v_mfma_f32_16x16x32_bf16 v[140:143], v[8:11], v[104:107], 0
	v_mfma_f32_16x16x32_bf16 v[144:147], v[0:3], v[112:115], 0
	v_mfma_f32_16x16x32_bf16 v[148:151], v[8:11], v[112:115], 0
	v_mfma_f32_16x16x32_bf16 v[0:3], v[0:3], v[120:123], 0
	v_mfma_f32_16x16x32_bf16 v[8:11], v[8:11], v[120:123], 0
	v_mfma_f32_16x16x32_bf16 v[128:131], v[4:7], v[100:103], v[128:131]
	v_mfma_f32_16x16x32_bf16 v[164:167], v[12:15], v[100:103], v[132:135]
	v_mfma_f32_16x16x32_bf16 v[134:137], v[4:7], v[108:111], v[136:139]
	v_mfma_f32_16x16x32_bf16 v[138:141], v[12:15], v[108:111], v[140:143]
	v_mfma_f32_16x16x32_bf16 v[142:145], v[4:7], v[116:119], v[144:147]
	v_mfma_f32_16x16x32_bf16 v[0:3], v[4:7], v[124:127], v[0:3]
	v_mfma_f32_16x16x32_bf16 v[4:7], v[12:15], v[124:127], v[8:11]
	v_mfma_f32_16x16x32_bf16 v[146:149], v[12:15], v[116:119], v[148:151]
	s_setprio 0
	s_barrier
	s_add_u32 s24, s22, 0xb0100
	s_addc_u32 s25, s23, 0
	s_add_i32 s52, s44, s36
	v_lshl_add_u64 v[8:9], s[24:25], 0, v[154:155]
	s_mov_b32 m0, s52
	s_add_i32 s53, s52, 0x2000
	global_load_lds_dwordx4 v[8:9], off
	s_mov_b32 m0, s53
	v_lshl_add_u64 v[8:9], s[24:25], 0, v[158:159]
	global_load_lds_dwordx4 v[8:9], off
	s_waitcnt vmcnt(6)
	s_barrier
	s_setprio 1
	v_mfma_f32_16x16x32_bf16 v[8:11], v[80:83], v[44:47], 0
	v_mfma_f32_16x16x32_bf16 v[12:15], v[88:91], v[44:47], 0
	v_mfma_f32_16x16x32_bf16 v[44:47], v[80:83], v[104:107], 0
	v_mfma_f32_16x16x32_bf16 v[104:107], v[88:91], v[104:107], 0
	v_mfma_f32_16x16x32_bf16 v[168:171], v[80:83], v[112:115], 0
	v_mfma_f32_16x16x32_bf16 v[112:115], v[88:91], v[112:115], 0
	v_mfma_f32_16x16x32_bf16 v[80:83], v[80:83], v[120:123], 0
	v_mfma_f32_16x16x32_bf16 v[88:91], v[88:91], v[120:123], 0
	v_mfma_f32_16x16x32_bf16 v[8:11], v[84:87], v[100:103], v[8:11]
	v_mfma_f32_16x16x32_bf16 v[172:175], v[92:95], v[100:103], v[12:15]
	v_mfma_f32_16x16x32_bf16 v[176:179], v[84:87], v[108:111], v[44:47]
	v_mfma_f32_16x16x32_bf16 v[190:193], v[92:95], v[108:111], v[104:107]
	v_mfma_f32_16x16x32_bf16 v[168:171], v[84:87], v[116:119], v[168:171]
	v_mfma_f32_16x16x32_bf16 v[194:197], v[92:95], v[116:119], v[112:115]
	v_mfma_f32_16x16x32_bf16 v[198:201], v[84:87], v[124:127], v[80:83]
	v_mfma_f32_16x16x32_bf16 v[202:205], v[92:95], v[124:127], v[88:91]
	s_setprio 0
	s_add_i32 s54, 0, 0x18000
	v_add_u32_e32 v132, s54, v183
	s_barrier
	ds_read_b128 v[12:15], v132
	ds_read_b128 v[206:209], v132 offset:1024
	ds_read_b128 v[44:47], v132 offset:2048
	ds_read_b128 v[210:213], v132 offset:3072
	s_add_u32 s24, s20, 0xb0100
	s_addc_u32 s25, s21, 0
	s_mov_b32 m0, s39
	v_lshl_add_u64 v[88:89], s[24:25], 0, v[152:153]
	ds_read_b128 v[80:83], v186 offset:32768
	ds_read_b128 v[84:87], v186 offset:33792
	ds_read_b128 v[100:103], v186 offset:34816
	ds_read_b128 v[214:217], v186 offset:35840
	ds_read_b128 v[120:123], v186 offset:36864
	ds_read_b128 v[222:225], v186 offset:37888
	ds_read_b128 v[124:127], v186 offset:38912
	ds_read_b128 v[226:229], v186 offset:39936
	global_load_lds_dwordx4 v[88:89], off
	s_mov_b32 m0, s40
	v_lshl_add_u64 v[88:89], s[24:25], 0, v[156:157]
	global_load_lds_dwordx4 v[88:89], off
	s_waitcnt lgkmcnt(8)
	s_barrier
	s_waitcnt lgkmcnt(0)
	s_setprio 1
	v_mfma_f32_16x16x32_bf16 v[48:51], v[12:15], v[80:83], v[48:51]
	v_mfma_f32_16x16x32_bf16 v[52:55], v[44:47], v[80:83], v[52:55]
	v_mfma_f32_16x16x32_bf16 v[56:59], v[12:15], v[100:103], v[56:59]
	v_mfma_f32_16x16x32_bf16 v[60:63], v[44:47], v[100:103], v[60:63]
	v_mfma_f32_16x16x32_bf16 v[64:67], v[12:15], v[120:123], v[64:67]
	v_mfma_f32_16x16x32_bf16 v[68:71], v[44:47], v[120:123], v[68:71]
	v_mfma_f32_16x16x32_bf16 v[72:75], v[12:15], v[124:127], v[72:75]
	v_mfma_f32_16x16x32_bf16 v[230:233], v[44:47], v[124:127], v[76:79]
	v_mfma_f32_16x16x32_bf16 v[116:119], v[206:209], v[84:87], v[48:51]
	v_mfma_f32_16x16x32_bf16 v[112:115], v[210:213], v[84:87], v[52:55]
	v_mfma_f32_16x16x32_bf16 v[108:111], v[206:209], v[214:217], v[56:59]
	v_mfma_f32_16x16x32_bf16 v[104:107], v[210:213], v[214:217], v[60:63]
	v_mfma_f32_16x16x32_bf16 v[92:95], v[206:209], v[222:225], v[64:67]
	v_mfma_f32_16x16x32_bf16 v[88:91], v[210:213], v[222:225], v[68:71]
	v_mfma_f32_16x16x32_bf16 v[76:79], v[206:209], v[226:229], v[72:75]
	v_mfma_f32_16x16x32_bf16 v[72:75], v[210:213], v[226:229], v[230:233]
	s_setprio 0
	s_barrier
	s_add_i32 s56, 0, 0x1c000
	s_add_i32 s54, s54, s36
	v_add_u32_e32 v133, s56, v183
	v_lshl_add_u64 v[48:49], v[180:181], 0, s[14:15]
	s_mov_b32 m0, s54
	s_add_i32 s55, s54, 0x2000
	ds_read_b128 v[56:59], v133
	ds_read_b128 v[230:233], v133 offset:1024
	ds_read_b128 v[60:63], v133 offset:2048
	ds_read_b128 v[234:237], v133 offset:3072
	global_load_lds_dwordx4 v[48:49], off
	s_mov_b32 m0, s55
	v_lshl_add_u64 v[48:49], v[218:219], 0, s[14:15]
	global_load_lds_dwordx4 v[48:49], off
	s_barrier
	s_waitcnt lgkmcnt(0)
	s_setprio 1
	v_mfma_f32_16x16x32_bf16 v[48:51], v[56:59], v[80:83], v[96:99]
	v_mfma_f32_16x16x32_bf16 v[16:19], v[60:63], v[80:83], v[16:19]
	v_mfma_f32_16x16x32_bf16 v[20:23], v[56:59], v[100:103], v[20:23]
	v_mfma_f32_16x16x32_bf16 v[24:27], v[60:63], v[100:103], v[24:27]
	v_mfma_f32_16x16x32_bf16 v[28:31], v[56:59], v[120:123], v[28:31]
	v_mfma_f32_16x16x32_bf16 v[32:35], v[60:63], v[120:123], v[32:35]
	v_mfma_f32_16x16x32_bf16 v[36:39], v[56:59], v[124:127], v[36:39]
	v_mfma_f32_16x16x32_bf16 v[40:43], v[60:63], v[124:127], v[40:43]
	v_mfma_f32_16x16x32_bf16 v[124:127], v[230:233], v[84:87], v[48:51]
	v_mfma_f32_16x16x32_bf16 v[120:123], v[234:237], v[84:87], v[16:19]
	v_mfma_f32_16x16x32_bf16 v[100:103], v[230:233], v[214:217], v[20:23]
	v_mfma_f32_16x16x32_bf16 v[96:99], v[234:237], v[214:217], v[24:27]
	v_mfma_f32_16x16x32_bf16 v[84:87], v[230:233], v[222:225], v[28:31]
	v_mfma_f32_16x16x32_bf16 v[80:83], v[234:237], v[222:225], v[32:35]
	v_mfma_f32_16x16x32_bf16 v[68:71], v[230:233], v[226:229], v[36:39]
	v_mfma_f32_16x16x32_bf16 v[64:67], v[234:237], v[226:229], v[40:43]
	s_setprio 0
	s_mov_b32 m0, s42
	v_lshl_add_u64 v[20:21], v[242:243], 0, s[14:15]
	s_barrier
	ds_read_b128 v[16:19], v186 offset:49152
	ds_read_b128 v[24:27], v186 offset:50176
	ds_read_b128 v[32:35], v186 offset:51200
	ds_read_b128 v[214:217], v186 offset:52224
	ds_read_b128 v[40:43], v186 offset:53248
	ds_read_b128 v[222:225], v186 offset:54272
	ds_read_b128 v[226:229], v186 offset:55296
	ds_read_b128 v[238:241], v186 offset:56320
	global_load_lds_dwordx4 v[20:21], off
	s_mov_b32 m0, s43
	v_lshl_add_u64 v[20:21], v[244:245], 0, s[14:15]
	global_load_lds_dwordx4 v[20:21], off
	s_barrier
;     __device__ __forceinline__ bool unit(int L, Unit& u) const { u.g = L; return order_mn(L, T / 256, NGU / 256, u.pm, u.pn); }
;     __device__ __forceinline__ bool unit(int L, Unit& u) const { u.g = L; return order_mn(L, T / 256, D / 256, u.pm, u.pn); }
;     __device__ __forceinline__ bool unit(int L, Unit& u) const { u.g = 0; return order_mn(L, T / 256, 8, u.pm, u.pn); }
;     __device__ __forceinline__ bool unit(int L, Unit& u) const { if (L >= NG * 4) return false; u.g = L >> 2; u.pm = (L >> 1) & 1; u.pn = L & 1; return true; }
;     __device__ __forceinline__ bool unit(int L, Unit& u) const { if (L >= NG * 8) return false; u.g = L >> 3; u.pm = (L >> 2) & 1; u.pn = L & 3; return true; }
;     ...
;         const bool has_next = p.unit((ui + 1) * G + c, nxt);
;         const char* nA = has_next ? p.a0(nxt) : cA; const char* nB = has_next ? p.b0(nxt) : cB;
;         const char* nA2 = P::SEG ? (has_next ? p.a1(nxt) : cA2) : nA; const char* nB2 = P::SEG ? (has_next ? p.b1(nxt) : cB2) : nB;
	s_waitcnt lgkmcnt(0)
	s_setprio 1
	v_mfma_f32_16x16x32_bf16 v[20:23], v[12:15], v[16:19], v[128:131]
	v_mfma_f32_16x16x32_bf16 v[28:31], v[44:47], v[16:19], v[164:167]
	v_mfma_f32_16x16x32_bf16 v[36:39], v[12:15], v[32:35], v[134:137]
	v_mfma_f32_16x16x32_bf16 v[128:131], v[44:47], v[32:35], v[138:141]
	v_mfma_f32_16x16x32_bf16 v[134:137], v[12:15], v[40:43], v[142:145]
	v_mfma_f32_16x16x32_bf16 v[138:141], v[44:47], v[40:43], v[146:149]
	v_mfma_f32_16x16x32_bf16 v[0:3], v[12:15], v[226:229], v[0:3]
	v_mfma_f32_16x16x32_bf16 v[4:7], v[44:47], v[226:229], v[4:7]
	v_mfma_f32_16x16x32_bf16 v[52:55], v[206:209], v[24:27], v[20:23]
	v_mfma_f32_16x16x32_bf16 v[48:51], v[210:213], v[24:27], v[28:31]
	v_mfma_f32_16x16x32_bf16 v[44:47], v[206:209], v[214:217], v[36:39]
	v_mfma_f32_16x16x32_bf16 v[36:39], v[210:213], v[214:217], v[128:131]
	v_mfma_f32_16x16x32_bf16 v[28:31], v[206:209], v[222:225], v[134:137]
	v_mfma_f32_16x16x32_bf16 v[20:23], v[210:213], v[222:225], v[138:141]
	v_mfma_f32_16x16x32_bf16 v[12:15], v[206:209], v[238:241], v[0:3]
	v_mfma_f32_16x16x32_bf16 v[4:7], v[210:213], v[238:241], v[4:7]
	s_setprio 0
	s_barrier
	s_add_u32 s24, s22, 0xb0180
	s_addc_u32 s25, s23, 0
	s_add_i32 s56, s56, s36
	v_lshl_add_u64 v[0:1], s[24:25], 0, v[154:155]
	s_mov_b32 m0, s56
	s_add_i32 s57, s56, 0x2000
	global_load_lds_dwordx4 v[0:1], off
	v_lshl_add_u64 v[0:1], s[24:25], 0, v[158:159]
	s_mov_b32 m0, s57
	s_mov_b64 s[24:25], 0xb0180
	global_load_lds_dwordx4 v[0:1], off
	s_waitcnt vmcnt(6)
	s_barrier
	s_setprio 1
	v_mfma_f32_16x16x32_bf16 v[0:3], v[56:59], v[16:19], v[8:11]
	v_mfma_f32_16x16x32_bf16 v[8:11], v[60:63], v[16:19], v[172:175]
	v_mfma_f32_16x16x32_bf16 v[16:19], v[56:59], v[32:35], v[176:179]
	v_mfma_f32_16x16x32_bf16 v[32:35], v[60:63], v[32:35], v[190:193]
	v_mfma_f32_16x16x32_bf16 v[128:131], v[56:59], v[40:43], v[168:171]
	v_mfma_f32_16x16x32_bf16 v[134:137], v[60:63], v[40:43], v[194:197]
	v_mfma_f32_16x16x32_bf16 v[138:141], v[56:59], v[226:229], v[198:201]
	v_mfma_f32_16x16x32_bf16 v[142:145], v[60:63], v[226:229], v[202:205]
	v_mfma_f32_16x16x32_bf16 v[60:63], v[230:233], v[24:27], v[0:3]
	v_mfma_f32_16x16x32_bf16 v[56:59], v[234:237], v[24:27], v[8:11]
	v_mfma_f32_16x16x32_bf16 v[40:43], v[230:233], v[214:217], v[16:19]
	v_mfma_f32_16x16x32_bf16 v[32:35], v[234:237], v[214:217], v[32:35]
	v_mfma_f32_16x16x32_bf16 v[24:27], v[230:233], v[222:225], v[128:131]
	v_mfma_f32_16x16x32_bf16 v[16:19], v[234:237], v[222:225], v[134:137]
	v_mfma_f32_16x16x32_bf16 v[8:11], v[230:233], v[238:241], v[138:141]
	v_mfma_f32_16x16x32_bf16 v[0:3], v[234:237], v[238:241], v[142:145]
	s_setprio 0
	v_lshl_add_u64 v[128:129], s[20:21], 0, v[160:161]
	v_lshl_add_u64 v[130:131], s[20:21], 0, v[162:163]
	s_mov_b32 s58, 0
	s_barrier
.LBB0_1906:
	ds_read_b128 v[134:137], v185
	ds_read_b128 v[138:141], v185 offset:1024
	ds_read_b128 v[142:145], v185 offset:2048
	ds_read_b128 v[146:149], v185 offset:3072
	s_mov_b32 m0, s45
	v_lshl_add_u64 v[150:151], v[128:129], 0, s[24:25]
	ds_read_b128 v[164:167], v186
	ds_read_b128 v[168:171], v186 offset:1024
	ds_read_b128 v[172:175], v186 offset:2048
	ds_read_b128 v[176:179], v186 offset:3072
	ds_read_b128 v[190:193], v186 offset:4096
	ds_read_b128 v[194:197], v186 offset:5120
	ds_read_b128 v[198:201], v186 offset:6144
	ds_read_b128 v[202:205], v186 offset:7168
	global_load_lds_dwordx4 v[150:151], off
	s_mov_b32 m0, s46
	v_lshl_add_u64 v[150:151], v[130:131], 0, s[24:25]
	global_load_lds_dwordx4 v[150:151], off
	s_waitcnt lgkmcnt(8)
	s_barrier
	s_waitcnt lgkmcnt(0)
	s_setprio 1
	v_mfma_f32_16x16x32_bf16 v[116:119], v[134:137], v[164:167], v[116:119]
	s_add_i32 s26, s24, 0xfff50080
	v_mfma_f32_16x16x32_bf16 v[112:115], v[142:145], v[164:167], v[112:115]
	s_cmp_eq_u32 s58, 40
	v_mfma_f32_16x16x32_bf16 v[108:111], v[134:137], v[172:175], v[108:111]
	s_cselect_b32 s59, s19, s21
	v_mfma_f32_16x16x32_bf16 v[104:107], v[142:145], v[172:175], v[104:107]
	s_cselect_b32 s60, s18, s20
	v_mfma_f32_16x16x32_bf16 v[92:95], v[134:137], v[190:193], v[92:95]
	s_cselect_b32 s27, s7, s23
	v_mfma_f32_16x16x32_bf16 v[88:91], v[142:145], v[190:193], v[88:91]
	s_cselect_b32 s61, s6, s22
	v_mfma_f32_16x16x32_bf16 v[76:79], v[134:137], v[198:201], v[76:79]
	v_mfma_f32_16x16x32_bf16 v[72:75], v[142:145], v[198:201], v[72:75]
	v_mfma_f32_16x16x32_bf16 v[116:119], v[138:141], v[168:171], v[116:119]
	v_mfma_f32_16x16x32_bf16 v[112:115], v[146:149], v[168:171], v[112:115]
	v_mfma_f32_16x16x32_bf16 v[108:111], v[138:141], v[176:179], v[108:111]
	v_mfma_f32_16x16x32_bf16 v[104:107], v[146:149], v[176:179], v[104:107]
	v_mfma_f32_16x16x32_bf16 v[92:95], v[138:141], v[194:197], v[92:95]
	v_mfma_f32_16x16x32_bf16 v[88:91], v[146:149], v[194:197], v[88:91]
	v_mfma_f32_16x16x32_bf16 v[76:79], v[138:141], v[202:205], v[76:79]
	v_mfma_f32_16x16x32_bf16 v[72:75], v[146:149], v[202:205], v[72:75]
	s_setprio 0
	s_barrier
	s_cselect_b32 s62, 0, s26
	s_add_u32 s26, s61, s62
	s_addc_u32 s27, s27, 0
	s_mov_b32 m0, s47
	v_lshl_add_u64 v[150:151], s[26:27], 0, v[154:155]
	ds_read_b128 v[206:209], v187
	ds_read_b128 v[210:213], v187 offset:1024
	ds_read_b128 v[214:217], v187 offset:2048
	ds_read_b128 v[222:225], v187 offset:3072
	global_load_lds_dwordx4 v[150:151], off
	s_mov_b32 m0, s48
	v_lshl_add_u64 v[180:181], s[26:27], 0, v[158:159]
	global_load_lds_dwordx4 v[180:181], off
	s_barrier
	s_waitcnt lgkmcnt(0)
	s_setprio 1
	v_mfma_f32_16x16x32_bf16 v[124:127], v[206:209], v[164:167], v[124:127]
	v_mfma_f32_16x16x32_bf16 v[120:123], v[214:217], v[164:167], v[120:123]
	v_mfma_f32_16x16x32_bf16 v[100:103], v[206:209], v[172:175], v[100:103]
	v_mfma_f32_16x16x32_bf16 v[96:99], v[214:217], v[172:175], v[96:99]
	v_mfma_f32_16x16x32_bf16 v[84:87], v[206:209], v[190:193], v[84:87]
	v_mfma_f32_16x16x32_bf16 v[80:83], v[214:217], v[190:193], v[80:83]
	v_mfma_f32_16x16x32_bf16 v[68:71], v[206:209], v[198:201], v[68:71]
	v_mfma_f32_16x16x32_bf16 v[64:67], v[214:217], v[198:201], v[64:67]
	v_mfma_f32_16x16x32_bf16 v[124:127], v[210:213], v[168:171], v[124:127]
	v_mfma_f32_16x16x32_bf16 v[120:123], v[222:225], v[168:171], v[120:123]
	v_mfma_f32_16x16x32_bf16 v[100:103], v[210:213], v[176:179], v[100:103]
	v_mfma_f32_16x16x32_bf16 v[96:99], v[222:225], v[176:179], v[96:99]
	v_mfma_f32_16x16x32_bf16 v[84:87], v[210:213], v[194:197], v[84:87]
	v_mfma_f32_16x16x32_bf16 v[80:83], v[222:225], v[194:197], v[80:83]
	v_mfma_f32_16x16x32_bf16 v[68:71], v[210:213], v[202:205], v[68:71]
	v_mfma_f32_16x16x32_bf16 v[64:67], v[222:225], v[202:205], v[64:67]
	s_setprio 0
	s_add_u32 s60, s60, s62
	s_addc_u32 s61, s59, 0
	s_mov_b32 m0, s37
	v_lshl_add_u64 v[218:219], s[60:61], 0, v[152:153]
	s_barrier
	ds_read_b128 v[164:167], v186 offset:16384
	ds_read_b128 v[168:171], v186 offset:17408
	ds_read_b128 v[172:175], v186 offset:18432
	ds_read_b128 v[176:179], v186 offset:19456
	ds_read_b128 v[190:193], v186 offset:20480
	ds_read_b128 v[194:197], v186 offset:21504
	ds_read_b128 v[198:201], v186 offset:22528
	ds_read_b128 v[202:205], v186 offset:23552
	global_load_lds_dwordx4 v[218:219], off
	s_mov_b32 m0, s38
	v_lshl_add_u64 v[226:227], s[60:61], 0, v[156:157]
	global_load_lds_dwordx4 v[226:227], off
	s_barrier
	s_waitcnt lgkmcnt(0)
	s_setprio 1
	v_mfma_f32_16x16x32_bf16 v[52:55], v[134:137], v[164:167], v[52:55]
	v_mfma_f32_16x16x32_bf16 v[48:51], v[142:145], v[164:167], v[48:51]
	v_mfma_f32_16x16x32_bf16 v[44:47], v[134:137], v[172:175], v[44:47]
	v_mfma_f32_16x16x32_bf16 v[36:39], v[142:145], v[172:175], v[36:39]
	v_mfma_f32_16x16x32_bf16 v[28:31], v[134:137], v[190:193], v[28:31]
	v_mfma_f32_16x16x32_bf16 v[20:23], v[142:145], v[190:193], v[20:23]
	v_mfma_f32_16x16x32_bf16 v[12:15], v[134:137], v[198:201], v[12:15]
	v_mfma_f32_16x16x32_bf16 v[4:7], v[142:145], v[198:201], v[4:7]
	v_mfma_f32_16x16x32_bf16 v[52:55], v[138:141], v[168:171], v[52:55]
	v_mfma_f32_16x16x32_bf16 v[48:51], v[146:149], v[168:171], v[48:51]
	v_mfma_f32_16x16x32_bf16 v[44:47], v[138:141], v[176:179], v[44:47]
	v_mfma_f32_16x16x32_bf16 v[36:39], v[146:149], v[176:179], v[36:39]
	v_mfma_f32_16x16x32_bf16 v[28:31], v[138:141], v[194:197], v[28:31]
	v_mfma_f32_16x16x32_bf16 v[20:23], v[146:149], v[194:197], v[20:23]
	v_mfma_f32_16x16x32_bf16 v[12:15], v[138:141], v[202:205], v[12:15]
	v_mfma_f32_16x16x32_bf16 v[4:7], v[146:149], v[202:205], v[4:7]
	s_setprio 0
	s_barrier
	s_add_u32 s62, s26, 0xb0000
	s_addc_u32 s63, s27, 0
	s_mov_b32 m0, s52
	v_lshl_add_u64 v[134:135], s[62:63], 0, v[154:155]
	global_load_lds_dwordx4 v[134:135], off
	s_mov_b32 m0, s53
	v_lshl_add_u64 v[134:135], s[62:63], 0, v[158:159]
	global_load_lds_dwordx4 v[134:135], off
	s_waitcnt vmcnt(6)
	s_barrier
	s_setprio 1
	v_mfma_f32_16x16x32_bf16 v[60:63], v[206:209], v[164:167], v[60:63]
	v_mfma_f32_16x16x32_bf16 v[56:59], v[214:217], v[164:167], v[56:59]
	v_mfma_f32_16x16x32_bf16 v[40:43], v[206:209], v[172:175], v[40:43]
	v_mfma_f32_16x16x32_bf16 v[32:35], v[214:217], v[172:175], v[32:35]
	v_mfma_f32_16x16x32_bf16 v[24:27], v[206:209], v[190:193], v[24:27]
	v_mfma_f32_16x16x32_bf16 v[16:19], v[214:217], v[190:193], v[16:19]
	v_mfma_f32_16x16x32_bf16 v[8:11], v[206:209], v[198:201], v[8:11]
	v_mfma_f32_16x16x32_bf16 v[0:3], v[214:217], v[198:201], v[0:3]
	v_mfma_f32_16x16x32_bf16 v[60:63], v[210:213], v[168:171], v[60:63]
	v_mfma_f32_16x16x32_bf16 v[56:59], v[222:225], v[168:171], v[56:59]
	v_mfma_f32_16x16x32_bf16 v[40:43], v[210:213], v[176:179], v[40:43]
	v_mfma_f32_16x16x32_bf16 v[32:35], v[222:225], v[176:179], v[32:35]
	v_mfma_f32_16x16x32_bf16 v[24:27], v[210:213], v[194:197], v[24:27]
	v_mfma_f32_16x16x32_bf16 v[16:19], v[222:225], v[194:197], v[16:19]
	v_mfma_f32_16x16x32_bf16 v[8:11], v[210:213], v[202:205], v[8:11]
	v_mfma_f32_16x16x32_bf16 v[0:3], v[222:225], v[202:205], v[0:3]
	s_setprio 0
	s_barrier
	ds_read_b128 v[134:137], v132
	ds_read_b128 v[138:141], v132 offset:1024
	ds_read_b128 v[142:145], v132 offset:2048
	ds_read_b128 v[146:149], v132 offset:3072
	s_add_u32 s60, s60, 0xb0000
	s_addc_u32 s61, s61, 0
	s_mov_b32 m0, s39
	v_lshl_add_u64 v[206:207], s[60:61], 0, v[152:153]
	ds_read_b128 v[164:167], v186 offset:32768
	ds_read_b128 v[168:171], v186 offset:33792
	ds_read_b128 v[172:175], v186 offset:34816
	ds_read_b128 v[176:179], v186 offset:35840
	ds_read_b128 v[190:193], v186 offset:36864
	ds_read_b128 v[194:197], v186 offset:37888
	ds_read_b128 v[198:201], v186 offset:38912
	ds_read_b128 v[202:205], v186 offset:39936
	global_load_lds_dwordx4 v[206:207], off
	s_mov_b32 m0, s40
	v_lshl_add_u64 v[206:207], s[60:61], 0, v[156:157]
	global_load_lds_dwordx4 v[206:207], off
	s_waitcnt lgkmcnt(8)
	s_barrier
	s_waitcnt lgkmcnt(0)
	s_setprio 1
	v_mfma_f32_16x16x32_bf16 v[116:119], v[134:137], v[164:167], v[116:119]
	v_mfma_f32_16x16x32_bf16 v[112:115], v[142:145], v[164:167], v[112:115]
	v_mfma_f32_16x16x32_bf16 v[108:111], v[134:137], v[172:175], v[108:111]
	v_mfma_f32_16x16x32_bf16 v[104:107], v[142:145], v[172:175], v[104:107]
	v_mfma_f32_16x16x32_bf16 v[92:95], v[134:137], v[190:193], v[92:95]
	v_mfma_f32_16x16x32_bf16 v[88:91], v[142:145], v[190:193], v[88:91]
	v_mfma_f32_16x16x32_bf16 v[76:79], v[134:137], v[198:201], v[76:79]
	v_mfma_f32_16x16x32_bf16 v[72:75], v[142:145], v[198:201], v[72:75]
	v_mfma_f32_16x16x32_bf16 v[116:119], v[138:141], v[168:171], v[116:119]
	v_mfma_f32_16x16x32_bf16 v[112:115], v[146:149], v[168:171], v[112:115]
	v_mfma_f32_16x16x32_bf16 v[108:111], v[138:141], v[176:179], v[108:111]
	v_mfma_f32_16x16x32_bf16 v[104:107], v[146:149], v[176:179], v[104:107]
	v_mfma_f32_16x16x32_bf16 v[92:95], v[138:141], v[194:197], v[92:95]
	v_mfma_f32_16x16x32_bf16 v[88:91], v[146:149], v[194:197], v[88:91]
	v_mfma_f32_16x16x32_bf16 v[76:79], v[138:141], v[202:205], v[76:79]
	v_mfma_f32_16x16x32_bf16 v[72:75], v[146:149], v[202:205], v[72:75]
	s_setprio 0
	s_barrier
	s_mov_b32 m0, s54
	v_lshl_add_u64 v[150:151], v[150:151], 0, s[10:11]
	ds_read_b128 v[206:209], v133
	ds_read_b128 v[210:213], v133 offset:1024
	ds_read_b128 v[214:217], v133 offset:2048
	ds_read_b128 v[222:225], v133 offset:3072
	global_load_lds_dwordx4 v[150:151], off
	s_mov_b32 m0, s55
	v_lshl_add_u64 v[150:151], v[180:181], 0, s[10:11]
	global_load_lds_dwordx4 v[150:151], off
	s_barrier
	s_waitcnt lgkmcnt(0)
	s_setprio 1
	v_mfma_f32_16x16x32_bf16 v[124:127], v[206:209], v[164:167], v[124:127]
	v_mfma_f32_16x16x32_bf16 v[120:123], v[214:217], v[164:167], v[120:123]
	v_mfma_f32_16x16x32_bf16 v[100:103], v[206:209], v[172:175], v[100:103]
	v_mfma_f32_16x16x32_bf16 v[96:99], v[214:217], v[172:175], v[96:99]
	v_mfma_f32_16x16x32_bf16 v[84:87], v[206:209], v[190:193], v[84:87]
	v_mfma_f32_16x16x32_bf16 v[80:83], v[214:217], v[190:193], v[80:83]
	v_mfma_f32_16x16x32_bf16 v[68:71], v[206:209], v[198:201], v[68:71]
	v_mfma_f32_16x16x32_bf16 v[64:67], v[214:217], v[198:201], v[64:67]
	v_mfma_f32_16x16x32_bf16 v[124:127], v[210:213], v[168:171], v[124:127]
	v_mfma_f32_16x16x32_bf16 v[120:123], v[222:225], v[168:171], v[120:123]
	v_mfma_f32_16x16x32_bf16 v[100:103], v[210:213], v[176:179], v[100:103]
	v_mfma_f32_16x16x32_bf16 v[96:99], v[222:225], v[176:179], v[96:99]
	v_mfma_f32_16x16x32_bf16 v[84:87], v[210:213], v[194:197], v[84:87]
	v_mfma_f32_16x16x32_bf16 v[80:83], v[222:225], v[194:197], v[80:83]
	v_mfma_f32_16x16x32_bf16 v[68:71], v[210:213], v[202:205], v[68:71]
	v_mfma_f32_16x16x32_bf16 v[64:67], v[222:225], v[202:205], v[64:67]
	s_setprio 0
	s_mov_b32 m0, s42
	v_lshl_add_u64 v[150:151], v[218:219], 0, s[10:11]
	s_barrier
	ds_read_b128 v[164:167], v186 offset:49152
	ds_read_b128 v[168:171], v186 offset:50176
	ds_read_b128 v[172:175], v186 offset:51200
	ds_read_b128 v[176:179], v186 offset:52224
	ds_read_b128 v[190:193], v186 offset:53248
	ds_read_b128 v[194:197], v186 offset:54272
	ds_read_b128 v[198:201], v186 offset:55296
	ds_read_b128 v[202:205], v186 offset:56320
	global_load_lds_dwordx4 v[150:151], off
	s_mov_b32 m0, s43
	v_lshl_add_u64 v[150:151], v[226:227], 0, s[10:11]
	global_load_lds_dwordx4 v[150:151], off
	s_barrier
	s_waitcnt lgkmcnt(0)
	s_setprio 1
	v_mfma_f32_16x16x32_bf16 v[52:55], v[134:137], v[164:167], v[52:55]
	v_mfma_f32_16x16x32_bf16 v[48:51], v[142:145], v[164:167], v[48:51]
	v_mfma_f32_16x16x32_bf16 v[44:47], v[134:137], v[172:175], v[44:47]
	v_mfma_f32_16x16x32_bf16 v[36:39], v[142:145], v[172:175], v[36:39]
	v_mfma_f32_16x16x32_bf16 v[28:31], v[134:137], v[190:193], v[28:31]
	v_mfma_f32_16x16x32_bf16 v[20:23], v[142:145], v[190:193], v[20:23]
	v_mfma_f32_16x16x32_bf16 v[12:15], v[134:137], v[198:201], v[12:15]
	v_mfma_f32_16x16x32_bf16 v[4:7], v[142:145], v[198:201], v[4:7]
	v_mfma_f32_16x16x32_bf16 v[52:55], v[138:141], v[168:171], v[52:55]
	v_mfma_f32_16x16x32_bf16 v[48:51], v[146:149], v[168:171], v[48:51]
	v_mfma_f32_16x16x32_bf16 v[44:47], v[138:141], v[176:179], v[44:47]
	v_mfma_f32_16x16x32_bf16 v[36:39], v[146:149], v[176:179], v[36:39]
	v_mfma_f32_16x16x32_bf16 v[28:31], v[138:141], v[194:197], v[28:31]
	v_mfma_f32_16x16x32_bf16 v[20:23], v[146:149], v[194:197], v[20:23]
	v_mfma_f32_16x16x32_bf16 v[12:15], v[138:141], v[202:205], v[12:15]
	v_mfma_f32_16x16x32_bf16 v[4:7], v[146:149], v[202:205], v[4:7]
	s_setprio 0
	s_barrier
	s_add_u32 s26, s26, 0xb0080
	s_addc_u32 s27, s27, 0
	s_mov_b32 m0, s56
	v_lshl_add_u64 v[134:135], s[26:27], 0, v[154:155]
	global_load_lds_dwordx4 v[134:135], off
	s_mov_b32 m0, s57
	v_lshl_add_u64 v[134:135], s[26:27], 0, v[158:159]
	global_load_lds_dwordx4 v[134:135], off
	s_waitcnt vmcnt(6)
	s_barrier
; __device__ __forceinline__ unsigned pk2(float lo, float hi) { unsigned r; asm volatile("v_cvt_pk_bf16_f32 %0, %1, %2" : "=v"(r) : "v"(lo), "v"(hi)); return r; }
; __device__ __forceinline__ unsigned pk2(float lo, float hi) { return f2bf(lo) | (f2bf(hi) << 16); }
;     ...
;         G_PAIR(0, 1);
; #pragma unroll 1
;         for (int t = 2; t < nt; t += 2) G_PAIR(t, 0);
;     __device__ __forceinline__ void epi(const f32x4 (&acc)[2][2][4][2], const Unit& u, int wr, int wc, int fr, int fq) const {
;         if ((PROBE & 64) && coef == 0.f) { dry_epi(acc, pool, rowss); return; }
;         ConvHost<3> ch; ch.begin(cj, u.g, 22, wr * 4 + wc, fq * 16 + fr);
;         const int row0 = u.pm * 256 + wr * 64 + fr, col0 = u.pn * 256 + wc * 32 + 8 * fq;
; #pragma unroll
;         for (int ai = 0; ai < 2; ++ai) {
;             u32x4 xo[4][2];
; #pragma unroll
;             for (int m = 0; m < 4; ++m)
; #pragma unroll
;                 for (int bj = 0; bj < 2; ++bj) xo[m][bj] = *(const u32x4*)(xb + (size_t)(row0 + ai * 128 + m * 16) * D + col0 + bj * 128);
; #pragma unroll
;             for (int m = 0; m < 4; ++m) {
;                 const int row = row0 + ai * 128 + m * 16; const size_t off = (size_t)row * D + col0; float ss = 0.f;
; #pragma unroll
;                 for (int bj = 0; bj < 2; ++bj) {
;                     const u32x4 o = xo[m][bj]; const f32x4 a0v = acc[ai][bj][m][0], a1v = acc[ai][bj][m][1];
;                     const float v0 = bf_lo(o.x) + coef * a0v[0], v1 = bf_hi(o.x) + coef * a0v[1], v2 = bf_lo(o.y) + coef * a0v[2], v3 = bf_hi(o.y) + coef * a0v[3];
;                     const float v4 = bf_lo(o.z) + coef * a1v[0], v5 = bf_hi(o.z) + coef * a1v[1], v6 = bf_lo(o.w) + coef * a1v[2], v7 = bf_hi(o.w) + coef * a1v[3];
;                     u32x4 w; w.x = pk2(v0, v1); w.y = pk2(v2, v3); w.z = pk2(v4, v5); w.w = pk2(v6, v7);
;                     *(u32x4*)(xb + off + bj * 128) = w;
;                     ss += ((v0 * v0 + v1 * v1) + (v2 * v2 + v3 * v3)) + ((v4 * v4 + v5 * v5) + (v6 * v6 + v7 * v7));
;                 }
;                 ss += __shfl_xor(ss, 16); ss += __shfl_xor(ss, 32);
;                 if (fq == 0) rowss[(size_t)row * 32 + u.pn * 4 + wc] = ss;
;             }
	s_setprio 1
	v_mfma_f32_16x16x32_bf16 v[60:63], v[206:209], v[164:167], v[60:63]
	v_mfma_f32_16x16x32_bf16 v[56:59], v[214:217], v[164:167], v[56:59]
	v_mfma_f32_16x16x32_bf16 v[40:43], v[206:209], v[172:175], v[40:43]
	v_mfma_f32_16x16x32_bf16 v[32:35], v[214:217], v[172:175], v[32:35]
	v_mfma_f32_16x16x32_bf16 v[24:27], v[206:209], v[190:193], v[24:27]
	v_mfma_f32_16x16x32_bf16 v[16:19], v[214:217], v[190:193], v[16:19]
	v_mfma_f32_16x16x32_bf16 v[8:11], v[206:209], v[198:201], v[8:11]
	v_mfma_f32_16x16x32_bf16 v[0:3], v[214:217], v[198:201], v[0:3]
	v_mfma_f32_16x16x32_bf16 v[60:63], v[210:213], v[168:171], v[60:63]
	v_mfma_f32_16x16x32_bf16 v[56:59], v[222:225], v[168:171], v[56:59]
	v_mfma_f32_16x16x32_bf16 v[40:43], v[210:213], v[176:179], v[40:43]
	v_mfma_f32_16x16x32_bf16 v[32:35], v[222:225], v[176:179], v[32:35]
	v_mfma_f32_16x16x32_bf16 v[24:27], v[210:213], v[194:197], v[24:27]
	v_mfma_f32_16x16x32_bf16 v[16:19], v[222:225], v[194:197], v[16:19]
	v_mfma_f32_16x16x32_bf16 v[8:11], v[210:213], v[202:205], v[8:11]
	v_mfma_f32_16x16x32_bf16 v[0:3], v[222:225], v[202:205], v[0:3]
	s_setprio 0
	s_add_i32 s58, s58, 2
	s_add_u32 s24, s24, 0x100
	s_addc_u32 s25, s25, 0
	s_cmp_gt_u32 s58, 41
	s_barrier
	s_cbranch_scc0 .LBB0_1906
	v_lshl_or_b32 v164, s30, 8, v184
	v_lshl_add_u32 v168, s2, 8, v182
	v_ashrrev_i32_e32 v165, 31, v164
	v_lshlrev_b64 v[198:199], 1, v[164:165]
	v_ashrrev_i32_e32 v169, 31, v168
	v_lshl_add_u64 v[166:167], s[0:1], 0, v[198:199]
	v_lshlrev_b64 v[200:201], 11, v[168:169]
	v_lshl_add_u64 v[128:129], v[166:167], 0, v[200:201]
	global_load_dwordx4 v[190:193], v[128:129], off
	global_load_dwordx4 v[194:197], v[128:129], off offset:256
	v_or_b32_e32 v178, 16, v168
	v_or_b32_e32 v174, 32, v168
	v_or_b32_e32 v170, 48, v168
	v_ashrrev_i32_e32 v179, 31, v178
	v_ashrrev_i32_e32 v175, 31, v174
	v_ashrrev_i32_e32 v171, 31, v170
	v_lshlrev_b64 v[180:181], 11, v[178:179]
	v_lshlrev_b64 v[176:177], 11, v[174:175]
	v_lshlrev_b64 v[172:173], 11, v[170:171]
	v_lshl_add_u64 v[128:129], v[166:167], 0, v[180:181]
	v_lshl_add_u64 v[130:131], v[166:167], 0, v[176:177]
	v_lshl_add_u64 v[202:203], v[166:167], 0, v[172:173]
	global_load_dwordx4 v[148:151], v[128:129], off
	global_load_dwordx4 v[144:147], v[128:129], off offset:256
	global_load_dwordx4 v[140:143], v[130:131], off
	global_load_dwordx4 v[136:139], v[130:131], off offset:256
	global_load_dwordx4 v[132:135], v[202:203], off
	s_nop 0
	global_load_dwordx4 v[128:131], v[202:203], off offset:256
	v_and_b32_e32 v202, 64, v188
	v_xor_b32_e32 v189, 16, v188
	v_add_u32_e32 v202, 64, v202
	v_cmp_lt_i32_e32 vcc, v189, v202
	s_waitcnt vmcnt(0)
	v_lshlrev_b32_e32 v203, 16, v190
	v_and_b32_e32 v190, 0xffff0000, v190
	v_lshlrev_b32_e32 v204, 16, v191
	v_and_b32_e32 v191, 0xffff0000, v191
	v_lshlrev_b32_e32 v205, 16, v192
	v_and_b32_e32 v192, 0xffff0000, v192
	v_lshlrev_b32_e32 v206, 16, v193
	v_and_b32_e32 v193, 0xffff0000, v193
	v_lshlrev_b32_e32 v207, 16, v194
	v_and_b32_e32 v194, 0xffff0000, v194
	v_lshlrev_b32_e32 v208, 16, v195
	v_and_b32_e32 v195, 0xffff0000, v195
	v_lshlrev_b32_e32 v209, 16, v196
	v_and_b32_e32 v196, 0xffff0000, v196
	v_lshlrev_b32_e32 v210, 16, v197
	v_and_b32_e32 v197, 0xffff0000, v197
	v_fmac_f32_e32 v190, 0.5, v117
	v_fmac_f32_e32 v191, 0.5, v119
	v_fmac_f32_e32 v192, 0.5, v113
	v_fmac_f32_e32 v193, 0.5, v115
	v_fmac_f32_e32 v194, 0.5, v125
	v_fmac_f32_e32 v195, 0.5, v127
	v_fmac_f32_e32 v196, 0.5, v121
	v_fmac_f32_e32 v197, 0.5, v123
	v_fmac_f32_e32 v203, 0.5, v116
	v_fmac_f32_e32 v204, 0.5, v118
	v_fmac_f32_e32 v205, 0.5, v112
	v_fmac_f32_e32 v206, 0.5, v114
	v_fmac_f32_e32 v207, 0.5, v124
	v_fmac_f32_e32 v208, 0.5, v126
	v_fmac_f32_e32 v209, 0.5, v120
	v_fmac_f32_e32 v210, 0.5, v122
	v_mul_f32_e32 v112, v190, v190
	v_mul_f32_e32 v113, v191, v191
	v_mul_f32_e32 v118, v192, v192
	v_mul_f32_e32 v119, v193, v193
	v_mul_f32_e32 v120, v194, v194
	v_mul_f32_e32 v121, v195, v195
	v_mul_f32_e32 v122, v196, v196
	v_mul_f32_e32 v123, v197, v197
	v_fmac_f32_e32 v112, v203, v203
	v_fmac_f32_e32 v113, v204, v204
	v_fmac_f32_e32 v118, v205, v205
	v_fmac_f32_e32 v119, v206, v206
	v_fmac_f32_e32 v120, v207, v207
	v_fmac_f32_e32 v121, v208, v208
	v_fmac_f32_e32 v122, v209, v209
	v_fmac_f32_e32 v123, v210, v210
	v_add_f32_e32 v112, v112, v113
	v_add_f32_e32 v113, v118, v119
	v_add_f32_e32 v118, v120, v121
	v_add_f32_e32 v119, v122, v123
	v_cndmask_b32_e32 v189, v188, v189, vcc
	v_add_f32_e32 v112, v112, v113
	v_add_f32_e32 v113, v118, v119
	v_add_f32_e32 v113, v112, v113
	v_lshlrev_b32_e32 v112, 2, v189
	ds_bpermute_b32 v122, v112, v113
	v_lshl_add_u64 v[118:119], s[0:1], 0, v[200:201]
	v_cvt_pk_bf16_f32 v114, v203, v190
	v_lshl_add_u64 v[120:121], v[118:119], 0, v[198:199]
	v_cvt_pk_bf16_f32 v115, v204, v191
	v_cvt_pk_bf16_f32 v116, v205, v192
	v_cvt_pk_bf16_f32 v117, v206, v193
	global_store_dwordx4 v[120:121], v[114:117], off
	s_waitcnt lgkmcnt(0)
	s_nop 0
	v_add_f32_e32 v114, v113, v122
	v_xor_b32_e32 v113, 32, v188
	v_cmp_lt_i32_e32 vcc, v113, v202
	v_cvt_pk_bf16_f32 v116, v207, v194
	v_cvt_pk_bf16_f32 v117, v208, v195
	v_cvt_pk_bf16_f32 v118, v209, v196
	v_cvt_pk_bf16_f32 v119, v210, v197
	global_store_dwordx4 v[120:121], v[116:119], off offset:256
	s_nop 0
	v_cndmask_b32_e32 v113, v188, v113, vcc
	v_lshlrev_b32_e32 v113, 2, v113
	ds_bpermute_b32 v115, v113, v114
	s_and_saveexec_b64 s[20:21], s[4:5]
	s_cbranch_execz .LBB0_1909
	s_waitcnt lgkmcnt(0)
	v_add_f32_e32 v116, v114, v115
	s_lshl_b32 s22, s30, 2
	v_lshlrev_b64 v[114:115], 7, v[168:169]
	s_ashr_i32 s23, s22, 31
	v_lshl_add_u64 v[114:115], s[8:9], 0, v[114:115]
	v_lshl_add_u64 v[114:115], s[22:23], 2, v[114:115]
	s_lshl_b32 s2, s41, 2
	v_lshl_add_u64 v[114:115], v[114:115], 0, s[2:3]
	global_store_dword v[114:115], v116, off
